# half-tile steps folded into extra per-lane offset VGPRs: 7 fewer SALU per K-iteration in the load segments (on full_c)
# baseline (speedup 1.0000x reference)
; template <class Epi, bool ALIGN_EPI = true>
; __device__ __forceinline__ void gemm_phase(LAS unsigned char* lds, const Gemm g, const Sched& S, const Epi& E) {
;     ...
;     for (int i = 0; i < 2; ++i) { int R, C; stage_rc(tid * 16 + i * 8192, R, C); const int Rb = (R & ~31) + perm32(R & 31);
;         voffA[i] = (unsigned)(R * g.lda + C) * 2u; voffB[i] = (unsigned)(Rb * g.ldb + C) * 2u; }
;     const size_t kstep = (size_t)(BK * 2);
;     const size_t hstepA = (size_t)HALF * g.lda * 2, hstepB = (size_t)HALF * g.ldb * 2;
;     ...
;         const bool has_next = S.next(ui + 1, nxt);
;         const char* nA = has_next ? (const char*)g.A + nxt.aoff : cA; const char* nB = has_next ? (const char*)g.Bt + nxt.boff : cB;
.LBB0_498:
	s_add_u32 s48, s57, s70
	s_addc_u32 s49, s26, s71
	v_readlane_b32 s4, v242, 27
	s_add_u32 s40, s4, s90
	v_readlane_b32 s4, v242, 28
	s_addc_u32 s41, s4, s91
	s_andn2_b64 vcc, exec, s[60:61]
	s_cbranch_vccnz .LBB0_501
	s_and_b64 s[4:5], s[72:73], exec
	s_cselect_b32 s16, s49, s1
	s_cselect_b32 s17, s48, s0
	s_cselect_b32 s18, s41, s55
	s_cselect_b32 s19, s40, s54
	s_cmp_eq_u32 s96, 0
	s_cselect_b64 s[4:5], -1, 0
	v_cndmask_b32_e64 v2, 0, 1, s[4:5]
	s_add_u32 s4, s0, 0x80080
	s_addc_u32 s5, s1, 0
	s_add_u32 s20, s54, 0x100
	s_mov_b32 s6, 0
	s_addc_u32 s21, s55, 0
	v_add_u32_e32 v197, 0x80000, v150
	v_add_u32_e32 v210, 0x80000, v154
	v_add_u32_e32 v211, 0x80000, v152
	v_add_u32_e32 v240, 0x80000, v156

; #define PG8_STAGE(bufoff, gbase, voff) do { _Pragma("unroll") for (int _i = 0; _i < 2; ++_i) \
;         __builtin_amdgcn_global_load_lds((const unsigned*)((const char*)(gbase) + (voff)[_i]), (LAS unsigned*)(lds + (bufoff) + ldsw + _i * 8192), 16, 0, 0); } while (0)
; #define PG8_LDA(dst, b, h) do { _Pragma("unroll") for (int m = 0; m < 4; ++m) _Pragma("unroll") for (int k = 0; k < 2; ++k) dst[m][k] = *(const LAS bf16x8*)(lds + PG8_SA(b, h) + aoff + m * 2048 + k * 1024); } while (0)
; #define PG8_LDB(dst, b, h) do { _Pragma("unroll") for (int n = 0; n < 2; ++n) _Pragma("unroll") for (int k = 0; k < 2; ++k) dst[n][k] = *(const LAS bf16x8*)(lds + PG8_SB(b, h) + boff + n * 2048 + k * 1024); } while (0)
; #define PG8_MMA(ai, bj, At, Bt) do { __builtin_amdgcn_s_setprio(1); _Pragma("unroll") for (int m = 0; m < 4; ++m) _Pragma("unroll") for (int n = 0; n < 2; ++n) _Pragma("unroll") for (int k = 0; k < 2; ++k) \
;         acc[ai][bj][m][n] = __builtin_amdgcn_mfma_f32_16x16x32_bf16(Bt[n][k], At[m][k], acc[ai][bj][m][n], 0, 0, 0); __builtin_amdgcn_s_setprio(0); } while (0)
; #define PG8_WAIT_V(n) asm volatile("s_waitcnt vmcnt(" #n ")" ::: "memory")
; #define PG8_WAIT_L(n) asm volatile("s_waitcnt lgkmcnt(" #n ")" ::: "memory")
; #define PG8_BAR __builtin_amdgcn_s_barrier()
; #define PG8_WAIT_RELAX(flag, n) asm volatile("s_cmp_eq_u32 %0, 0\n\ts_cbranch_scc1 .Lrw%=\n\ts_waitcnt vmcnt(8)\n.Lrw%=:\n\ts_waitcnt vmcnt(%1)" :: "s"(flag), "n"(n) : "scc", "memory")
; #define PG8_SCHED __builtin_amdgcn_sched_barrier(0)
; template <class Epi, bool ALIGN_EPI = true>
; __device__ __forceinline__ void gemm_phase(LAS unsigned char* lds, const Gemm g, const Sched& S, const Epi& E) {
;     ...
;             PG8_LDB(B0, 0, 0); PG8_LDB(B1, 0, 1); PG8_SCHED; PG8_LDA(At, 0, 0); PG8_STAGE(PG8_SA(1, 1), a1 + hstepA, voffA);
;             if constexpr (Epi::NSTORES > 0) PG8_WAIT_RELAX(rflag, 8 + Epi::NSTORES); else PG8_WAIT_V(8);
;             PG8_WAIT_L(0); PG8_BAR; PG8_MMA(0, 0, At, B0); PG8_MMA(0, 1, At, B1); PG8_BAR; PG8_SCHED;
;             PG8_LDA(At, 0, 1); PG8_STAGE(PG8_SB(0, 0), b2, voffB); PG8_STAGE(PG8_SB(0, 1), b2 + hstepB, voffB); PG8_STAGE(PG8_SA(0, 0), a2, voffA);
.Lrw6:
	s_waitcnt vmcnt(24) lgkmcnt(0)
	s_barrier
	s_setprio 1
	v_mfma_f32_16x16x32_bf16 v[130:133], v[134:137], v[178:181], v[130:133]
	v_mfma_f32_16x16x32_bf16 v[126:129], v[142:145], v[178:181], v[126:129]
	v_mfma_f32_16x16x32_bf16 v[122:125], v[134:137], v[192:195], v[122:125]
	v_mfma_f32_16x16x32_bf16 v[118:121], v[142:145], v[192:195], v[118:121]
	v_mfma_f32_16x16x32_bf16 v[114:117], v[134:137], v[224:227], v[114:117]
	v_mfma_f32_16x16x32_bf16 v[110:113], v[142:145], v[224:227], v[110:113]
	v_mfma_f32_16x16x32_bf16 v[106:109], v[134:137], v[232:235], v[106:109]
	v_mfma_f32_16x16x32_bf16 v[102:105], v[142:145], v[232:235], v[102:105]
	v_mfma_f32_16x16x32_bf16 v[130:133], v[138:141], v[188:191], v[130:133]
	v_mfma_f32_16x16x32_bf16 v[126:129], v[146:149], v[188:191], v[126:129]
	v_mfma_f32_16x16x32_bf16 v[122:125], v[138:141], v[206:209], v[122:125]
	v_mfma_f32_16x16x32_bf16 v[118:121], v[146:149], v[206:209], v[118:121]
	v_mfma_f32_16x16x32_bf16 v[114:117], v[138:141], v[228:231], v[114:117]
	v_mfma_f32_16x16x32_bf16 v[110:113], v[146:149], v[228:231], v[110:113]
	v_mfma_f32_16x16x32_bf16 v[106:109], v[138:141], v[236:239], v[106:109]
	v_mfma_f32_16x16x32_bf16 v[102:105], v[146:149], v[236:239], v[102:105]
	s_setprio 0
	s_setprio 1
	v_mfma_f32_16x16x32_bf16 v[98:101], v[162:165], v[178:181], v[98:101]
	v_mfma_f32_16x16x32_bf16 v[94:97], v[170:173], v[178:181], v[94:97]
	v_mfma_f32_16x16x32_bf16 v[90:93], v[162:165], v[192:195], v[90:93]
	v_mfma_f32_16x16x32_bf16 v[86:89], v[170:173], v[192:195], v[86:89]
	v_mfma_f32_16x16x32_bf16 v[82:85], v[162:165], v[224:227], v[82:85]
	v_mfma_f32_16x16x32_bf16 v[78:81], v[170:173], v[224:227], v[78:81]
	v_mfma_f32_16x16x32_bf16 v[74:77], v[162:165], v[232:235], v[74:77]
	v_mfma_f32_16x16x32_bf16 v[70:73], v[170:173], v[232:235], v[70:73]
	v_mfma_f32_16x16x32_bf16 v[98:101], v[166:169], v[188:191], v[98:101]
	v_mfma_f32_16x16x32_bf16 v[94:97], v[174:177], v[188:191], v[94:97]
	v_mfma_f32_16x16x32_bf16 v[90:93], v[166:169], v[206:209], v[90:93]
	v_mfma_f32_16x16x32_bf16 v[86:89], v[174:177], v[206:209], v[86:89]
	v_mfma_f32_16x16x32_bf16 v[82:85], v[166:169], v[228:231], v[82:85]
	v_mfma_f32_16x16x32_bf16 v[78:81], v[174:177], v[228:231], v[78:81]
	v_mfma_f32_16x16x32_bf16 v[74:77], v[166:169], v[236:239], v[74:77]
	v_mfma_f32_16x16x32_bf16 v[70:73], v[174:177], v[236:239], v[70:73]
	s_setprio 0
	s_barrier
	ds_read_b128 v[178:181], v186 offset:16384
	ds_read_b128 v[188:191], v186 offset:17408
	ds_read_b128 v[192:195], v186 offset:18432
	ds_read_b128 v[206:209], v186 offset:19456
	s_add_i32 m0, s27, 0x10000
	ds_read_b128 v[224:227], v186 offset:20480
	global_load_lds_dwordx4 v152, s[6:7]
	s_add_i32 m0, s27, 0x12000
	ds_read_b128 v[228:231], v186 offset:21504
	global_load_lds_dwordx4 v156, s[6:7]
	s_add_i32 m0, s27, 0x14000
	ds_read_b128 v[232:235], v186 offset:22528
	global_load_lds_dwordx4 v211, s[6:7]
	s_add_i32 m0, s27, 0x16000
	ds_read_b128 v[236:239], v186 offset:23552
	global_load_lds_dwordx4 v240, s[6:7]
	s_cmp_eq_u32 s53, 0
	s_cbranch_scc1 .Lrw7
	s_waitcnt vmcnt(6)
; #define PG8_STAGE(bufoff, gbase, voff) do { _Pragma("unroll") for (int _i = 0; _i < 2; ++_i) \
;         __builtin_amdgcn_global_load_lds((const unsigned*)((const char*)(gbase) + (voff)[_i]), (LAS unsigned*)(lds + (bufoff) + ldsw + _i * 8192), 16, 0, 0); } while (0)
; #define PG8_LDA(dst, b, h) do { _Pragma("unroll") for (int m = 0; m < 4; ++m) _Pragma("unroll") for (int k = 0; k < 2; ++k) dst[m][k] = *(const LAS bf16x8*)(lds + PG8_SA(b, h) + aoff + m * 2048 + k * 1024); } while (0)
; #define PG8_LDB(dst, b, h) do { _Pragma("unroll") for (int n = 0; n < 2; ++n) _Pragma("unroll") for (int k = 0; k < 2; ++k) dst[n][k] = *(const LAS bf16x8*)(lds + PG8_SB(b, h) + boff + n * 2048 + k * 1024); } while (0)
; #define PG8_MMA(ai, bj, At, Bt) do { __builtin_amdgcn_s_setprio(1); _Pragma("unroll") for (int m = 0; m < 4; ++m) _Pragma("unroll") for (int n = 0; n < 2; ++n) _Pragma("unroll") for (int k = 0; k < 2; ++k) \
;         acc[ai][bj][m][n] = __builtin_amdgcn_mfma_f32_16x16x32_bf16(Bt[n][k], At[m][k], acc[ai][bj][m][n], 0, 0, 0); __builtin_amdgcn_s_setprio(0); } while (0)
; #define PG8_WAIT_V(n) asm volatile("s_waitcnt vmcnt(" #n ")" ::: "memory")
; #define PG8_WAIT_L(n) asm volatile("s_waitcnt lgkmcnt(" #n ")" ::: "memory")
; #define PG8_BAR __builtin_amdgcn_s_barrier()
; #define PG8_WAIT_RELAX(flag, n) asm volatile("s_cmp_eq_u32 %0, 0\n\ts_cbranch_scc1 .Lrw%=\n\ts_waitcnt vmcnt(8)\n.Lrw%=:\n\ts_waitcnt vmcnt(%1)" :: "s"(flag), "n"(n) : "scc", "memory")
; template <class Epi, bool ALIGN_EPI = true>
; __device__ __forceinline__ void gemm_phase(LAS unsigned char* lds, const Gemm g, const Sched& S, const Epi& E) {
;     ...
;             if constexpr (Epi::NSTORES > 0) PG8_WAIT_RELAX(rflag, 8 + Epi::NSTORES); else PG8_WAIT_V(8);
;             PG8_WAIT_L(0); PG8_BAR; PG8_MMA(1, 0, At, B0); PG8_MMA(1, 1, At, B1); PG8_BAR; PG8_SCHED;
;             PG8_LDB(B0, 1, 0); PG8_LDB(B1, 1, 1); PG8_SCHED; PG8_LDA(At, 1, 0); PG8_STAGE(PG8_SA(0, 1), a2 + hstepA, voffA);
;             PG8_WAIT_V(8); PG8_WAIT_L(0); PG8_BAR; PG8_MMA(0, 0, At, B0); PG8_MMA(0, 1, At, B1); PG8_BAR; PG8_SCHED;
;             PG8_LDA(At, 1, 1); PG8_STAGE(PG8_SB(1, 0), b3, voffB); PG8_STAGE(PG8_SB(1, 1), b3 + hstepB, voffB); PG8_STAGE(PG8_SA(1, 0), a3, voffA);
;             PG8_WAIT_V(8); PG8_WAIT_L(0); PG8_BAR; PG8_MMA(1, 0, At, B0); PG8_MMA(1, 1, At, B1); PG8_BAR; PG8_SCHED;
;         }
.Lrw7:
	s_waitcnt vmcnt(24) lgkmcnt(0)
	s_barrier
	s_setprio 1
	v_mfma_f32_16x16x32_bf16 v[66:69], v[134:137], v[178:181], v[66:69]
	v_mfma_f32_16x16x32_bf16 v[62:65], v[142:145], v[178:181], v[62:65]
	v_mfma_f32_16x16x32_bf16 v[58:61], v[134:137], v[192:195], v[58:61]
	v_mfma_f32_16x16x32_bf16 v[54:57], v[142:145], v[192:195], v[54:57]
	v_mfma_f32_16x16x32_bf16 v[50:53], v[134:137], v[224:227], v[50:53]
	v_mfma_f32_16x16x32_bf16 v[46:49], v[142:145], v[224:227], v[46:49]
	v_mfma_f32_16x16x32_bf16 v[42:45], v[134:137], v[232:235], v[42:45]
	v_mfma_f32_16x16x32_bf16 v[38:41], v[142:145], v[232:235], v[38:41]
	v_mfma_f32_16x16x32_bf16 v[66:69], v[138:141], v[188:191], v[66:69]
	v_mfma_f32_16x16x32_bf16 v[62:65], v[146:149], v[188:191], v[62:65]
	v_mfma_f32_16x16x32_bf16 v[58:61], v[138:141], v[206:209], v[58:61]
	v_mfma_f32_16x16x32_bf16 v[54:57], v[146:149], v[206:209], v[54:57]
	v_mfma_f32_16x16x32_bf16 v[50:53], v[138:141], v[228:231], v[50:53]
	v_mfma_f32_16x16x32_bf16 v[46:49], v[146:149], v[228:231], v[46:49]
	v_mfma_f32_16x16x32_bf16 v[42:45], v[138:141], v[236:239], v[42:45]
	v_mfma_f32_16x16x32_bf16 v[38:41], v[146:149], v[236:239], v[38:41]
	s_setprio 0
	s_setprio 1
	v_mfma_f32_16x16x32_bf16 v[34:37], v[162:165], v[178:181], v[34:37]
	v_mfma_f32_16x16x32_bf16 v[30:33], v[170:173], v[178:181], v[30:33]
	v_mfma_f32_16x16x32_bf16 v[26:29], v[162:165], v[192:195], v[26:29]
	v_mfma_f32_16x16x32_bf16 v[22:25], v[170:173], v[192:195], v[22:25]
	v_mfma_f32_16x16x32_bf16 v[18:21], v[162:165], v[224:227], v[18:21]
	v_mfma_f32_16x16x32_bf16 v[14:17], v[170:173], v[224:227], v[14:17]
	v_mfma_f32_16x16x32_bf16 v[10:13], v[162:165], v[232:235], v[10:13]
	v_mfma_f32_16x16x32_bf16 v[4:7], v[170:173], v[232:235], v[6:9]
	v_mfma_f32_16x16x32_bf16 v[34:37], v[166:169], v[188:191], v[34:37]
	v_mfma_f32_16x16x32_bf16 v[30:33], v[174:177], v[188:191], v[30:33]
	v_mfma_f32_16x16x32_bf16 v[26:29], v[166:169], v[206:209], v[26:29]
	v_mfma_f32_16x16x32_bf16 v[22:25], v[174:177], v[206:209], v[22:25]
	v_mfma_f32_16x16x32_bf16 v[18:21], v[166:169], v[228:231], v[18:21]
	v_mfma_f32_16x16x32_bf16 v[14:17], v[174:177], v[228:231], v[14:17]
	v_mfma_f32_16x16x32_bf16 v[10:13], v[166:169], v[236:239], v[10:13]
	v_mfma_f32_16x16x32_bf16 v[4:7], v[174:177], v[236:239], v[4:7]
	s_setprio 0
	s_barrier
	ds_read_b128 v[134:137], v185 offset:32768
	ds_read_b128 v[138:141], v185 offset:33792
	ds_read_b128 v[142:145], v185 offset:34816
	ds_read_b128 v[146:149], v185 offset:35840
	ds_read_b128 v[162:165], v185 offset:49152
	ds_read_b128 v[166:169], v185 offset:50176
	ds_read_b128 v[170:173], v185 offset:51200
	ds_read_b128 v[174:177], v185 offset:52224
	ds_read_b128 v[178:181], v186 offset:32768
	ds_read_b128 v[188:191], v186 offset:33792
	ds_read_b128 v[192:195], v186 offset:34816
	ds_read_b128 v[206:209], v186 offset:35840
	s_mov_b32 m0, s50
	ds_read_b128 v[224:227], v186 offset:36864
	global_load_lds_dwordx4 v150, s[14:15]
	s_mov_b32 m0, s51
	ds_read_b128 v[228:231], v186 offset:37888
	global_load_lds_dwordx4 v154, s[14:15]
	s_mov_b32 m0, s36
	ds_read_b128 v[232:235], v186 offset:38912
	global_load_lds_dwordx4 v197, s[14:15]
	s_mov_b32 m0, s37
	ds_read_b128 v[236:239], v186 offset:39936
	global_load_lds_dwordx4 v210, s[14:15]
	s_waitcnt vmcnt(8) lgkmcnt(0)
	s_barrier
	s_setprio 1
	v_mfma_f32_16x16x32_bf16 v[130:133], v[134:137], v[178:181], v[130:133]
	v_mfma_f32_16x16x32_bf16 v[126:129], v[142:145], v[178:181], v[126:129]
	v_mfma_f32_16x16x32_bf16 v[122:125], v[134:137], v[192:195], v[122:125]
	v_mfma_f32_16x16x32_bf16 v[118:121], v[142:145], v[192:195], v[118:121]
	v_mfma_f32_16x16x32_bf16 v[114:117], v[134:137], v[224:227], v[114:117]
	v_mfma_f32_16x16x32_bf16 v[110:113], v[142:145], v[224:227], v[110:113]
	v_mfma_f32_16x16x32_bf16 v[106:109], v[134:137], v[232:235], v[106:109]
	v_mfma_f32_16x16x32_bf16 v[102:105], v[142:145], v[232:235], v[102:105]
	v_mfma_f32_16x16x32_bf16 v[130:133], v[138:141], v[188:191], v[130:133]
	v_mfma_f32_16x16x32_bf16 v[126:129], v[146:149], v[188:191], v[126:129]
	v_mfma_f32_16x16x32_bf16 v[122:125], v[138:141], v[206:209], v[122:125]
	v_mfma_f32_16x16x32_bf16 v[118:121], v[146:149], v[206:209], v[118:121]
	v_mfma_f32_16x16x32_bf16 v[114:117], v[138:141], v[228:231], v[114:117]
	v_mfma_f32_16x16x32_bf16 v[110:113], v[146:149], v[228:231], v[110:113]
	v_mfma_f32_16x16x32_bf16 v[106:109], v[138:141], v[236:239], v[106:109]
	v_mfma_f32_16x16x32_bf16 v[102:105], v[146:149], v[236:239], v[102:105]
	s_setprio 0
	s_setprio 1
	v_mfma_f32_16x16x32_bf16 v[98:101], v[162:165], v[178:181], v[98:101]
	v_mfma_f32_16x16x32_bf16 v[94:97], v[170:173], v[178:181], v[94:97]
	v_mfma_f32_16x16x32_bf16 v[90:93], v[162:165], v[192:195], v[90:93]
	v_mfma_f32_16x16x32_bf16 v[86:89], v[170:173], v[192:195], v[86:89]
	v_mfma_f32_16x16x32_bf16 v[82:85], v[162:165], v[224:227], v[82:85]
	v_mfma_f32_16x16x32_bf16 v[78:81], v[170:173], v[224:227], v[78:81]
	v_mfma_f32_16x16x32_bf16 v[74:77], v[162:165], v[232:235], v[74:77]
	v_mfma_f32_16x16x32_bf16 v[70:73], v[170:173], v[232:235], v[70:73]
	v_mfma_f32_16x16x32_bf16 v[98:101], v[166:169], v[188:191], v[98:101]
	v_mfma_f32_16x16x32_bf16 v[94:97], v[174:177], v[188:191], v[94:97]
	v_mfma_f32_16x16x32_bf16 v[90:93], v[166:169], v[206:209], v[90:93]
	v_mfma_f32_16x16x32_bf16 v[86:89], v[174:177], v[206:209], v[86:89]
	v_mfma_f32_16x16x32_bf16 v[82:85], v[166:169], v[228:231], v[82:85]
	v_mfma_f32_16x16x32_bf16 v[78:81], v[174:177], v[228:231], v[78:81]
	v_mfma_f32_16x16x32_bf16 v[74:77], v[166:169], v[236:239], v[74:77]
	v_mfma_f32_16x16x32_bf16 v[70:73], v[174:177], v[236:239], v[70:73]
	s_setprio 0
	s_barrier
	ds_read_b128 v[178:181], v186 offset:49152
	ds_read_b128 v[188:191], v186 offset:50176
	ds_read_b128 v[192:195], v186 offset:51200
	ds_read_b128 v[206:209], v186 offset:52224
	s_add_i32 m0, s27, 0x17f80
	ds_read_b128 v[224:227], v186 offset:53248
	global_load_lds_dwordx4 v152, s[6:7] offset:128
	s_add_i32 m0, s27, 0x19f80
	ds_read_b128 v[228:231], v186 offset:54272
	global_load_lds_dwordx4 v156, s[6:7] offset:128
	s_add_i32 m0, s27, 0x1bf80
	ds_read_b128 v[232:235], v186 offset:55296
	global_load_lds_dwordx4 v211, s[6:7] offset:128
	s_add_i32 m0, s27, 0x1df80
	ds_read_b128 v[236:239], v186 offset:56320
	global_load_lds_dwordx4 v240, s[6:7] offset:128
	s_cmp_ge_i32 s22, s46
	s_cbranch_scc0 .Lx4last_3
	s_add_i32 m0, s92, 0xffffff80
	s_nop 0
	global_load_lds_dwordx4 v150, s[14:15] offset:128
	s_add_i32 m0, s93, 0xffffff80
	s_nop 0
	global_load_lds_dwordx4 v154, s[14:15] offset:128

; template <class Epi, bool ALIGN_EPI = true>
; __device__ __forceinline__ void gemm_phase(LAS unsigned char* lds, const Gemm g, const Sched& S, const Epi& E) {
;     ...
;     for (int i = 0; i < 2; ++i) { int R, C; stage_rc(tid * 16 + i * 8192, R, C); const int Rb = (R & ~31) + perm32(R & 31);
;         voffA[i] = (unsigned)(R * g.lda + C) * 2u; voffB[i] = (unsigned)(Rb * g.ldb + C) * 2u; }
;     const size_t kstep = (size_t)(BK * 2);
;     const size_t hstepA = (size_t)HALF * g.lda * 2, hstepB = (size_t)HALF * g.ldb * 2;
;     ...
;         const bool has_next = S.next(ui + 1, nxt);
;         const char* nA = has_next ? (const char*)g.A + nxt.aoff : cA; const char* nB = has_next ? (const char*)g.Bt + nxt.boff : cB;
.LBB0_952:
	s_add_u32 s0, s26, s64
	s_addc_u32 s1, s27, s65
	v_readlane_b32 s4, v242, 27
	s_add_u32 s70, s4, s68
	v_readlane_b32 s4, v242, 28
	s_addc_u32 s71, s4, s69
	s_andn2_b64 vcc, exec, s[84:85]
	s_cbranch_vccnz .LBB0_955
	s_and_b64 s[4:5], s[90:91], exec
	s_cselect_b32 s16, s1, s51
	s_cselect_b32 s17, s0, s50
	s_cselect_b32 s18, s71, s41
	s_cselect_b32 s19, s70, s40
	s_cmp_eq_u32 s92, 0
	s_cselect_b64 s[4:5], -1, 0
	v_cndmask_b32_e64 v2, 0, 1, s[4:5]
	s_add_u32 s4, s50, 0x80080
	s_addc_u32 s5, s51, 0
	s_add_u32 s20, s40, 0x100
	s_mov_b32 s6, 0
	s_addc_u32 s21, s41, 0
	v_add_u32_e32 v197, 0x80000, v150
	v_add_u32_e32 v210, 0x80000, v154
	v_add_u32_e32 v211, 0x80000, v152
	v_add_u32_e32 v240, 0x80000, v156

; #define PG8_STAGE(bufoff, gbase, voff) do { _Pragma("unroll") for (int _i = 0; _i < 2; ++_i) \
;         __builtin_amdgcn_global_load_lds((const unsigned*)((const char*)(gbase) + (voff)[_i]), (LAS unsigned*)(lds + (bufoff) + ldsw + _i * 8192), 16, 0, 0); } while (0)
; #define PG8_LDA(dst, b, h) do { _Pragma("unroll") for (int m = 0; m < 4; ++m) _Pragma("unroll") for (int k = 0; k < 2; ++k) dst[m][k] = *(const LAS bf16x8*)(lds + PG8_SA(b, h) + aoff + m * 2048 + k * 1024); } while (0)
; #define PG8_LDB(dst, b, h) do { _Pragma("unroll") for (int n = 0; n < 2; ++n) _Pragma("unroll") for (int k = 0; k < 2; ++k) dst[n][k] = *(const LAS bf16x8*)(lds + PG8_SB(b, h) + boff + n * 2048 + k * 1024); } while (0)
; #define PG8_MMA(ai, bj, At, Bt) do { __builtin_amdgcn_s_setprio(1); _Pragma("unroll") for (int m = 0; m < 4; ++m) _Pragma("unroll") for (int n = 0; n < 2; ++n) _Pragma("unroll") for (int k = 0; k < 2; ++k) \
;         acc[ai][bj][m][n] = __builtin_amdgcn_mfma_f32_16x16x32_bf16(Bt[n][k], At[m][k], acc[ai][bj][m][n], 0, 0, 0); __builtin_amdgcn_s_setprio(0); } while (0)
; #define PG8_WAIT_V(n) asm volatile("s_waitcnt vmcnt(" #n ")" ::: "memory")
; #define PG8_WAIT_L(n) asm volatile("s_waitcnt lgkmcnt(" #n ")" ::: "memory")
; #define PG8_BAR __builtin_amdgcn_s_barrier()
; #define PG8_WAIT_RELAX(flag, n) asm volatile("s_cmp_eq_u32 %0, 0\n\ts_cbranch_scc1 .Lrw%=\n\ts_waitcnt vmcnt(8)\n.Lrw%=:\n\ts_waitcnt vmcnt(%1)" :: "s"(flag), "n"(n) : "scc", "memory")
; #define PG8_SCHED __builtin_amdgcn_sched_barrier(0)
; template <class Epi, bool ALIGN_EPI = true>
; __device__ __forceinline__ void gemm_phase(LAS unsigned char* lds, const Gemm g, const Sched& S, const Epi& E) {
;     ...
;             PG8_LDB(B0, 0, 0); PG8_LDB(B1, 0, 1); PG8_SCHED; PG8_LDA(At, 0, 0); PG8_STAGE(PG8_SA(1, 1), a1 + hstepA, voffA);
;             if constexpr (Epi::NSTORES > 0) PG8_WAIT_RELAX(rflag, 8 + Epi::NSTORES); else PG8_WAIT_V(8);
;             PG8_WAIT_L(0); PG8_BAR; PG8_MMA(0, 0, At, B0); PG8_MMA(0, 1, At, B1); PG8_BAR; PG8_SCHED;
;             PG8_LDA(At, 0, 1); PG8_STAGE(PG8_SB(0, 0), b2, voffB); PG8_STAGE(PG8_SB(0, 1), b2 + hstepB, voffB); PG8_STAGE(PG8_SA(0, 0), a2, voffA);
.Lrw12:
	s_waitcnt vmcnt(24) lgkmcnt(0)
	s_barrier
	s_setprio 1
	v_mfma_f32_16x16x32_bf16 v[130:133], v[134:137], v[178:181], v[130:133]
	v_mfma_f32_16x16x32_bf16 v[126:129], v[142:145], v[178:181], v[126:129]
	v_mfma_f32_16x16x32_bf16 v[122:125], v[134:137], v[192:195], v[122:125]
	v_mfma_f32_16x16x32_bf16 v[118:121], v[142:145], v[192:195], v[118:121]
	v_mfma_f32_16x16x32_bf16 v[114:117], v[134:137], v[224:227], v[114:117]
	v_mfma_f32_16x16x32_bf16 v[110:113], v[142:145], v[224:227], v[110:113]
	v_mfma_f32_16x16x32_bf16 v[106:109], v[134:137], v[232:235], v[106:109]
	v_mfma_f32_16x16x32_bf16 v[102:105], v[142:145], v[232:235], v[102:105]
	v_mfma_f32_16x16x32_bf16 v[130:133], v[138:141], v[188:191], v[130:133]
	v_mfma_f32_16x16x32_bf16 v[126:129], v[146:149], v[188:191], v[126:129]
	v_mfma_f32_16x16x32_bf16 v[122:125], v[138:141], v[206:209], v[122:125]
	v_mfma_f32_16x16x32_bf16 v[118:121], v[146:149], v[206:209], v[118:121]
	v_mfma_f32_16x16x32_bf16 v[114:117], v[138:141], v[228:231], v[114:117]
	v_mfma_f32_16x16x32_bf16 v[110:113], v[146:149], v[228:231], v[110:113]
	v_mfma_f32_16x16x32_bf16 v[106:109], v[138:141], v[236:239], v[106:109]
	v_mfma_f32_16x16x32_bf16 v[102:105], v[146:149], v[236:239], v[102:105]
	s_setprio 0
	s_setprio 1
	v_mfma_f32_16x16x32_bf16 v[98:101], v[162:165], v[178:181], v[98:101]
	v_mfma_f32_16x16x32_bf16 v[94:97], v[170:173], v[178:181], v[94:97]
	v_mfma_f32_16x16x32_bf16 v[90:93], v[162:165], v[192:195], v[90:93]
	v_mfma_f32_16x16x32_bf16 v[86:89], v[170:173], v[192:195], v[86:89]
	v_mfma_f32_16x16x32_bf16 v[82:85], v[162:165], v[224:227], v[82:85]
	v_mfma_f32_16x16x32_bf16 v[78:81], v[170:173], v[224:227], v[78:81]
	v_mfma_f32_16x16x32_bf16 v[74:77], v[162:165], v[232:235], v[74:77]
	v_mfma_f32_16x16x32_bf16 v[70:73], v[170:173], v[232:235], v[70:73]
	v_mfma_f32_16x16x32_bf16 v[98:101], v[166:169], v[188:191], v[98:101]
	v_mfma_f32_16x16x32_bf16 v[94:97], v[174:177], v[188:191], v[94:97]
	v_mfma_f32_16x16x32_bf16 v[90:93], v[166:169], v[206:209], v[90:93]
	v_mfma_f32_16x16x32_bf16 v[86:89], v[174:177], v[206:209], v[86:89]
	v_mfma_f32_16x16x32_bf16 v[82:85], v[166:169], v[228:231], v[82:85]
	v_mfma_f32_16x16x32_bf16 v[78:81], v[174:177], v[228:231], v[78:81]
	v_mfma_f32_16x16x32_bf16 v[74:77], v[166:169], v[236:239], v[74:77]
	v_mfma_f32_16x16x32_bf16 v[70:73], v[174:177], v[236:239], v[70:73]
	s_setprio 0
	s_barrier
	ds_read_b128 v[178:181], v186 offset:16384
	ds_read_b128 v[188:191], v186 offset:17408
	ds_read_b128 v[192:195], v186 offset:18432
	ds_read_b128 v[206:209], v186 offset:19456
	s_add_i32 m0, s94, 0x10000
	ds_read_b128 v[224:227], v186 offset:20480
	global_load_lds_dwordx4 v152, s[6:7]
	s_add_i32 m0, s94, 0x12000
	ds_read_b128 v[228:231], v186 offset:21504
	global_load_lds_dwordx4 v156, s[6:7]
	s_add_i32 m0, s94, 0x14000
	ds_read_b128 v[232:235], v186 offset:22528
	global_load_lds_dwordx4 v211, s[6:7]
	s_add_i32 m0, s94, 0x16000
	ds_read_b128 v[236:239], v186 offset:23552
	global_load_lds_dwordx4 v240, s[6:7]
	s_cmp_eq_u32 s59, 0
	s_cbranch_scc1 .Lrw13
	s_waitcnt vmcnt(6)
; #define PG8_STAGE(bufoff, gbase, voff) do { _Pragma("unroll") for (int _i = 0; _i < 2; ++_i) \
;         __builtin_amdgcn_global_load_lds((const unsigned*)((const char*)(gbase) + (voff)[_i]), (LAS unsigned*)(lds + (bufoff) + ldsw + _i * 8192), 16, 0, 0); } while (0)
; #define PG8_LDA(dst, b, h) do { _Pragma("unroll") for (int m = 0; m < 4; ++m) _Pragma("unroll") for (int k = 0; k < 2; ++k) dst[m][k] = *(const LAS bf16x8*)(lds + PG8_SA(b, h) + aoff + m * 2048 + k * 1024); } while (0)
; #define PG8_LDB(dst, b, h) do { _Pragma("unroll") for (int n = 0; n < 2; ++n) _Pragma("unroll") for (int k = 0; k < 2; ++k) dst[n][k] = *(const LAS bf16x8*)(lds + PG8_SB(b, h) + boff + n * 2048 + k * 1024); } while (0)
; #define PG8_MMA(ai, bj, At, Bt) do { __builtin_amdgcn_s_setprio(1); _Pragma("unroll") for (int m = 0; m < 4; ++m) _Pragma("unroll") for (int n = 0; n < 2; ++n) _Pragma("unroll") for (int k = 0; k < 2; ++k) \
;         acc[ai][bj][m][n] = __builtin_amdgcn_mfma_f32_16x16x32_bf16(Bt[n][k], At[m][k], acc[ai][bj][m][n], 0, 0, 0); __builtin_amdgcn_s_setprio(0); } while (0)
; #define PG8_WAIT_V(n) asm volatile("s_waitcnt vmcnt(" #n ")" ::: "memory")
; #define PG8_WAIT_L(n) asm volatile("s_waitcnt lgkmcnt(" #n ")" ::: "memory")
; #define PG8_BAR __builtin_amdgcn_s_barrier()
; #define PG8_WAIT_RELAX(flag, n) asm volatile("s_cmp_eq_u32 %0, 0\n\ts_cbranch_scc1 .Lrw%=\n\ts_waitcnt vmcnt(8)\n.Lrw%=:\n\ts_waitcnt vmcnt(%1)" :: "s"(flag), "n"(n) : "scc", "memory")
; template <class Epi, bool ALIGN_EPI = true>
; __device__ __forceinline__ void gemm_phase(LAS unsigned char* lds, const Gemm g, const Sched& S, const Epi& E) {
;     ...
;             if constexpr (Epi::NSTORES > 0) PG8_WAIT_RELAX(rflag, 8 + Epi::NSTORES); else PG8_WAIT_V(8);
;             PG8_WAIT_L(0); PG8_BAR; PG8_MMA(1, 0, At, B0); PG8_MMA(1, 1, At, B1); PG8_BAR; PG8_SCHED;
;             PG8_LDB(B0, 1, 0); PG8_LDB(B1, 1, 1); PG8_SCHED; PG8_LDA(At, 1, 0); PG8_STAGE(PG8_SA(0, 1), a2 + hstepA, voffA);
;             PG8_WAIT_V(8); PG8_WAIT_L(0); PG8_BAR; PG8_MMA(0, 0, At, B0); PG8_MMA(0, 1, At, B1); PG8_BAR; PG8_SCHED;
;             PG8_LDA(At, 1, 1); PG8_STAGE(PG8_SB(1, 0), b3, voffB); PG8_STAGE(PG8_SB(1, 1), b3 + hstepB, voffB); PG8_STAGE(PG8_SA(1, 0), a3, voffA);
;             PG8_WAIT_V(8); PG8_WAIT_L(0); PG8_BAR; PG8_MMA(1, 0, At, B0); PG8_MMA(1, 1, At, B1); PG8_BAR; PG8_SCHED;
;         }
.Lrw13:
	s_waitcnt vmcnt(24) lgkmcnt(0)
	s_barrier
	s_setprio 1
	v_mfma_f32_16x16x32_bf16 v[66:69], v[134:137], v[178:181], v[66:69]
	v_mfma_f32_16x16x32_bf16 v[62:65], v[142:145], v[178:181], v[62:65]
	v_mfma_f32_16x16x32_bf16 v[58:61], v[134:137], v[192:195], v[58:61]
	v_mfma_f32_16x16x32_bf16 v[54:57], v[142:145], v[192:195], v[54:57]
	v_mfma_f32_16x16x32_bf16 v[50:53], v[134:137], v[224:227], v[50:53]
	v_mfma_f32_16x16x32_bf16 v[46:49], v[142:145], v[224:227], v[46:49]
	v_mfma_f32_16x16x32_bf16 v[42:45], v[134:137], v[232:235], v[42:45]
	v_mfma_f32_16x16x32_bf16 v[38:41], v[142:145], v[232:235], v[38:41]
	v_mfma_f32_16x16x32_bf16 v[66:69], v[138:141], v[188:191], v[66:69]
	v_mfma_f32_16x16x32_bf16 v[62:65], v[146:149], v[188:191], v[62:65]
	v_mfma_f32_16x16x32_bf16 v[58:61], v[138:141], v[206:209], v[58:61]
	v_mfma_f32_16x16x32_bf16 v[54:57], v[146:149], v[206:209], v[54:57]
	v_mfma_f32_16x16x32_bf16 v[50:53], v[138:141], v[228:231], v[50:53]
	v_mfma_f32_16x16x32_bf16 v[46:49], v[146:149], v[228:231], v[46:49]
	v_mfma_f32_16x16x32_bf16 v[42:45], v[138:141], v[236:239], v[42:45]
	v_mfma_f32_16x16x32_bf16 v[38:41], v[146:149], v[236:239], v[38:41]
	s_setprio 0
	s_setprio 1
	v_mfma_f32_16x16x32_bf16 v[34:37], v[162:165], v[178:181], v[34:37]
	v_mfma_f32_16x16x32_bf16 v[30:33], v[170:173], v[178:181], v[30:33]
	v_mfma_f32_16x16x32_bf16 v[26:29], v[162:165], v[192:195], v[26:29]
	v_mfma_f32_16x16x32_bf16 v[22:25], v[170:173], v[192:195], v[22:25]
	v_mfma_f32_16x16x32_bf16 v[18:21], v[162:165], v[224:227], v[18:21]
	v_mfma_f32_16x16x32_bf16 v[14:17], v[170:173], v[224:227], v[14:17]
	v_mfma_f32_16x16x32_bf16 v[10:13], v[162:165], v[232:235], v[10:13]
	v_mfma_f32_16x16x32_bf16 v[4:7], v[170:173], v[232:235], v[6:9]
	v_mfma_f32_16x16x32_bf16 v[34:37], v[166:169], v[188:191], v[34:37]
	v_mfma_f32_16x16x32_bf16 v[30:33], v[174:177], v[188:191], v[30:33]
	v_mfma_f32_16x16x32_bf16 v[26:29], v[166:169], v[206:209], v[26:29]
	v_mfma_f32_16x16x32_bf16 v[22:25], v[174:177], v[206:209], v[22:25]
	v_mfma_f32_16x16x32_bf16 v[18:21], v[166:169], v[228:231], v[18:21]
	v_mfma_f32_16x16x32_bf16 v[14:17], v[174:177], v[228:231], v[14:17]
	v_mfma_f32_16x16x32_bf16 v[10:13], v[166:169], v[236:239], v[10:13]
	v_mfma_f32_16x16x32_bf16 v[4:7], v[174:177], v[236:239], v[4:7]
	s_setprio 0
	s_barrier
	ds_read_b128 v[134:137], v185 offset:32768
	ds_read_b128 v[138:141], v185 offset:33792
	ds_read_b128 v[142:145], v185 offset:34816
	ds_read_b128 v[146:149], v185 offset:35840
	ds_read_b128 v[162:165], v185 offset:49152
	ds_read_b128 v[166:169], v185 offset:50176
	ds_read_b128 v[170:173], v185 offset:51200
	ds_read_b128 v[174:177], v185 offset:52224
	ds_read_b128 v[178:181], v186 offset:32768
	ds_read_b128 v[188:191], v186 offset:33792
	ds_read_b128 v[192:195], v186 offset:34816
	ds_read_b128 v[206:209], v186 offset:35840
	s_mov_b32 m0, s48
	ds_read_b128 v[224:227], v186 offset:36864
	global_load_lds_dwordx4 v150, s[14:15]
	s_mov_b32 m0, s49
	ds_read_b128 v[228:231], v186 offset:37888
	global_load_lds_dwordx4 v154, s[14:15]
	s_mov_b32 m0, s46
	ds_read_b128 v[232:235], v186 offset:38912
	global_load_lds_dwordx4 v197, s[14:15]
	s_mov_b32 m0, s47
	ds_read_b128 v[236:239], v186 offset:39936
	global_load_lds_dwordx4 v210, s[14:15]
	s_waitcnt vmcnt(8) lgkmcnt(0)
	s_barrier
	s_setprio 1
	v_mfma_f32_16x16x32_bf16 v[130:133], v[134:137], v[178:181], v[130:133]
	v_mfma_f32_16x16x32_bf16 v[126:129], v[142:145], v[178:181], v[126:129]
	v_mfma_f32_16x16x32_bf16 v[122:125], v[134:137], v[192:195], v[122:125]
	v_mfma_f32_16x16x32_bf16 v[118:121], v[142:145], v[192:195], v[118:121]
	v_mfma_f32_16x16x32_bf16 v[114:117], v[134:137], v[224:227], v[114:117]
	v_mfma_f32_16x16x32_bf16 v[110:113], v[142:145], v[224:227], v[110:113]
	v_mfma_f32_16x16x32_bf16 v[106:109], v[134:137], v[232:235], v[106:109]
	v_mfma_f32_16x16x32_bf16 v[102:105], v[142:145], v[232:235], v[102:105]
	v_mfma_f32_16x16x32_bf16 v[130:133], v[138:141], v[188:191], v[130:133]
	v_mfma_f32_16x16x32_bf16 v[126:129], v[146:149], v[188:191], v[126:129]
	v_mfma_f32_16x16x32_bf16 v[122:125], v[138:141], v[206:209], v[122:125]
	v_mfma_f32_16x16x32_bf16 v[118:121], v[146:149], v[206:209], v[118:121]
	v_mfma_f32_16x16x32_bf16 v[114:117], v[138:141], v[228:231], v[114:117]
	v_mfma_f32_16x16x32_bf16 v[110:113], v[146:149], v[228:231], v[110:113]
	v_mfma_f32_16x16x32_bf16 v[106:109], v[138:141], v[236:239], v[106:109]
	v_mfma_f32_16x16x32_bf16 v[102:105], v[146:149], v[236:239], v[102:105]
	s_setprio 0
	s_setprio 1
	v_mfma_f32_16x16x32_bf16 v[98:101], v[162:165], v[178:181], v[98:101]
	v_mfma_f32_16x16x32_bf16 v[94:97], v[170:173], v[178:181], v[94:97]
	v_mfma_f32_16x16x32_bf16 v[90:93], v[162:165], v[192:195], v[90:93]
	v_mfma_f32_16x16x32_bf16 v[86:89], v[170:173], v[192:195], v[86:89]
	v_mfma_f32_16x16x32_bf16 v[82:85], v[162:165], v[224:227], v[82:85]
	v_mfma_f32_16x16x32_bf16 v[78:81], v[170:173], v[224:227], v[78:81]
	v_mfma_f32_16x16x32_bf16 v[74:77], v[162:165], v[232:235], v[74:77]
	v_mfma_f32_16x16x32_bf16 v[70:73], v[170:173], v[232:235], v[70:73]
	v_mfma_f32_16x16x32_bf16 v[98:101], v[166:169], v[188:191], v[98:101]
	v_mfma_f32_16x16x32_bf16 v[94:97], v[174:177], v[188:191], v[94:97]
	v_mfma_f32_16x16x32_bf16 v[90:93], v[166:169], v[206:209], v[90:93]
	v_mfma_f32_16x16x32_bf16 v[86:89], v[174:177], v[206:209], v[86:89]
	v_mfma_f32_16x16x32_bf16 v[82:85], v[166:169], v[228:231], v[82:85]
	v_mfma_f32_16x16x32_bf16 v[78:81], v[174:177], v[228:231], v[78:81]
	v_mfma_f32_16x16x32_bf16 v[74:77], v[166:169], v[236:239], v[74:77]
	v_mfma_f32_16x16x32_bf16 v[70:73], v[174:177], v[236:239], v[70:73]
	s_setprio 0
	s_barrier
	ds_read_b128 v[178:181], v186 offset:49152
	ds_read_b128 v[188:191], v186 offset:50176
	ds_read_b128 v[192:195], v186 offset:51200
	ds_read_b128 v[206:209], v186 offset:52224
	s_add_i32 m0, s94, 0x17f80
	ds_read_b128 v[224:227], v186 offset:53248
	global_load_lds_dwordx4 v152, s[6:7] offset:128
	s_add_i32 m0, s94, 0x19f80
	ds_read_b128 v[228:231], v186 offset:54272
	global_load_lds_dwordx4 v156, s[6:7] offset:128
	s_add_i32 m0, s94, 0x1bf80
	ds_read_b128 v[232:235], v186 offset:55296
	global_load_lds_dwordx4 v211, s[6:7] offset:128
	s_add_i32 m0, s94, 0x1df80
	ds_read_b128 v[236:239], v186 offset:56320
	global_load_lds_dwordx4 v240, s[6:7] offset:128
	s_cmp_ge_i32 s22, s31
	s_cbranch_scc0 .Lx4last_6
	s_add_i32 m0, s30, 0xffffff80
	s_nop 0
	global_load_lds_dwordx4 v150, s[14:15] offset:128
	s_add_i32 m0, s33, 0xffffff80
	s_nop 0
	global_load_lds_dwordx4 v154, s[14:15] offset:128

; #define PG8_STAGE(bufoff, gbase, voff) do { _Pragma("unroll") for (int _i = 0; _i < 2; ++_i) \
;         __builtin_amdgcn_global_load_lds((const unsigned*)((const char*)(gbase) + (voff)[_i]), (LAS unsigned*)(lds + (bufoff) + ldsw + _i * 8192), 16, 0, 0); } while (0)
; #define PG8_LDA(dst, b, h) do { _Pragma("unroll") for (int m = 0; m < 4; ++m) _Pragma("unroll") for (int k = 0; k < 2; ++k) dst[m][k] = *(const LAS bf16x8*)(lds + PG8_SA(b, h) + aoff + m * 2048 + k * 1024); } while (0)
; #define PG8_LDB(dst, b, h) do { _Pragma("unroll") for (int n = 0; n < 2; ++n) _Pragma("unroll") for (int k = 0; k < 2; ++k) dst[n][k] = *(const LAS bf16x8*)(lds + PG8_SB(b, h) + boff + n * 2048 + k * 1024); } while (0)
; #define PG8_MMA(ai, bj, At, Bt) do { __builtin_amdgcn_s_setprio(1); _Pragma("unroll") for (int m = 0; m < 4; ++m) _Pragma("unroll") for (int n = 0; n < 2; ++n) _Pragma("unroll") for (int k = 0; k < 2; ++k) \
;         acc[ai][bj][m][n] = __builtin_amdgcn_mfma_f32_16x16x32_bf16(Bt[n][k], At[m][k], acc[ai][bj][m][n], 0, 0, 0); __builtin_amdgcn_s_setprio(0); } while (0)
; #define PG8_WAIT_V(n) asm volatile("s_waitcnt vmcnt(" #n ")" ::: "memory")
; #define PG8_WAIT_L(n) asm volatile("s_waitcnt lgkmcnt(" #n ")" ::: "memory")
; #define PG8_BAR __builtin_amdgcn_s_barrier()
; template <class Epi, bool ALIGN_EPI = true>
; __device__ __forceinline__ void gemm_phase(LAS unsigned char* lds, const Gemm g, const Sched& S, const Epi& E) {
;     ...
;         for (int t = t_lo; t < t_hi; t += 2) {
;             const bool last = (t == nt - 2);
;             const char* a1 = cA + (size_t)(t + 1) * kstep;
;             const char* a2 = last ? nA : cA + (size_t)(t + 2) * kstep; const char* b2 = last ? nB : cB + (size_t)(t + 2) * kstep;
;             const char* a3 = a2 + kstep; const char* b3 = b2 + kstep;
;             const int rflag = __builtin_amdgcn_readfirstlane(t | (int)(ui == 0));
;             PG8_LDB(B0, 0, 0); PG8_LDB(B1, 0, 1); PG8_SCHED; PG8_LDA(At, 0, 0); PG8_STAGE(PG8_SA(1, 1), a1 + hstepA, voffA);
;             if constexpr (Epi::NSTORES > 0) PG8_WAIT_RELAX(rflag, 8 + Epi::NSTORES); else PG8_WAIT_V(8);
;             PG8_WAIT_L(0); PG8_BAR; PG8_MMA(0, 0, At, B0); PG8_MMA(0, 1, At, B1); PG8_BAR; PG8_SCHED;
;             PG8_LDA(At, 0, 1); PG8_STAGE(PG8_SB(0, 0), b2, voffB); PG8_STAGE(PG8_SB(0, 1), b2 + hstepB, voffB); PG8_STAGE(PG8_SA(0, 0), a2, voffA);
.LBB0_1235:
	s_andn2_b64 vcc, exec, s[16:17]
	s_cbranch_vccnz .LBB0_1232
	s_add_i32 s90, s26, 1
	s_mul_i32 s90, s90, s84
	s_mul_i32 s24, s26, s84
	v_add_u32_e32 v230, 0x80000, v208
	v_add_u32_e32 v231, 0x80000, v196
	v_add_u32_e32 v232, 0x80000, v206
	v_add_u32_e32 v233, 0x80000, v194
.LBB0_1237:
	s_add_i32 s94, s24, 1
	s_lshl_b64 s[92:93], s[94:95], 7
	s_add_i32 s94, s24, 2
	s_lshl_b64 s[26:27], s[94:95], 7
	s_add_u32 s25, s56, s26
	s_addc_u32 s91, s57, s27
	s_add_u32 s96, s54, s26
	s_addc_u32 s97, s55, s27
	s_cmp_eq_u32 s85, s24
	s_cselect_b32 s27, s19, s91
	s_cselect_b32 s26, s87, s25
	s_cselect_b32 s25, s88, s97
	s_cselect_b32 s24, s89, s96
	s_add_u32 s92, s56, s92
	s_addc_u32 s93, s57, s93
	s_add_u32 s92, s92, 0x80000
	s_addc_u32 s93, s93, 0
	s_add_u32 s100, s92, 0xfff80000
	s_addc_u32 s101, s93, -1
	ds_read_b128 v[134:137], v224
	ds_read_b128 v[138:141], v224 offset:1024
	ds_read_b128 v[142:145], v224 offset:2048
	ds_read_b128 v[146:149], v224 offset:3072
	ds_read_b128 v[150:153], v224 offset:16384
	ds_read_b128 v[154:157], v224 offset:17408
	ds_read_b128 v[158:161], v224 offset:18432
	ds_read_b128 v[162:165], v224 offset:19456
	ds_read_b128 v[166:169], v225
	ds_read_b128 v[170:173], v225 offset:1024
	ds_read_b128 v[174:177], v225 offset:2048
	ds_read_b128 v[178:181], v225 offset:3072
	s_mov_b32 m0, s81
	ds_read_b128 v[182:185], v225 offset:4096
	global_load_lds_dwordx4 v208, s[100:101]
	s_mov_b32 m0, s82
	ds_read_b128 v[186:189], v225 offset:5120
	global_load_lds_dwordx4 v196, s[100:101]
	s_add_i32 m0, s36, 0xc000
	ds_read_b128 v[190:193], v225 offset:6144
	global_load_lds_dwordx4 v208, s[92:93]
	s_add_i32 m0, s36, 0xe000
	ds_read_b128 v[226:229], v225 offset:7168
	global_load_lds_dwordx4 v196, s[92:93]
	s_waitcnt vmcnt(8) lgkmcnt(0)
	s_barrier
	s_setprio 1
	v_mfma_f32_16x16x32_bf16 v[130:133], v[134:137], v[166:169], v[130:133]
	v_mfma_f32_16x16x32_bf16 v[126:129], v[142:145], v[166:169], v[126:129]
	v_mfma_f32_16x16x32_bf16 v[114:117], v[134:137], v[174:177], v[114:117]
	v_mfma_f32_16x16x32_bf16 v[110:113], v[142:145], v[174:177], v[110:113]
	v_mfma_f32_16x16x32_bf16 v[98:101], v[134:137], v[182:185], v[98:101]
	v_mfma_f32_16x16x32_bf16 v[94:97], v[142:145], v[182:185], v[94:97]
	v_mfma_f32_16x16x32_bf16 v[82:85], v[134:137], v[190:193], v[82:85]
	v_mfma_f32_16x16x32_bf16 v[78:81], v[142:145], v[190:193], v[78:81]
	v_mfma_f32_16x16x32_bf16 v[130:133], v[138:141], v[170:173], v[130:133]
	v_mfma_f32_16x16x32_bf16 v[126:129], v[146:149], v[170:173], v[126:129]
	v_mfma_f32_16x16x32_bf16 v[114:117], v[138:141], v[178:181], v[114:117]
	v_mfma_f32_16x16x32_bf16 v[110:113], v[146:149], v[178:181], v[110:113]
	v_mfma_f32_16x16x32_bf16 v[98:101], v[138:141], v[186:189], v[98:101]
	v_mfma_f32_16x16x32_bf16 v[94:97], v[146:149], v[186:189], v[94:97]
	v_mfma_f32_16x16x32_bf16 v[82:85], v[138:141], v[226:229], v[82:85]
	v_mfma_f32_16x16x32_bf16 v[78:81], v[146:149], v[226:229], v[78:81]
	s_setprio 0
	s_setprio 1
	v_mfma_f32_16x16x32_bf16 v[122:125], v[150:153], v[166:169], v[122:125]
	v_mfma_f32_16x16x32_bf16 v[118:121], v[158:161], v[166:169], v[118:121]
	v_mfma_f32_16x16x32_bf16 v[106:109], v[150:153], v[174:177], v[106:109]
	v_mfma_f32_16x16x32_bf16 v[102:105], v[158:161], v[174:177], v[102:105]
	v_mfma_f32_16x16x32_bf16 v[90:93], v[150:153], v[182:185], v[90:93]
	v_mfma_f32_16x16x32_bf16 v[86:89], v[158:161], v[182:185], v[86:89]
	v_mfma_f32_16x16x32_bf16 v[74:77], v[150:153], v[190:193], v[74:77]
	v_mfma_f32_16x16x32_bf16 v[70:73], v[158:161], v[190:193], v[70:73]
	v_mfma_f32_16x16x32_bf16 v[122:125], v[154:157], v[170:173], v[122:125]
	v_mfma_f32_16x16x32_bf16 v[118:121], v[162:165], v[170:173], v[118:121]
	v_mfma_f32_16x16x32_bf16 v[106:109], v[154:157], v[178:181], v[106:109]
	v_mfma_f32_16x16x32_bf16 v[102:105], v[162:165], v[178:181], v[102:105]
	v_mfma_f32_16x16x32_bf16 v[90:93], v[154:157], v[186:189], v[90:93]
	v_mfma_f32_16x16x32_bf16 v[86:89], v[162:165], v[186:189], v[86:89]
	v_mfma_f32_16x16x32_bf16 v[74:77], v[154:157], v[226:229], v[74:77]
	v_mfma_f32_16x16x32_bf16 v[70:73], v[162:165], v[226:229], v[70:73]
	s_setprio 0
	s_barrier
	ds_read_b128 v[166:169], v225 offset:16384
	ds_read_b128 v[170:173], v225 offset:17408
	ds_read_b128 v[174:177], v225 offset:18432
	ds_read_b128 v[178:181], v225 offset:19456
	s_add_i32 m0, s35, 0x10000
	ds_read_b128 v[182:185], v225 offset:20480
	global_load_lds_dwordx4 v206, s[24:25]
	s_add_i32 m0, s35, 0x12000
	ds_read_b128 v[186:189], v225 offset:21504
	global_load_lds_dwordx4 v194, s[24:25]
	s_add_i32 m0, s35, 0x14000
	ds_read_b128 v[190:193], v225 offset:22528
	global_load_lds_dwordx4 v232, s[24:25]
	s_add_i32 m0, s35, 0x16000
	ds_read_b128 v[226:229], v225 offset:23552
	global_load_lds_dwordx4 v233, s[24:25]
	s_waitcnt vmcnt(6) lgkmcnt(0)
	s_barrier
; #define PG8_STAGE(bufoff, gbase, voff) do { _Pragma("unroll") for (int _i = 0; _i < 2; ++_i) \
;         __builtin_amdgcn_global_load_lds((const unsigned*)((const char*)(gbase) + (voff)[_i]), (LAS unsigned*)(lds + (bufoff) + ldsw + _i * 8192), 16, 0, 0); } while (0)
; #define PG8_LDA(dst, b, h) do { _Pragma("unroll") for (int m = 0; m < 4; ++m) _Pragma("unroll") for (int k = 0; k < 2; ++k) dst[m][k] = *(const LAS bf16x8*)(lds + PG8_SA(b, h) + aoff + m * 2048 + k * 1024); } while (0)
; #define PG8_LDB(dst, b, h) do { _Pragma("unroll") for (int n = 0; n < 2; ++n) _Pragma("unroll") for (int k = 0; k < 2; ++k) dst[n][k] = *(const LAS bf16x8*)(lds + PG8_SB(b, h) + boff + n * 2048 + k * 1024); } while (0)
; #define PG8_MMA(ai, bj, At, Bt) do { __builtin_amdgcn_s_setprio(1); _Pragma("unroll") for (int m = 0; m < 4; ++m) _Pragma("unroll") for (int n = 0; n < 2; ++n) _Pragma("unroll") for (int k = 0; k < 2; ++k) \
;         acc[ai][bj][m][n] = __builtin_amdgcn_mfma_f32_16x16x32_bf16(Bt[n][k], At[m][k], acc[ai][bj][m][n], 0, 0, 0); __builtin_amdgcn_s_setprio(0); } while (0)
; #define PG8_WAIT_V(n) asm volatile("s_waitcnt vmcnt(" #n ")" ::: "memory")
; #define PG8_WAIT_L(n) asm volatile("s_waitcnt lgkmcnt(" #n ")" ::: "memory")
; #define PG8_BAR __builtin_amdgcn_s_barrier()
; #define PG8_WAIT_RELAX(flag, n) asm volatile("s_cmp_eq_u32 %0, 0\n\ts_cbranch_scc1 .Lrw%=\n\ts_waitcnt vmcnt(8)\n.Lrw%=:\n\ts_waitcnt vmcnt(%1)" :: "s"(flag), "n"(n) : "scc", "memory")
; #define PG8_SCHED __builtin_amdgcn_sched_barrier(0)
; template <class Epi, bool ALIGN_EPI = true>
; __device__ __forceinline__ void gemm_phase(LAS unsigned char* lds, const Gemm g, const Sched& S, const Epi& E) {
;     ...
;             if constexpr (Epi::NSTORES > 0) PG8_WAIT_RELAX(rflag, 8 + Epi::NSTORES); else PG8_WAIT_V(8);
;             PG8_WAIT_L(0); PG8_BAR; PG8_MMA(1, 0, At, B0); PG8_MMA(1, 1, At, B1); PG8_BAR; PG8_SCHED;
;             PG8_LDB(B0, 1, 0); PG8_LDB(B1, 1, 1); PG8_SCHED; PG8_LDA(At, 1, 0); PG8_STAGE(PG8_SA(0, 1), a2 + hstepA, voffA);
	s_setprio 1
	v_mfma_f32_16x16x32_bf16 v[66:69], v[134:137], v[166:169], v[66:69]
	v_mfma_f32_16x16x32_bf16 v[62:65], v[142:145], v[166:169], v[62:65]
	v_mfma_f32_16x16x32_bf16 v[50:53], v[134:137], v[174:177], v[50:53]
	v_mfma_f32_16x16x32_bf16 v[46:49], v[142:145], v[174:177], v[46:49]
	v_mfma_f32_16x16x32_bf16 v[34:37], v[134:137], v[182:185], v[34:37]
	v_mfma_f32_16x16x32_bf16 v[30:33], v[142:145], v[182:185], v[30:33]
	v_mfma_f32_16x16x32_bf16 v[18:21], v[134:137], v[190:193], v[18:21]
	v_mfma_f32_16x16x32_bf16 v[14:17], v[142:145], v[190:193], v[14:17]
	v_mfma_f32_16x16x32_bf16 v[66:69], v[138:141], v[170:173], v[66:69]
	v_mfma_f32_16x16x32_bf16 v[62:65], v[146:149], v[170:173], v[62:65]
	v_mfma_f32_16x16x32_bf16 v[50:53], v[138:141], v[178:181], v[50:53]
	v_mfma_f32_16x16x32_bf16 v[46:49], v[146:149], v[178:181], v[46:49]
	v_mfma_f32_16x16x32_bf16 v[34:37], v[138:141], v[186:189], v[34:37]
	v_mfma_f32_16x16x32_bf16 v[30:33], v[146:149], v[186:189], v[30:33]
	v_mfma_f32_16x16x32_bf16 v[18:21], v[138:141], v[226:229], v[18:21]
	v_mfma_f32_16x16x32_bf16 v[14:17], v[146:149], v[226:229], v[14:17]
	s_setprio 0
	s_setprio 1
	v_mfma_f32_16x16x32_bf16 v[58:61], v[150:153], v[166:169], v[58:61]
	v_mfma_f32_16x16x32_bf16 v[54:57], v[158:161], v[166:169], v[54:57]
	v_mfma_f32_16x16x32_bf16 v[42:45], v[150:153], v[174:177], v[42:45]
	v_mfma_f32_16x16x32_bf16 v[38:41], v[158:161], v[174:177], v[38:41]
	v_mfma_f32_16x16x32_bf16 v[26:29], v[150:153], v[182:185], v[26:29]
	v_mfma_f32_16x16x32_bf16 v[22:25], v[158:161], v[182:185], v[22:25]
	v_mfma_f32_16x16x32_bf16 v[10:13], v[150:153], v[190:193], v[10:13]
	v_mfma_f32_16x16x32_bf16 v[4:7], v[158:161], v[190:193], v[6:9]
	v_mfma_f32_16x16x32_bf16 v[58:61], v[154:157], v[170:173], v[58:61]
	v_mfma_f32_16x16x32_bf16 v[54:57], v[162:165], v[170:173], v[54:57]
	v_mfma_f32_16x16x32_bf16 v[42:45], v[154:157], v[178:181], v[42:45]
	v_mfma_f32_16x16x32_bf16 v[38:41], v[162:165], v[178:181], v[38:41]
	v_mfma_f32_16x16x32_bf16 v[26:29], v[154:157], v[186:189], v[26:29]
	v_mfma_f32_16x16x32_bf16 v[22:25], v[162:165], v[186:189], v[22:25]
	v_mfma_f32_16x16x32_bf16 v[10:13], v[154:157], v[226:229], v[10:13]
	v_mfma_f32_16x16x32_bf16 v[4:7], v[162:165], v[226:229], v[4:7]
	s_setprio 0
	s_barrier
	ds_read_b128 v[134:137], v224 offset:32768
	ds_read_b128 v[138:141], v224 offset:33792
	ds_read_b128 v[142:145], v224 offset:34816
	ds_read_b128 v[146:149], v224 offset:35840
	ds_read_b128 v[150:153], v224 offset:49152
	ds_read_b128 v[154:157], v224 offset:50176
	ds_read_b128 v[158:161], v224 offset:51200
	ds_read_b128 v[162:165], v224 offset:52224
	ds_read_b128 v[166:169], v225 offset:32768
	ds_read_b128 v[170:173], v225 offset:33792
	ds_read_b128 v[174:177], v225 offset:34816
	ds_read_b128 v[178:181], v225 offset:35840
	s_mov_b32 m0, s36
	ds_read_b128 v[182:185], v225 offset:36864
	global_load_lds_dwordx4 v208, s[26:27]
	s_mov_b32 m0, s37
	ds_read_b128 v[186:189], v225 offset:37888
	global_load_lds_dwordx4 v196, s[26:27]
	s_mov_b32 m0, s76
	ds_read_b128 v[190:193], v225 offset:38912
	global_load_lds_dwordx4 v230, s[26:27]
	s_mov_b32 m0, s77
	ds_read_b128 v[226:229], v225 offset:39936
	global_load_lds_dwordx4 v231, s[26:27]
	s_waitcnt vmcnt(8) lgkmcnt(0)
	s_barrier
; #define PG8_STAGE(bufoff, gbase, voff) do { _Pragma("unroll") for (int _i = 0; _i < 2; ++_i) \
;         __builtin_amdgcn_global_load_lds((const unsigned*)((const char*)(gbase) + (voff)[_i]), (LAS unsigned*)(lds + (bufoff) + ldsw + _i * 8192), 16, 0, 0); } while (0)
; #define PG8_LDA(dst, b, h) do { _Pragma("unroll") for (int m = 0; m < 4; ++m) _Pragma("unroll") for (int k = 0; k < 2; ++k) dst[m][k] = *(const LAS bf16x8*)(lds + PG8_SA(b, h) + aoff + m * 2048 + k * 1024); } while (0)
; #define PG8_LDB(dst, b, h) do { _Pragma("unroll") for (int n = 0; n < 2; ++n) _Pragma("unroll") for (int k = 0; k < 2; ++k) dst[n][k] = *(const LAS bf16x8*)(lds + PG8_SB(b, h) + boff + n * 2048 + k * 1024); } while (0)
; #define PG8_MMA(ai, bj, At, Bt) do { __builtin_amdgcn_s_setprio(1); _Pragma("unroll") for (int m = 0; m < 4; ++m) _Pragma("unroll") for (int n = 0; n < 2; ++n) _Pragma("unroll") for (int k = 0; k < 2; ++k) \
;         acc[ai][bj][m][n] = __builtin_amdgcn_mfma_f32_16x16x32_bf16(Bt[n][k], At[m][k], acc[ai][bj][m][n], 0, 0, 0); __builtin_amdgcn_s_setprio(0); } while (0)
; #define PG8_WAIT_V(n) asm volatile("s_waitcnt vmcnt(" #n ")" ::: "memory")
; #define PG8_WAIT_L(n) asm volatile("s_waitcnt lgkmcnt(" #n ")" ::: "memory")
; #define PG8_BAR __builtin_amdgcn_s_barrier()
; #define PG8_SCHED __builtin_amdgcn_sched_barrier(0)
; template <class Epi, bool ALIGN_EPI = true>
; __device__ __forceinline__ void gemm_phase(LAS unsigned char* lds, const Gemm g, const Sched& S, const Epi& E) {
;     ...
;             PG8_LDB(B0, 1, 0); PG8_LDB(B1, 1, 1); PG8_SCHED; PG8_LDA(At, 1, 0); PG8_STAGE(PG8_SA(0, 1), a2 + hstepA, voffA);
;             PG8_WAIT_V(8); PG8_WAIT_L(0); PG8_BAR; PG8_MMA(0, 0, At, B0); PG8_MMA(0, 1, At, B1); PG8_BAR; PG8_SCHED;
;             PG8_LDA(At, 1, 1); PG8_STAGE(PG8_SB(1, 0), b3, voffB); PG8_STAGE(PG8_SB(1, 1), b3 + hstepB, voffB); PG8_STAGE(PG8_SA(1, 0), a3, voffA);
;             PG8_WAIT_V(8); PG8_WAIT_L(0); PG8_BAR; PG8_MMA(1, 0, At, B0); PG8_MMA(1, 1, At, B1); PG8_BAR; PG8_SCHED;
;         }
	s_setprio 1
	v_mfma_f32_16x16x32_bf16 v[130:133], v[134:137], v[166:169], v[130:133]
	v_mfma_f32_16x16x32_bf16 v[126:129], v[142:145], v[166:169], v[126:129]
	v_mfma_f32_16x16x32_bf16 v[114:117], v[134:137], v[174:177], v[114:117]
	v_mfma_f32_16x16x32_bf16 v[110:113], v[142:145], v[174:177], v[110:113]
	v_mfma_f32_16x16x32_bf16 v[98:101], v[134:137], v[182:185], v[98:101]
	v_mfma_f32_16x16x32_bf16 v[94:97], v[142:145], v[182:185], v[94:97]
	v_mfma_f32_16x16x32_bf16 v[82:85], v[134:137], v[190:193], v[82:85]
	v_mfma_f32_16x16x32_bf16 v[78:81], v[142:145], v[190:193], v[78:81]
	v_mfma_f32_16x16x32_bf16 v[130:133], v[138:141], v[170:173], v[130:133]
	v_mfma_f32_16x16x32_bf16 v[126:129], v[146:149], v[170:173], v[126:129]
	v_mfma_f32_16x16x32_bf16 v[114:117], v[138:141], v[178:181], v[114:117]
	v_mfma_f32_16x16x32_bf16 v[110:113], v[146:149], v[178:181], v[110:113]
	v_mfma_f32_16x16x32_bf16 v[98:101], v[138:141], v[186:189], v[98:101]
	v_mfma_f32_16x16x32_bf16 v[94:97], v[146:149], v[186:189], v[94:97]
	v_mfma_f32_16x16x32_bf16 v[82:85], v[138:141], v[226:229], v[82:85]
	v_mfma_f32_16x16x32_bf16 v[78:81], v[146:149], v[226:229], v[78:81]
	s_setprio 0
	s_setprio 1
	v_mfma_f32_16x16x32_bf16 v[122:125], v[150:153], v[166:169], v[122:125]
	v_mfma_f32_16x16x32_bf16 v[118:121], v[158:161], v[166:169], v[118:121]
	v_mfma_f32_16x16x32_bf16 v[106:109], v[150:153], v[174:177], v[106:109]
	v_mfma_f32_16x16x32_bf16 v[102:105], v[158:161], v[174:177], v[102:105]
	v_mfma_f32_16x16x32_bf16 v[90:93], v[150:153], v[182:185], v[90:93]
	v_mfma_f32_16x16x32_bf16 v[86:89], v[158:161], v[182:185], v[86:89]
	v_mfma_f32_16x16x32_bf16 v[74:77], v[150:153], v[190:193], v[74:77]
	v_mfma_f32_16x16x32_bf16 v[70:73], v[158:161], v[190:193], v[70:73]
	v_mfma_f32_16x16x32_bf16 v[122:125], v[154:157], v[170:173], v[122:125]
	v_mfma_f32_16x16x32_bf16 v[118:121], v[162:165], v[170:173], v[118:121]
	v_mfma_f32_16x16x32_bf16 v[106:109], v[154:157], v[178:181], v[106:109]
	v_mfma_f32_16x16x32_bf16 v[102:105], v[162:165], v[178:181], v[102:105]
	v_mfma_f32_16x16x32_bf16 v[90:93], v[154:157], v[186:189], v[90:93]
	v_mfma_f32_16x16x32_bf16 v[86:89], v[162:165], v[186:189], v[86:89]
	v_mfma_f32_16x16x32_bf16 v[74:77], v[154:157], v[226:229], v[74:77]
	v_mfma_f32_16x16x32_bf16 v[70:73], v[162:165], v[226:229], v[70:73]
	s_setprio 0
	s_barrier
	ds_read_b128 v[166:169], v225 offset:49152
	ds_read_b128 v[170:173], v225 offset:50176
	ds_read_b128 v[174:177], v225 offset:51200
	ds_read_b128 v[178:181], v225 offset:52224
	s_add_i32 m0, s35, 0x17f80
	ds_read_b128 v[182:185], v225 offset:53248
	global_load_lds_dwordx4 v206, s[24:25] offset:128
	s_add_i32 m0, s35, 0x19f80
	ds_read_b128 v[186:189], v225 offset:54272
	global_load_lds_dwordx4 v194, s[24:25] offset:128
	s_add_i32 m0, s35, 0x1bf80
	ds_read_b128 v[190:193], v225 offset:55296
	global_load_lds_dwordx4 v232, s[24:25] offset:128
	s_add_i32 m0, s35, 0x1df80
	ds_read_b128 v[226:229], v225 offset:56320
	global_load_lds_dwordx4 v233, s[24:25] offset:128
	s_waitcnt vmcnt(6) lgkmcnt(0)
	s_barrier
	s_setprio 1
	v_mfma_f32_16x16x32_bf16 v[66:69], v[134:137], v[166:169], v[66:69]
	v_mfma_f32_16x16x32_bf16 v[62:65], v[142:145], v[166:169], v[62:65]
	v_mfma_f32_16x16x32_bf16 v[50:53], v[134:137], v[174:177], v[50:53]
	v_mfma_f32_16x16x32_bf16 v[46:49], v[142:145], v[174:177], v[46:49]
	v_mfma_f32_16x16x32_bf16 v[34:37], v[134:137], v[182:185], v[34:37]
	v_mfma_f32_16x16x32_bf16 v[30:33], v[142:145], v[182:185], v[30:33]
	v_mfma_f32_16x16x32_bf16 v[18:21], v[134:137], v[190:193], v[18:21]
	v_mfma_f32_16x16x32_bf16 v[14:17], v[142:145], v[190:193], v[14:17]
	v_mfma_f32_16x16x32_bf16 v[66:69], v[138:141], v[170:173], v[66:69]
	v_mfma_f32_16x16x32_bf16 v[62:65], v[146:149], v[170:173], v[62:65]
	v_mfma_f32_16x16x32_bf16 v[50:53], v[138:141], v[178:181], v[50:53]
	v_mfma_f32_16x16x32_bf16 v[46:49], v[146:149], v[178:181], v[46:49]
	v_mfma_f32_16x16x32_bf16 v[34:37], v[138:141], v[186:189], v[34:37]
	v_mfma_f32_16x16x32_bf16 v[30:33], v[146:149], v[186:189], v[30:33]
	v_mfma_f32_16x16x32_bf16 v[18:21], v[138:141], v[226:229], v[18:21]
	v_mfma_f32_16x16x32_bf16 v[14:17], v[146:149], v[226:229], v[14:17]
	s_setprio 0
	s_setprio 1
	v_mfma_f32_16x16x32_bf16 v[58:61], v[150:153], v[166:169], v[58:61]
	v_mfma_f32_16x16x32_bf16 v[54:57], v[158:161], v[166:169], v[54:57]
	v_mfma_f32_16x16x32_bf16 v[42:45], v[150:153], v[174:177], v[42:45]
	v_mfma_f32_16x16x32_bf16 v[38:41], v[158:161], v[174:177], v[38:41]
	v_mfma_f32_16x16x32_bf16 v[26:29], v[150:153], v[182:185], v[26:29]
	v_mfma_f32_16x16x32_bf16 v[22:25], v[158:161], v[182:185], v[22:25]
	v_mfma_f32_16x16x32_bf16 v[8:11], v[150:153], v[190:193], v[10:13]
	v_mfma_f32_16x16x32_bf16 v[4:7], v[158:161], v[190:193], v[4:7]
	v_mfma_f32_16x16x32_bf16 v[58:61], v[154:157], v[170:173], v[58:61]
	v_mfma_f32_16x16x32_bf16 v[54:57], v[162:165], v[170:173], v[54:57]
	v_mfma_f32_16x16x32_bf16 v[42:45], v[154:157], v[178:181], v[42:45]
	v_mfma_f32_16x16x32_bf16 v[38:41], v[162:165], v[178:181], v[38:41]
	v_mfma_f32_16x16x32_bf16 v[26:29], v[154:157], v[186:189], v[26:29]
	v_mfma_f32_16x16x32_bf16 v[22:25], v[162:165], v[186:189], v[22:25]
	v_mfma_f32_16x16x32_bf16 v[10:13], v[154:157], v[226:229], v[8:11]
	v_mfma_f32_16x16x32_bf16 v[6:9], v[162:165], v[226:229], v[4:7]
	s_setprio 0
	s_barrier
	s_cmp_ge_i32 s94, s90
	s_mov_b32 s24, s94
	s_cbranch_scc0 .LBB0_1237
	s_add_i32 s26, s35, 0x1c000
	s_mov_b32 s91, 0x18000
	s_mov_b32 s92, 0x1c000
	s_mov_b32 vcc_lo, 0x10000
	s_branch .LBB0_1232

; #define PG8_STAGE(bufoff, gbase, voff) do { _Pragma("unroll") for (int _i = 0; _i < 2; ++_i) \
;         __builtin_amdgcn_global_load_lds((const unsigned*)((const char*)(gbase) + (voff)[_i]), (LAS unsigned*)(lds + (bufoff) + ldsw + _i * 8192), 16, 0, 0); } while (0)
; #define PG8_LDA(dst, b, h) do { _Pragma("unroll") for (int m = 0; m < 4; ++m) _Pragma("unroll") for (int k = 0; k < 2; ++k) dst[m][k] = *(const LAS bf16x8*)(lds + PG8_SA(b, h) + aoff + m * 2048 + k * 1024); } while (0)
; #define PG8_LDB(dst, b, h) do { _Pragma("unroll") for (int n = 0; n < 2; ++n) _Pragma("unroll") for (int k = 0; k < 2; ++k) dst[n][k] = *(const LAS bf16x8*)(lds + PG8_SB(b, h) + boff + n * 2048 + k * 1024); } while (0)
; #define PG8_MMA(ai, bj, At, Bt) do { __builtin_amdgcn_s_setprio(1); _Pragma("unroll") for (int m = 0; m < 4; ++m) _Pragma("unroll") for (int n = 0; n < 2; ++n) _Pragma("unroll") for (int k = 0; k < 2; ++k) \
;         acc[ai][bj][m][n] = __builtin_amdgcn_mfma_f32_16x16x32_bf16(Bt[n][k], At[m][k], acc[ai][bj][m][n], 0, 0, 0); __builtin_amdgcn_s_setprio(0); } while (0)
; #define PG8_WAIT_V(n) asm volatile("s_waitcnt vmcnt(" #n ")" ::: "memory")
; #define PG8_WAIT_L(n) asm volatile("s_waitcnt lgkmcnt(" #n ")" ::: "memory")
; #define PG8_BAR __builtin_amdgcn_s_barrier()
; template <class Epi, bool ALIGN_EPI = true>
; __device__ __forceinline__ void gemm_phase(LAS unsigned char* lds, const Gemm g, const Sched& S, const Epi& E) {
;     ...
;         for (int t = t_lo; t < t_hi; t += 2) {
;             const bool last = (t == nt - 2);
;             const char* a1 = cA + (size_t)(t + 1) * kstep;
;             const char* a2 = last ? nA : cA + (size_t)(t + 2) * kstep; const char* b2 = last ? nB : cB + (size_t)(t + 2) * kstep;
;             const char* a3 = a2 + kstep; const char* b3 = b2 + kstep;
;             const int rflag = __builtin_amdgcn_readfirstlane(t | (int)(ui == 0));
;             PG8_LDB(B0, 0, 0); PG8_LDB(B1, 0, 1); PG8_SCHED; PG8_LDA(At, 0, 0); PG8_STAGE(PG8_SA(1, 1), a1 + hstepA, voffA);
;             if constexpr (Epi::NSTORES > 0) PG8_WAIT_RELAX(rflag, 8 + Epi::NSTORES); else PG8_WAIT_V(8);
;             PG8_WAIT_L(0); PG8_BAR; PG8_MMA(0, 0, At, B0); PG8_MMA(0, 1, At, B1); PG8_BAR; PG8_SCHED;
;             PG8_LDA(At, 0, 1); PG8_STAGE(PG8_SB(0, 0), b2, voffB); PG8_STAGE(PG8_SB(0, 1), b2 + hstepB, voffB); PG8_STAGE(PG8_SA(0, 0), a2, voffA);
.LBB0_1309:
	s_add_u32 s26, s33, s24
	s_addc_u32 s27, s34, s25
	s_add_u32 s42, s35, s40
	s_addc_u32 s43, s36, s41
	s_andn2_b64 vcc, exec, s[18:19]
	s_cbranch_vccnz .LBB0_1312
	s_and_b64 s[46:47], s[44:45], exec
	s_cselect_b32 s21, s27, s17
	s_cselect_b32 s23, s26, s16
	s_cselect_b32 s63, s43, s15
	s_cselect_b32 s64, s42, s14
	s_add_u32 s46, s16, 0x80080
	s_addc_u32 s47, s17, 0
	s_add_u32 s65, s14, 0x100
	s_addc_u32 s66, s15, 0
	s_mov_b32 s48, 0
	v_add_u32_e32 v236, 0x80000, v140
	v_add_u32_e32 v237, 0x80000, v136
	v_add_u32_e32 v238, 0x80000, v138
	v_add_u32_e32 v239, 0x80000, v134
.LBB0_1311:
	s_add_i32 s67, s48, 2
	s_add_u32 s49, s46, 0xfff80080
	s_addc_u32 s50, s47, -1
	s_cmp_eq_u32 s59, s48
	s_cselect_b32 s51, s21, s50
	s_cselect_b32 s50, s23, s49
	s_cselect_b32 s49, s63, s66
	s_cselect_b32 s48, s64, s65
	s_add_u32 s100, s46, 0xfff80000
	s_addc_u32 s101, s47, -1
	ds_read_b128 v[150:153], v147
	ds_read_b128 v[154:157], v147 offset:1024
	ds_read_b128 v[158:161], v147 offset:2048
	ds_read_b128 v[162:165], v147 offset:3072
	ds_read_b128 v[166:169], v147 offset:16384
	ds_read_b128 v[170:173], v147 offset:17408
	ds_read_b128 v[174:177], v147 offset:18432
	ds_read_b128 v[178:181], v147 offset:19456
	ds_read_b128 v[182:185], v148
	ds_read_b128 v[186:189], v148 offset:1024
	ds_read_b128 v[190:193], v148 offset:2048
	ds_read_b128 v[194:197], v148 offset:3072
	s_mov_b32 m0, s57
	ds_read_b128 v[206:209], v148 offset:4096
	global_load_lds_dwordx4 v142, s[100:101]
	s_mov_b32 m0, s58
	ds_read_b128 v[224:227], v148 offset:5120
	global_load_lds_dwordx4 v144, s[100:101]
	s_add_i32 m0, s52, 0xc000
	ds_read_b128 v[228:231], v148 offset:6144
	global_load_lds_dwordx4 v142, s[46:47]
	s_add_i32 m0, s52, 0xe000
	ds_read_b128 v[232:235], v148 offset:7168
	global_load_lds_dwordx4 v144, s[46:47]
	s_waitcnt vmcnt(8) lgkmcnt(0)
	s_barrier
	s_setprio 1
	v_mfma_f32_16x16x32_bf16 v[130:133], v[150:153], v[182:185], v[130:133]
	v_mfma_f32_16x16x32_bf16 v[126:129], v[158:161], v[182:185], v[126:129]
	v_mfma_f32_16x16x32_bf16 v[114:117], v[150:153], v[190:193], v[114:117]
	v_mfma_f32_16x16x32_bf16 v[110:113], v[158:161], v[190:193], v[110:113]
	v_mfma_f32_16x16x32_bf16 v[98:101], v[150:153], v[206:209], v[98:101]
	v_mfma_f32_16x16x32_bf16 v[94:97], v[158:161], v[206:209], v[94:97]
	v_mfma_f32_16x16x32_bf16 v[82:85], v[150:153], v[228:231], v[82:85]
	v_mfma_f32_16x16x32_bf16 v[78:81], v[158:161], v[228:231], v[78:81]
	v_mfma_f32_16x16x32_bf16 v[130:133], v[154:157], v[186:189], v[130:133]
	v_mfma_f32_16x16x32_bf16 v[126:129], v[162:165], v[186:189], v[126:129]
	v_mfma_f32_16x16x32_bf16 v[114:117], v[154:157], v[194:197], v[114:117]
	v_mfma_f32_16x16x32_bf16 v[110:113], v[162:165], v[194:197], v[110:113]
	v_mfma_f32_16x16x32_bf16 v[98:101], v[154:157], v[224:227], v[98:101]
	v_mfma_f32_16x16x32_bf16 v[94:97], v[162:165], v[224:227], v[94:97]
	v_mfma_f32_16x16x32_bf16 v[82:85], v[154:157], v[232:235], v[82:85]
	v_mfma_f32_16x16x32_bf16 v[78:81], v[162:165], v[232:235], v[78:81]
	s_setprio 0
	s_setprio 1
	v_mfma_f32_16x16x32_bf16 v[122:125], v[166:169], v[182:185], v[122:125]
	v_mfma_f32_16x16x32_bf16 v[118:121], v[174:177], v[182:185], v[118:121]
	v_mfma_f32_16x16x32_bf16 v[106:109], v[166:169], v[190:193], v[106:109]
	v_mfma_f32_16x16x32_bf16 v[102:105], v[174:177], v[190:193], v[102:105]
	v_mfma_f32_16x16x32_bf16 v[90:93], v[166:169], v[206:209], v[90:93]
	v_mfma_f32_16x16x32_bf16 v[86:89], v[174:177], v[206:209], v[86:89]
	v_mfma_f32_16x16x32_bf16 v[74:77], v[166:169], v[228:231], v[74:77]
	v_mfma_f32_16x16x32_bf16 v[70:73], v[174:177], v[228:231], v[70:73]
	v_mfma_f32_16x16x32_bf16 v[122:125], v[170:173], v[186:189], v[122:125]
	v_mfma_f32_16x16x32_bf16 v[118:121], v[178:181], v[186:189], v[118:121]
	v_mfma_f32_16x16x32_bf16 v[106:109], v[170:173], v[194:197], v[106:109]
	v_mfma_f32_16x16x32_bf16 v[102:105], v[178:181], v[194:197], v[102:105]
	v_mfma_f32_16x16x32_bf16 v[90:93], v[170:173], v[224:227], v[90:93]
	v_mfma_f32_16x16x32_bf16 v[86:89], v[178:181], v[224:227], v[86:89]
	v_mfma_f32_16x16x32_bf16 v[74:77], v[170:173], v[232:235], v[74:77]
	v_mfma_f32_16x16x32_bf16 v[70:73], v[178:181], v[232:235], v[70:73]
	s_setprio 0
	s_barrier
	ds_read_b128 v[182:185], v148 offset:16384
	ds_read_b128 v[186:189], v148 offset:17408
	ds_read_b128 v[190:193], v148 offset:18432
	ds_read_b128 v[194:197], v148 offset:19456
	s_add_i32 m0, s37, 0x10000
	ds_read_b128 v[206:209], v148 offset:20480
	global_load_lds_dwordx4 v138, s[48:49]
	s_add_i32 m0, s37, 0x12000
	ds_read_b128 v[224:227], v148 offset:21504
	global_load_lds_dwordx4 v134, s[48:49]
	s_add_i32 m0, s37, 0x14000
	ds_read_b128 v[228:231], v148 offset:22528
	global_load_lds_dwordx4 v238, s[48:49]
	s_add_i32 m0, s37, 0x16000
	ds_read_b128 v[232:235], v148 offset:23552
	global_load_lds_dwordx4 v239, s[48:49]
	s_waitcnt vmcnt(6) lgkmcnt(0)
	s_barrier
; #define PG8_STAGE(bufoff, gbase, voff) do { _Pragma("unroll") for (int _i = 0; _i < 2; ++_i) \
;         __builtin_amdgcn_global_load_lds((const unsigned*)((const char*)(gbase) + (voff)[_i]), (LAS unsigned*)(lds + (bufoff) + ldsw + _i * 8192), 16, 0, 0); } while (0)
; #define PG8_LDA(dst, b, h) do { _Pragma("unroll") for (int m = 0; m < 4; ++m) _Pragma("unroll") for (int k = 0; k < 2; ++k) dst[m][k] = *(const LAS bf16x8*)(lds + PG8_SA(b, h) + aoff + m * 2048 + k * 1024); } while (0)
; #define PG8_LDB(dst, b, h) do { _Pragma("unroll") for (int n = 0; n < 2; ++n) _Pragma("unroll") for (int k = 0; k < 2; ++k) dst[n][k] = *(const LAS bf16x8*)(lds + PG8_SB(b, h) + boff + n * 2048 + k * 1024); } while (0)
; #define PG8_MMA(ai, bj, At, Bt) do { __builtin_amdgcn_s_setprio(1); _Pragma("unroll") for (int m = 0; m < 4; ++m) _Pragma("unroll") for (int n = 0; n < 2; ++n) _Pragma("unroll") for (int k = 0; k < 2; ++k) \
;         acc[ai][bj][m][n] = __builtin_amdgcn_mfma_f32_16x16x32_bf16(Bt[n][k], At[m][k], acc[ai][bj][m][n], 0, 0, 0); __builtin_amdgcn_s_setprio(0); } while (0)
; #define PG8_WAIT_V(n) asm volatile("s_waitcnt vmcnt(" #n ")" ::: "memory")
; #define PG8_WAIT_L(n) asm volatile("s_waitcnt lgkmcnt(" #n ")" ::: "memory")
; #define PG8_BAR __builtin_amdgcn_s_barrier()
; #define PG8_WAIT_RELAX(flag, n) asm volatile("s_cmp_eq_u32 %0, 0\n\ts_cbranch_scc1 .Lrw%=\n\ts_waitcnt vmcnt(8)\n.Lrw%=:\n\ts_waitcnt vmcnt(%1)" :: "s"(flag), "n"(n) : "scc", "memory")
; #define PG8_SCHED __builtin_amdgcn_sched_barrier(0)
; template <class Epi, bool ALIGN_EPI = true>
; __device__ __forceinline__ void gemm_phase(LAS unsigned char* lds, const Gemm g, const Sched& S, const Epi& E) {
;     ...
;             if constexpr (Epi::NSTORES > 0) PG8_WAIT_RELAX(rflag, 8 + Epi::NSTORES); else PG8_WAIT_V(8);
;             PG8_WAIT_L(0); PG8_BAR; PG8_MMA(1, 0, At, B0); PG8_MMA(1, 1, At, B1); PG8_BAR; PG8_SCHED;
;             PG8_LDB(B0, 1, 0); PG8_LDB(B1, 1, 1); PG8_SCHED; PG8_LDA(At, 1, 0); PG8_STAGE(PG8_SA(0, 1), a2 + hstepA, voffA);
;             PG8_WAIT_V(8); PG8_WAIT_L(0); PG8_BAR; PG8_MMA(0, 0, At, B0); PG8_MMA(0, 1, At, B1); PG8_BAR; PG8_SCHED;
	s_setprio 1
	v_mfma_f32_16x16x32_bf16 v[66:69], v[150:153], v[182:185], v[66:69]
	v_mfma_f32_16x16x32_bf16 v[62:65], v[158:161], v[182:185], v[62:65]
	v_mfma_f32_16x16x32_bf16 v[50:53], v[150:153], v[190:193], v[50:53]
	v_mfma_f32_16x16x32_bf16 v[46:49], v[158:161], v[190:193], v[46:49]
	v_mfma_f32_16x16x32_bf16 v[34:37], v[150:153], v[206:209], v[34:37]
	v_mfma_f32_16x16x32_bf16 v[30:33], v[158:161], v[206:209], v[30:33]
	v_mfma_f32_16x16x32_bf16 v[18:21], v[150:153], v[228:231], v[18:21]
	v_mfma_f32_16x16x32_bf16 v[14:17], v[158:161], v[228:231], v[14:17]
	v_mfma_f32_16x16x32_bf16 v[66:69], v[154:157], v[186:189], v[66:69]
	v_mfma_f32_16x16x32_bf16 v[62:65], v[162:165], v[186:189], v[62:65]
	v_mfma_f32_16x16x32_bf16 v[50:53], v[154:157], v[194:197], v[50:53]
	v_mfma_f32_16x16x32_bf16 v[46:49], v[162:165], v[194:197], v[46:49]
	v_mfma_f32_16x16x32_bf16 v[34:37], v[154:157], v[224:227], v[34:37]
	v_mfma_f32_16x16x32_bf16 v[30:33], v[162:165], v[224:227], v[30:33]
	v_mfma_f32_16x16x32_bf16 v[18:21], v[154:157], v[232:235], v[18:21]
	v_mfma_f32_16x16x32_bf16 v[14:17], v[162:165], v[232:235], v[14:17]
	s_setprio 0
	s_setprio 1
	v_mfma_f32_16x16x32_bf16 v[58:61], v[166:169], v[182:185], v[58:61]
	v_mfma_f32_16x16x32_bf16 v[54:57], v[174:177], v[182:185], v[54:57]
	v_mfma_f32_16x16x32_bf16 v[42:45], v[166:169], v[190:193], v[42:45]
	v_mfma_f32_16x16x32_bf16 v[38:41], v[174:177], v[190:193], v[38:41]
	v_mfma_f32_16x16x32_bf16 v[26:29], v[166:169], v[206:209], v[26:29]
	v_mfma_f32_16x16x32_bf16 v[22:25], v[174:177], v[206:209], v[22:25]
	v_mfma_f32_16x16x32_bf16 v[10:13], v[166:169], v[228:231], v[10:13]
	v_mfma_f32_16x16x32_bf16 v[4:7], v[174:177], v[228:231], v[6:9]
	v_mfma_f32_16x16x32_bf16 v[58:61], v[170:173], v[186:189], v[58:61]
	v_mfma_f32_16x16x32_bf16 v[54:57], v[178:181], v[186:189], v[54:57]
	v_mfma_f32_16x16x32_bf16 v[42:45], v[170:173], v[194:197], v[42:45]
	v_mfma_f32_16x16x32_bf16 v[38:41], v[178:181], v[194:197], v[38:41]
	v_mfma_f32_16x16x32_bf16 v[26:29], v[170:173], v[224:227], v[26:29]
	v_mfma_f32_16x16x32_bf16 v[22:25], v[178:181], v[224:227], v[22:25]
	v_mfma_f32_16x16x32_bf16 v[10:13], v[170:173], v[232:235], v[10:13]
	v_mfma_f32_16x16x32_bf16 v[4:7], v[178:181], v[232:235], v[4:7]
	s_setprio 0
	s_barrier
	ds_read_b128 v[150:153], v147 offset:32768
	ds_read_b128 v[154:157], v147 offset:33792
	ds_read_b128 v[158:161], v147 offset:34816
	ds_read_b128 v[162:165], v147 offset:35840
	ds_read_b128 v[166:169], v147 offset:49152
	ds_read_b128 v[170:173], v147 offset:50176
	ds_read_b128 v[174:177], v147 offset:51200
	ds_read_b128 v[178:181], v147 offset:52224
	ds_read_b128 v[182:185], v148 offset:32768
	ds_read_b128 v[186:189], v148 offset:33792
	ds_read_b128 v[190:193], v148 offset:34816
	ds_read_b128 v[194:197], v148 offset:35840
	s_mov_b32 m0, s52
	ds_read_b128 v[206:209], v148 offset:36864
	global_load_lds_dwordx4 v140, s[50:51]
	s_mov_b32 m0, s53
	ds_read_b128 v[224:227], v148 offset:37888
	global_load_lds_dwordx4 v136, s[50:51]
	s_mov_b32 m0, s54
	ds_read_b128 v[228:231], v148 offset:38912
	global_load_lds_dwordx4 v236, s[50:51]
	s_mov_b32 m0, s55
	ds_read_b128 v[232:235], v148 offset:39936
	global_load_lds_dwordx4 v237, s[50:51]
	s_waitcnt vmcnt(8) lgkmcnt(0)
	s_barrier
	s_setprio 1
	v_mfma_f32_16x16x32_bf16 v[130:133], v[150:153], v[182:185], v[130:133]
	v_mfma_f32_16x16x32_bf16 v[126:129], v[158:161], v[182:185], v[126:129]
	v_mfma_f32_16x16x32_bf16 v[114:117], v[150:153], v[190:193], v[114:117]
	v_mfma_f32_16x16x32_bf16 v[110:113], v[158:161], v[190:193], v[110:113]
	v_mfma_f32_16x16x32_bf16 v[98:101], v[150:153], v[206:209], v[98:101]
	v_mfma_f32_16x16x32_bf16 v[94:97], v[158:161], v[206:209], v[94:97]
	v_mfma_f32_16x16x32_bf16 v[82:85], v[150:153], v[228:231], v[82:85]
	v_mfma_f32_16x16x32_bf16 v[78:81], v[158:161], v[228:231], v[78:81]
	v_mfma_f32_16x16x32_bf16 v[130:133], v[154:157], v[186:189], v[130:133]
	v_mfma_f32_16x16x32_bf16 v[126:129], v[162:165], v[186:189], v[126:129]
	v_mfma_f32_16x16x32_bf16 v[114:117], v[154:157], v[194:197], v[114:117]
	v_mfma_f32_16x16x32_bf16 v[110:113], v[162:165], v[194:197], v[110:113]
	v_mfma_f32_16x16x32_bf16 v[98:101], v[154:157], v[224:227], v[98:101]
	v_mfma_f32_16x16x32_bf16 v[94:97], v[162:165], v[224:227], v[94:97]
	v_mfma_f32_16x16x32_bf16 v[82:85], v[154:157], v[232:235], v[82:85]
	v_mfma_f32_16x16x32_bf16 v[78:81], v[162:165], v[232:235], v[78:81]
	s_setprio 0
	s_setprio 1
	v_mfma_f32_16x16x32_bf16 v[122:125], v[166:169], v[182:185], v[122:125]
	v_mfma_f32_16x16x32_bf16 v[118:121], v[174:177], v[182:185], v[118:121]
	v_mfma_f32_16x16x32_bf16 v[106:109], v[166:169], v[190:193], v[106:109]
	v_mfma_f32_16x16x32_bf16 v[102:105], v[174:177], v[190:193], v[102:105]
	v_mfma_f32_16x16x32_bf16 v[90:93], v[166:169], v[206:209], v[90:93]
	v_mfma_f32_16x16x32_bf16 v[86:89], v[174:177], v[206:209], v[86:89]
	v_mfma_f32_16x16x32_bf16 v[74:77], v[166:169], v[228:231], v[74:77]
	v_mfma_f32_16x16x32_bf16 v[70:73], v[174:177], v[228:231], v[70:73]
	v_mfma_f32_16x16x32_bf16 v[122:125], v[170:173], v[186:189], v[122:125]
	v_mfma_f32_16x16x32_bf16 v[118:121], v[178:181], v[186:189], v[118:121]
	v_mfma_f32_16x16x32_bf16 v[106:109], v[170:173], v[194:197], v[106:109]
	v_mfma_f32_16x16x32_bf16 v[102:105], v[178:181], v[194:197], v[102:105]
	v_mfma_f32_16x16x32_bf16 v[90:93], v[170:173], v[224:227], v[90:93]
	v_mfma_f32_16x16x32_bf16 v[86:89], v[178:181], v[224:227], v[86:89]
	v_mfma_f32_16x16x32_bf16 v[74:77], v[170:173], v[232:235], v[74:77]
	v_mfma_f32_16x16x32_bf16 v[70:73], v[178:181], v[232:235], v[70:73]
	s_setprio 0
	s_barrier
; #define PG8_STAGE(bufoff, gbase, voff) do { _Pragma("unroll") for (int _i = 0; _i < 2; ++_i) \
;         __builtin_amdgcn_global_load_lds((const unsigned*)((const char*)(gbase) + (voff)[_i]), (LAS unsigned*)(lds + (bufoff) + ldsw + _i * 8192), 16, 0, 0); } while (0)
; #define PG8_LDA(dst, b, h) do { _Pragma("unroll") for (int m = 0; m < 4; ++m) _Pragma("unroll") for (int k = 0; k < 2; ++k) dst[m][k] = *(const LAS bf16x8*)(lds + PG8_SA(b, h) + aoff + m * 2048 + k * 1024); } while (0)
; #define PG8_MMA(ai, bj, At, Bt) do { __builtin_amdgcn_s_setprio(1); _Pragma("unroll") for (int m = 0; m < 4; ++m) _Pragma("unroll") for (int n = 0; n < 2; ++n) _Pragma("unroll") for (int k = 0; k < 2; ++k) \
;         acc[ai][bj][m][n] = __builtin_amdgcn_mfma_f32_16x16x32_bf16(Bt[n][k], At[m][k], acc[ai][bj][m][n], 0, 0, 0); __builtin_amdgcn_s_setprio(0); } while (0)
; #define PG8_WAIT_V(n) asm volatile("s_waitcnt vmcnt(" #n ")" ::: "memory")
; #define PG8_WAIT_L(n) asm volatile("s_waitcnt lgkmcnt(" #n ")" ::: "memory")
; #define PG8_BAR __builtin_amdgcn_s_barrier()
; #define PG8_SCHED __builtin_amdgcn_sched_barrier(0)
; template <class Epi, bool ALIGN_EPI = true>
; __device__ __forceinline__ void gemm_phase(LAS unsigned char* lds, const Gemm g, const Sched& S, const Epi& E) {
;     ...
;             PG8_LDA(At, 1, 1); PG8_STAGE(PG8_SB(1, 0), b3, voffB); PG8_STAGE(PG8_SB(1, 1), b3 + hstepB, voffB); PG8_STAGE(PG8_SA(1, 0), a3, voffA);
;             PG8_WAIT_V(8); PG8_WAIT_L(0); PG8_BAR; PG8_MMA(1, 0, At, B0); PG8_MMA(1, 1, At, B1); PG8_BAR; PG8_SCHED;
;         }
	ds_read_b128 v[182:185], v148 offset:49152
	ds_read_b128 v[186:189], v148 offset:50176
	ds_read_b128 v[190:193], v148 offset:51200
	ds_read_b128 v[194:197], v148 offset:52224
	s_add_i32 m0, s37, 0x17f80
	ds_read_b128 v[206:209], v148 offset:53248
	global_load_lds_dwordx4 v138, s[48:49] offset:128
	s_add_i32 m0, s37, 0x19f80
	ds_read_b128 v[224:227], v148 offset:54272
	global_load_lds_dwordx4 v134, s[48:49] offset:128
	s_add_i32 m0, s37, 0x1bf80
	ds_read_b128 v[228:231], v148 offset:55296
	global_load_lds_dwordx4 v238, s[48:49] offset:128
	s_add_i32 m0, s37, 0x1df80
	ds_read_b128 v[232:235], v148 offset:56320
	global_load_lds_dwordx4 v239, s[48:49] offset:128
	s_waitcnt vmcnt(6) lgkmcnt(0)
	s_barrier
	s_setprio 1
	v_mfma_f32_16x16x32_bf16 v[66:69], v[150:153], v[182:185], v[66:69]
	v_mfma_f32_16x16x32_bf16 v[62:65], v[158:161], v[182:185], v[62:65]
	v_mfma_f32_16x16x32_bf16 v[50:53], v[150:153], v[190:193], v[50:53]
	v_mfma_f32_16x16x32_bf16 v[46:49], v[158:161], v[190:193], v[46:49]
	v_mfma_f32_16x16x32_bf16 v[34:37], v[150:153], v[206:209], v[34:37]
	v_mfma_f32_16x16x32_bf16 v[30:33], v[158:161], v[206:209], v[30:33]
	v_mfma_f32_16x16x32_bf16 v[18:21], v[150:153], v[228:231], v[18:21]
	v_mfma_f32_16x16x32_bf16 v[14:17], v[158:161], v[228:231], v[14:17]
	v_mfma_f32_16x16x32_bf16 v[66:69], v[154:157], v[186:189], v[66:69]
	v_mfma_f32_16x16x32_bf16 v[62:65], v[162:165], v[186:189], v[62:65]
	v_mfma_f32_16x16x32_bf16 v[50:53], v[154:157], v[194:197], v[50:53]
	v_mfma_f32_16x16x32_bf16 v[46:49], v[162:165], v[194:197], v[46:49]
	v_mfma_f32_16x16x32_bf16 v[34:37], v[154:157], v[224:227], v[34:37]
	v_mfma_f32_16x16x32_bf16 v[30:33], v[162:165], v[224:227], v[30:33]
	v_mfma_f32_16x16x32_bf16 v[18:21], v[154:157], v[232:235], v[18:21]
	v_mfma_f32_16x16x32_bf16 v[14:17], v[162:165], v[232:235], v[14:17]
	s_setprio 0
	s_setprio 1
	v_mfma_f32_16x16x32_bf16 v[58:61], v[166:169], v[182:185], v[58:61]
	v_mfma_f32_16x16x32_bf16 v[54:57], v[174:177], v[182:185], v[54:57]
	v_mfma_f32_16x16x32_bf16 v[42:45], v[166:169], v[190:193], v[42:45]
	v_mfma_f32_16x16x32_bf16 v[38:41], v[174:177], v[190:193], v[38:41]
	v_mfma_f32_16x16x32_bf16 v[26:29], v[166:169], v[206:209], v[26:29]
	v_mfma_f32_16x16x32_bf16 v[22:25], v[174:177], v[206:209], v[22:25]
	v_mfma_f32_16x16x32_bf16 v[8:11], v[166:169], v[228:231], v[10:13]
	v_mfma_f32_16x16x32_bf16 v[4:7], v[174:177], v[228:231], v[4:7]
	v_mfma_f32_16x16x32_bf16 v[58:61], v[170:173], v[186:189], v[58:61]
	v_mfma_f32_16x16x32_bf16 v[54:57], v[178:181], v[186:189], v[54:57]
	v_mfma_f32_16x16x32_bf16 v[42:45], v[170:173], v[194:197], v[42:45]
	v_mfma_f32_16x16x32_bf16 v[38:41], v[178:181], v[194:197], v[38:41]
	v_mfma_f32_16x16x32_bf16 v[26:29], v[170:173], v[224:227], v[26:29]
	v_mfma_f32_16x16x32_bf16 v[22:25], v[178:181], v[224:227], v[22:25]
	v_mfma_f32_16x16x32_bf16 v[10:13], v[170:173], v[232:235], v[8:11]
	v_mfma_f32_16x16x32_bf16 v[6:9], v[178:181], v[232:235], v[4:7]
	s_setprio 0
	s_barrier
	s_add_u32 s46, s46, 0x100
	s_addc_u32 s47, s47, 0
	s_add_u32 s65, s65, 0x100
	s_addc_u32 s66, s66, 0
	s_cmp_ge_i32 s67, s56
	s_mov_b32 s48, s67
	s_cbranch_scc0 .LBB0_1311
	s_add_i32 s50, s37, 0x1c000
	s_mov_b32 s68, 0x18000
	s_mov_b32 s69, 0x1c000
	s_add_i32 s70, s37, 0x14000

; #define PG8_STAGE(bufoff, gbase, voff) do { _Pragma("unroll") for (int _i = 0; _i < 2; ++_i) \
;         __builtin_amdgcn_global_load_lds((const unsigned*)((const char*)(gbase) + (voff)[_i]), (LAS unsigned*)(lds + (bufoff) + ldsw + _i * 8192), 16, 0, 0); } while (0)
; #define PG8_LDA(dst, b, h) do { _Pragma("unroll") for (int m = 0; m < 4; ++m) _Pragma("unroll") for (int k = 0; k < 2; ++k) dst[m][k] = *(const LAS bf16x8*)(lds + PG8_SA(b, h) + aoff + m * 2048 + k * 1024); } while (0)
; #define PG8_LDB(dst, b, h) do { _Pragma("unroll") for (int n = 0; n < 2; ++n) _Pragma("unroll") for (int k = 0; k < 2; ++k) dst[n][k] = *(const LAS bf16x8*)(lds + PG8_SB(b, h) + boff + n * 2048 + k * 1024); } while (0)
; #define PG8_MMA(ai, bj, At, Bt) do { __builtin_amdgcn_s_setprio(1); _Pragma("unroll") for (int m = 0; m < 4; ++m) _Pragma("unroll") for (int n = 0; n < 2; ++n) _Pragma("unroll") for (int k = 0; k < 2; ++k) \
;         acc[ai][bj][m][n] = __builtin_amdgcn_mfma_f32_16x16x32_bf16(Bt[n][k], At[m][k], acc[ai][bj][m][n], 0, 0, 0); __builtin_amdgcn_s_setprio(0); } while (0)
; #define PG8_WAIT_V(n) asm volatile("s_waitcnt vmcnt(" #n ")" ::: "memory")
; #define PG8_WAIT_L(n) asm volatile("s_waitcnt lgkmcnt(" #n ")" ::: "memory")
; #define PG8_BAR __builtin_amdgcn_s_barrier()
; template <class Epi, bool ALIGN_EPI = true>
; __device__ __forceinline__ void gemm_phase(LAS unsigned char* lds, const Gemm g, const Sched& S, const Epi& E) {
;     ...
;         for (int t = t_lo; t < t_hi; t += 2) {
;             const bool last = (t == nt - 2);
;             const char* a1 = cA + (size_t)(t + 1) * kstep;
;             const char* a2 = last ? nA : cA + (size_t)(t + 2) * kstep; const char* b2 = last ? nB : cB + (size_t)(t + 2) * kstep;
;             const char* a3 = a2 + kstep; const char* b3 = b2 + kstep;
;             const int rflag = __builtin_amdgcn_readfirstlane(t | (int)(ui == 0));
;             PG8_LDB(B0, 0, 0); PG8_LDB(B1, 0, 1); PG8_SCHED; PG8_LDA(At, 0, 0); PG8_STAGE(PG8_SA(1, 1), a1 + hstepA, voffA);
;             if constexpr (Epi::NSTORES > 0) PG8_WAIT_RELAX(rflag, 8 + Epi::NSTORES); else PG8_WAIT_V(8);
;             PG8_WAIT_L(0); PG8_BAR; PG8_MMA(0, 0, At, B0); PG8_MMA(0, 1, At, B1); PG8_BAR; PG8_SCHED;
;             PG8_LDA(At, 0, 1); PG8_STAGE(PG8_SB(0, 0), b2, voffB); PG8_STAGE(PG8_SB(0, 1), b2 + hstepB, voffB); PG8_STAGE(PG8_SA(0, 0), a2, voffA);
.LBB0_1400:
	s_add_u32 s26, s35, s22
	s_addc_u32 s27, s36, s23
	s_add_u32 s40, s37, s24
	s_addc_u32 s41, s50, s25
	s_andn2_b64 vcc, exec, s[16:17]
	s_cbranch_vccnz .LBB0_1403
	s_and_b64 s[44:45], s[42:43], exec
	s_cselect_b32 s19, s27, s15
	s_cselect_b32 s21, s26, s14
	s_cselect_b32 s63, s41, s7
	s_cselect_b32 s64, s40, s6
	s_add_u32 s44, s14, 0x80080
	s_addc_u32 s45, s15, 0
	s_add_u32 s65, s6, 0x100
	s_addc_u32 s66, s7, 0
	s_mov_b32 s46, 0
	v_add_u32_e32 v236, 0x80000, v140
	v_add_u32_e32 v237, 0x80000, v136
	v_add_u32_e32 v238, 0x80000, v138
	v_add_u32_e32 v239, 0x80000, v134
.LBB0_1402:
	s_add_i32 s67, s46, 2
	s_add_u32 s47, s44, 0xfff80080
	s_addc_u32 s48, s45, -1
	s_cmp_eq_u32 s59, s46
	s_cselect_b32 s49, s19, s48
	s_cselect_b32 s48, s21, s47
	s_cselect_b32 s47, s63, s66
	s_cselect_b32 s46, s64, s65
	s_add_u32 s100, s44, 0xfff80000
	s_addc_u32 s101, s45, -1
	ds_read_b128 v[150:153], v147
	ds_read_b128 v[154:157], v147 offset:1024
	ds_read_b128 v[158:161], v147 offset:2048
	ds_read_b128 v[162:165], v147 offset:3072
	ds_read_b128 v[166:169], v147 offset:16384
	ds_read_b128 v[170:173], v147 offset:17408
	ds_read_b128 v[174:177], v147 offset:18432
	ds_read_b128 v[178:181], v147 offset:19456
	ds_read_b128 v[182:185], v148
	ds_read_b128 v[186:189], v148 offset:1024
	ds_read_b128 v[190:193], v148 offset:2048
	ds_read_b128 v[194:197], v148 offset:3072
	s_mov_b32 m0, s57
	ds_read_b128 v[206:209], v148 offset:4096
	global_load_lds_dwordx4 v142, s[100:101]
	s_mov_b32 m0, s58
	ds_read_b128 v[224:227], v148 offset:5120
	global_load_lds_dwordx4 v144, s[100:101]
	s_add_i32 m0, s52, 0xc000
	ds_read_b128 v[228:231], v148 offset:6144
	global_load_lds_dwordx4 v142, s[44:45]
	s_add_i32 m0, s52, 0xe000
	ds_read_b128 v[232:235], v148 offset:7168
	global_load_lds_dwordx4 v144, s[44:45]
	s_waitcnt vmcnt(8) lgkmcnt(0)
	s_barrier
	s_setprio 1
	v_mfma_f32_16x16x32_bf16 v[130:133], v[150:153], v[182:185], v[130:133]
	v_mfma_f32_16x16x32_bf16 v[126:129], v[158:161], v[182:185], v[126:129]
	v_mfma_f32_16x16x32_bf16 v[114:117], v[150:153], v[190:193], v[114:117]
	v_mfma_f32_16x16x32_bf16 v[110:113], v[158:161], v[190:193], v[110:113]
	v_mfma_f32_16x16x32_bf16 v[98:101], v[150:153], v[206:209], v[98:101]
	v_mfma_f32_16x16x32_bf16 v[94:97], v[158:161], v[206:209], v[94:97]
	v_mfma_f32_16x16x32_bf16 v[82:85], v[150:153], v[228:231], v[82:85]
	v_mfma_f32_16x16x32_bf16 v[78:81], v[158:161], v[228:231], v[78:81]
	v_mfma_f32_16x16x32_bf16 v[130:133], v[154:157], v[186:189], v[130:133]
	v_mfma_f32_16x16x32_bf16 v[126:129], v[162:165], v[186:189], v[126:129]
	v_mfma_f32_16x16x32_bf16 v[114:117], v[154:157], v[194:197], v[114:117]
	v_mfma_f32_16x16x32_bf16 v[110:113], v[162:165], v[194:197], v[110:113]
	v_mfma_f32_16x16x32_bf16 v[98:101], v[154:157], v[224:227], v[98:101]
	v_mfma_f32_16x16x32_bf16 v[94:97], v[162:165], v[224:227], v[94:97]
	v_mfma_f32_16x16x32_bf16 v[82:85], v[154:157], v[232:235], v[82:85]
	v_mfma_f32_16x16x32_bf16 v[78:81], v[162:165], v[232:235], v[78:81]
	s_setprio 0
	s_setprio 1
	v_mfma_f32_16x16x32_bf16 v[122:125], v[166:169], v[182:185], v[122:125]
	v_mfma_f32_16x16x32_bf16 v[118:121], v[174:177], v[182:185], v[118:121]
	v_mfma_f32_16x16x32_bf16 v[106:109], v[166:169], v[190:193], v[106:109]
	v_mfma_f32_16x16x32_bf16 v[102:105], v[174:177], v[190:193], v[102:105]
	v_mfma_f32_16x16x32_bf16 v[90:93], v[166:169], v[206:209], v[90:93]
	v_mfma_f32_16x16x32_bf16 v[86:89], v[174:177], v[206:209], v[86:89]
	v_mfma_f32_16x16x32_bf16 v[74:77], v[166:169], v[228:231], v[74:77]
	v_mfma_f32_16x16x32_bf16 v[70:73], v[174:177], v[228:231], v[70:73]
	v_mfma_f32_16x16x32_bf16 v[122:125], v[170:173], v[186:189], v[122:125]
	v_mfma_f32_16x16x32_bf16 v[118:121], v[178:181], v[186:189], v[118:121]
	v_mfma_f32_16x16x32_bf16 v[106:109], v[170:173], v[194:197], v[106:109]
	v_mfma_f32_16x16x32_bf16 v[102:105], v[178:181], v[194:197], v[102:105]
	v_mfma_f32_16x16x32_bf16 v[90:93], v[170:173], v[224:227], v[90:93]
	v_mfma_f32_16x16x32_bf16 v[86:89], v[178:181], v[224:227], v[86:89]
	v_mfma_f32_16x16x32_bf16 v[74:77], v[170:173], v[232:235], v[74:77]
	v_mfma_f32_16x16x32_bf16 v[70:73], v[178:181], v[232:235], v[70:73]
	s_setprio 0
	s_barrier
	ds_read_b128 v[182:185], v148 offset:16384
	ds_read_b128 v[186:189], v148 offset:17408
	ds_read_b128 v[190:193], v148 offset:18432
	ds_read_b128 v[194:197], v148 offset:19456
	s_add_i32 m0, s51, 0x10000
	ds_read_b128 v[206:209], v148 offset:20480
	global_load_lds_dwordx4 v138, s[46:47]
	s_add_i32 m0, s51, 0x12000
	ds_read_b128 v[224:227], v148 offset:21504
	global_load_lds_dwordx4 v134, s[46:47]
	s_add_i32 m0, s51, 0x14000
	ds_read_b128 v[228:231], v148 offset:22528
	global_load_lds_dwordx4 v238, s[46:47]
	s_add_i32 m0, s51, 0x16000
	ds_read_b128 v[232:235], v148 offset:23552
	global_load_lds_dwordx4 v239, s[46:47]
	s_waitcnt vmcnt(6) lgkmcnt(0)
	s_barrier
; #define PG8_STAGE(bufoff, gbase, voff) do { _Pragma("unroll") for (int _i = 0; _i < 2; ++_i) \
;         __builtin_amdgcn_global_load_lds((const unsigned*)((const char*)(gbase) + (voff)[_i]), (LAS unsigned*)(lds + (bufoff) + ldsw + _i * 8192), 16, 0, 0); } while (0)
; #define PG8_LDA(dst, b, h) do { _Pragma("unroll") for (int m = 0; m < 4; ++m) _Pragma("unroll") for (int k = 0; k < 2; ++k) dst[m][k] = *(const LAS bf16x8*)(lds + PG8_SA(b, h) + aoff + m * 2048 + k * 1024); } while (0)
; #define PG8_LDB(dst, b, h) do { _Pragma("unroll") for (int n = 0; n < 2; ++n) _Pragma("unroll") for (int k = 0; k < 2; ++k) dst[n][k] = *(const LAS bf16x8*)(lds + PG8_SB(b, h) + boff + n * 2048 + k * 1024); } while (0)
; #define PG8_MMA(ai, bj, At, Bt) do { __builtin_amdgcn_s_setprio(1); _Pragma("unroll") for (int m = 0; m < 4; ++m) _Pragma("unroll") for (int n = 0; n < 2; ++n) _Pragma("unroll") for (int k = 0; k < 2; ++k) \
;         acc[ai][bj][m][n] = __builtin_amdgcn_mfma_f32_16x16x32_bf16(Bt[n][k], At[m][k], acc[ai][bj][m][n], 0, 0, 0); __builtin_amdgcn_s_setprio(0); } while (0)
; #define PG8_WAIT_V(n) asm volatile("s_waitcnt vmcnt(" #n ")" ::: "memory")
; #define PG8_WAIT_L(n) asm volatile("s_waitcnt lgkmcnt(" #n ")" ::: "memory")
; #define PG8_BAR __builtin_amdgcn_s_barrier()
; #define PG8_WAIT_RELAX(flag, n) asm volatile("s_cmp_eq_u32 %0, 0\n\ts_cbranch_scc1 .Lrw%=\n\ts_waitcnt vmcnt(8)\n.Lrw%=:\n\ts_waitcnt vmcnt(%1)" :: "s"(flag), "n"(n) : "scc", "memory")
; #define PG8_SCHED __builtin_amdgcn_sched_barrier(0)
; template <class Epi, bool ALIGN_EPI = true>
; __device__ __forceinline__ void gemm_phase(LAS unsigned char* lds, const Gemm g, const Sched& S, const Epi& E) {
;     ...
;             if constexpr (Epi::NSTORES > 0) PG8_WAIT_RELAX(rflag, 8 + Epi::NSTORES); else PG8_WAIT_V(8);
;             PG8_WAIT_L(0); PG8_BAR; PG8_MMA(1, 0, At, B0); PG8_MMA(1, 1, At, B1); PG8_BAR; PG8_SCHED;
;             PG8_LDB(B0, 1, 0); PG8_LDB(B1, 1, 1); PG8_SCHED; PG8_LDA(At, 1, 0); PG8_STAGE(PG8_SA(0, 1), a2 + hstepA, voffA);
;             PG8_WAIT_V(8); PG8_WAIT_L(0); PG8_BAR; PG8_MMA(0, 0, At, B0); PG8_MMA(0, 1, At, B1); PG8_BAR; PG8_SCHED;
	s_setprio 1
	v_mfma_f32_16x16x32_bf16 v[66:69], v[150:153], v[182:185], v[66:69]
	v_mfma_f32_16x16x32_bf16 v[62:65], v[158:161], v[182:185], v[62:65]
	v_mfma_f32_16x16x32_bf16 v[50:53], v[150:153], v[190:193], v[50:53]
	v_mfma_f32_16x16x32_bf16 v[46:49], v[158:161], v[190:193], v[46:49]
	v_mfma_f32_16x16x32_bf16 v[34:37], v[150:153], v[206:209], v[34:37]
	v_mfma_f32_16x16x32_bf16 v[30:33], v[158:161], v[206:209], v[30:33]
	v_mfma_f32_16x16x32_bf16 v[18:21], v[150:153], v[228:231], v[18:21]
	v_mfma_f32_16x16x32_bf16 v[14:17], v[158:161], v[228:231], v[14:17]
	v_mfma_f32_16x16x32_bf16 v[66:69], v[154:157], v[186:189], v[66:69]
	v_mfma_f32_16x16x32_bf16 v[62:65], v[162:165], v[186:189], v[62:65]
	v_mfma_f32_16x16x32_bf16 v[50:53], v[154:157], v[194:197], v[50:53]
	v_mfma_f32_16x16x32_bf16 v[46:49], v[162:165], v[194:197], v[46:49]
	v_mfma_f32_16x16x32_bf16 v[34:37], v[154:157], v[224:227], v[34:37]
	v_mfma_f32_16x16x32_bf16 v[30:33], v[162:165], v[224:227], v[30:33]
	v_mfma_f32_16x16x32_bf16 v[18:21], v[154:157], v[232:235], v[18:21]
	v_mfma_f32_16x16x32_bf16 v[14:17], v[162:165], v[232:235], v[14:17]
	s_setprio 0
	s_setprio 1
	v_mfma_f32_16x16x32_bf16 v[58:61], v[166:169], v[182:185], v[58:61]
	v_mfma_f32_16x16x32_bf16 v[54:57], v[174:177], v[182:185], v[54:57]
	v_mfma_f32_16x16x32_bf16 v[42:45], v[166:169], v[190:193], v[42:45]
	v_mfma_f32_16x16x32_bf16 v[38:41], v[174:177], v[190:193], v[38:41]
	v_mfma_f32_16x16x32_bf16 v[26:29], v[166:169], v[206:209], v[26:29]
	v_mfma_f32_16x16x32_bf16 v[22:25], v[174:177], v[206:209], v[22:25]
	v_mfma_f32_16x16x32_bf16 v[10:13], v[166:169], v[228:231], v[10:13]
	v_mfma_f32_16x16x32_bf16 v[4:7], v[174:177], v[228:231], v[6:9]
	v_mfma_f32_16x16x32_bf16 v[58:61], v[170:173], v[186:189], v[58:61]
	v_mfma_f32_16x16x32_bf16 v[54:57], v[178:181], v[186:189], v[54:57]
	v_mfma_f32_16x16x32_bf16 v[42:45], v[170:173], v[194:197], v[42:45]
	v_mfma_f32_16x16x32_bf16 v[38:41], v[178:181], v[194:197], v[38:41]
	v_mfma_f32_16x16x32_bf16 v[26:29], v[170:173], v[224:227], v[26:29]
	v_mfma_f32_16x16x32_bf16 v[22:25], v[178:181], v[224:227], v[22:25]
	v_mfma_f32_16x16x32_bf16 v[10:13], v[170:173], v[232:235], v[10:13]
	v_mfma_f32_16x16x32_bf16 v[4:7], v[178:181], v[232:235], v[4:7]
	s_setprio 0
	s_barrier
	ds_read_b128 v[150:153], v147 offset:32768
	ds_read_b128 v[154:157], v147 offset:33792
	ds_read_b128 v[158:161], v147 offset:34816
	ds_read_b128 v[162:165], v147 offset:35840
	ds_read_b128 v[166:169], v147 offset:49152
	ds_read_b128 v[170:173], v147 offset:50176
	ds_read_b128 v[174:177], v147 offset:51200
	ds_read_b128 v[178:181], v147 offset:52224
	ds_read_b128 v[182:185], v148 offset:32768
	ds_read_b128 v[186:189], v148 offset:33792
	ds_read_b128 v[190:193], v148 offset:34816
	ds_read_b128 v[194:197], v148 offset:35840
	s_mov_b32 m0, s52
	ds_read_b128 v[206:209], v148 offset:36864
	global_load_lds_dwordx4 v140, s[48:49]
	s_mov_b32 m0, s53
	ds_read_b128 v[224:227], v148 offset:37888
	global_load_lds_dwordx4 v136, s[48:49]
	s_mov_b32 m0, s54
	ds_read_b128 v[228:231], v148 offset:38912
	global_load_lds_dwordx4 v236, s[48:49]
	s_mov_b32 m0, s55
	ds_read_b128 v[232:235], v148 offset:39936
	global_load_lds_dwordx4 v237, s[48:49]
	s_waitcnt vmcnt(8) lgkmcnt(0)
	s_barrier
	s_setprio 1
	v_mfma_f32_16x16x32_bf16 v[130:133], v[150:153], v[182:185], v[130:133]
	v_mfma_f32_16x16x32_bf16 v[126:129], v[158:161], v[182:185], v[126:129]
	v_mfma_f32_16x16x32_bf16 v[114:117], v[150:153], v[190:193], v[114:117]
	v_mfma_f32_16x16x32_bf16 v[110:113], v[158:161], v[190:193], v[110:113]
	v_mfma_f32_16x16x32_bf16 v[98:101], v[150:153], v[206:209], v[98:101]
	v_mfma_f32_16x16x32_bf16 v[94:97], v[158:161], v[206:209], v[94:97]
	v_mfma_f32_16x16x32_bf16 v[82:85], v[150:153], v[228:231], v[82:85]
	v_mfma_f32_16x16x32_bf16 v[78:81], v[158:161], v[228:231], v[78:81]
	v_mfma_f32_16x16x32_bf16 v[130:133], v[154:157], v[186:189], v[130:133]
	v_mfma_f32_16x16x32_bf16 v[126:129], v[162:165], v[186:189], v[126:129]
	v_mfma_f32_16x16x32_bf16 v[114:117], v[154:157], v[194:197], v[114:117]
	v_mfma_f32_16x16x32_bf16 v[110:113], v[162:165], v[194:197], v[110:113]
	v_mfma_f32_16x16x32_bf16 v[98:101], v[154:157], v[224:227], v[98:101]
	v_mfma_f32_16x16x32_bf16 v[94:97], v[162:165], v[224:227], v[94:97]
	v_mfma_f32_16x16x32_bf16 v[82:85], v[154:157], v[232:235], v[82:85]
	v_mfma_f32_16x16x32_bf16 v[78:81], v[162:165], v[232:235], v[78:81]
	s_setprio 0
	s_setprio 1
	v_mfma_f32_16x16x32_bf16 v[122:125], v[166:169], v[182:185], v[122:125]
	v_mfma_f32_16x16x32_bf16 v[118:121], v[174:177], v[182:185], v[118:121]
	v_mfma_f32_16x16x32_bf16 v[106:109], v[166:169], v[190:193], v[106:109]
	v_mfma_f32_16x16x32_bf16 v[102:105], v[174:177], v[190:193], v[102:105]
	v_mfma_f32_16x16x32_bf16 v[90:93], v[166:169], v[206:209], v[90:93]
	v_mfma_f32_16x16x32_bf16 v[86:89], v[174:177], v[206:209], v[86:89]
	v_mfma_f32_16x16x32_bf16 v[74:77], v[166:169], v[228:231], v[74:77]
	v_mfma_f32_16x16x32_bf16 v[70:73], v[174:177], v[228:231], v[70:73]
	v_mfma_f32_16x16x32_bf16 v[122:125], v[170:173], v[186:189], v[122:125]
	v_mfma_f32_16x16x32_bf16 v[118:121], v[178:181], v[186:189], v[118:121]
	v_mfma_f32_16x16x32_bf16 v[106:109], v[170:173], v[194:197], v[106:109]
	v_mfma_f32_16x16x32_bf16 v[102:105], v[178:181], v[194:197], v[102:105]
	v_mfma_f32_16x16x32_bf16 v[90:93], v[170:173], v[224:227], v[90:93]
	v_mfma_f32_16x16x32_bf16 v[86:89], v[178:181], v[224:227], v[86:89]
	v_mfma_f32_16x16x32_bf16 v[74:77], v[170:173], v[232:235], v[74:77]
	v_mfma_f32_16x16x32_bf16 v[70:73], v[178:181], v[232:235], v[70:73]
	s_setprio 0
	s_barrier
; #define PG8_STAGE(bufoff, gbase, voff) do { _Pragma("unroll") for (int _i = 0; _i < 2; ++_i) \
;         __builtin_amdgcn_global_load_lds((const unsigned*)((const char*)(gbase) + (voff)[_i]), (LAS unsigned*)(lds + (bufoff) + ldsw + _i * 8192), 16, 0, 0); } while (0)
; #define PG8_LDA(dst, b, h) do { _Pragma("unroll") for (int m = 0; m < 4; ++m) _Pragma("unroll") for (int k = 0; k < 2; ++k) dst[m][k] = *(const LAS bf16x8*)(lds + PG8_SA(b, h) + aoff + m * 2048 + k * 1024); } while (0)
; #define PG8_MMA(ai, bj, At, Bt) do { __builtin_amdgcn_s_setprio(1); _Pragma("unroll") for (int m = 0; m < 4; ++m) _Pragma("unroll") for (int n = 0; n < 2; ++n) _Pragma("unroll") for (int k = 0; k < 2; ++k) \
;         acc[ai][bj][m][n] = __builtin_amdgcn_mfma_f32_16x16x32_bf16(Bt[n][k], At[m][k], acc[ai][bj][m][n], 0, 0, 0); __builtin_amdgcn_s_setprio(0); } while (0)
; #define PG8_WAIT_V(n) asm volatile("s_waitcnt vmcnt(" #n ")" ::: "memory")
; #define PG8_WAIT_L(n) asm volatile("s_waitcnt lgkmcnt(" #n ")" ::: "memory")
; #define PG8_BAR __builtin_amdgcn_s_barrier()
; #define PG8_SCHED __builtin_amdgcn_sched_barrier(0)
; template <class Epi, bool ALIGN_EPI = true>
; __device__ __forceinline__ void gemm_phase(LAS unsigned char* lds, const Gemm g, const Sched& S, const Epi& E) {
;     ...
;             PG8_LDA(At, 1, 1); PG8_STAGE(PG8_SB(1, 0), b3, voffB); PG8_STAGE(PG8_SB(1, 1), b3 + hstepB, voffB); PG8_STAGE(PG8_SA(1, 0), a3, voffA);
;             PG8_WAIT_V(8); PG8_WAIT_L(0); PG8_BAR; PG8_MMA(1, 0, At, B0); PG8_MMA(1, 1, At, B1); PG8_BAR; PG8_SCHED;
;         }
	ds_read_b128 v[182:185], v148 offset:49152
	ds_read_b128 v[186:189], v148 offset:50176
	ds_read_b128 v[190:193], v148 offset:51200
	ds_read_b128 v[194:197], v148 offset:52224
	s_add_i32 m0, s51, 0x17f80
	ds_read_b128 v[206:209], v148 offset:53248
	global_load_lds_dwordx4 v138, s[46:47] offset:128
	s_add_i32 m0, s51, 0x19f80
	ds_read_b128 v[224:227], v148 offset:54272
	global_load_lds_dwordx4 v134, s[46:47] offset:128
	s_add_i32 m0, s51, 0x1bf80
	ds_read_b128 v[228:231], v148 offset:55296
	global_load_lds_dwordx4 v238, s[46:47] offset:128
	s_add_i32 m0, s51, 0x1df80
	ds_read_b128 v[232:235], v148 offset:56320
	global_load_lds_dwordx4 v239, s[46:47] offset:128
	s_waitcnt vmcnt(6) lgkmcnt(0)
	s_barrier
	s_setprio 1
	v_mfma_f32_16x16x32_bf16 v[66:69], v[150:153], v[182:185], v[66:69]
	v_mfma_f32_16x16x32_bf16 v[62:65], v[158:161], v[182:185], v[62:65]
	v_mfma_f32_16x16x32_bf16 v[50:53], v[150:153], v[190:193], v[50:53]
	v_mfma_f32_16x16x32_bf16 v[46:49], v[158:161], v[190:193], v[46:49]
	v_mfma_f32_16x16x32_bf16 v[34:37], v[150:153], v[206:209], v[34:37]
	v_mfma_f32_16x16x32_bf16 v[30:33], v[158:161], v[206:209], v[30:33]
	v_mfma_f32_16x16x32_bf16 v[18:21], v[150:153], v[228:231], v[18:21]
	v_mfma_f32_16x16x32_bf16 v[14:17], v[158:161], v[228:231], v[14:17]
	v_mfma_f32_16x16x32_bf16 v[66:69], v[154:157], v[186:189], v[66:69]
	v_mfma_f32_16x16x32_bf16 v[62:65], v[162:165], v[186:189], v[62:65]
	v_mfma_f32_16x16x32_bf16 v[50:53], v[154:157], v[194:197], v[50:53]
	v_mfma_f32_16x16x32_bf16 v[46:49], v[162:165], v[194:197], v[46:49]
	v_mfma_f32_16x16x32_bf16 v[34:37], v[154:157], v[224:227], v[34:37]
	v_mfma_f32_16x16x32_bf16 v[30:33], v[162:165], v[224:227], v[30:33]
	v_mfma_f32_16x16x32_bf16 v[18:21], v[154:157], v[232:235], v[18:21]
	v_mfma_f32_16x16x32_bf16 v[14:17], v[162:165], v[232:235], v[14:17]
	s_setprio 0
	s_setprio 1
	v_mfma_f32_16x16x32_bf16 v[58:61], v[166:169], v[182:185], v[58:61]
	v_mfma_f32_16x16x32_bf16 v[54:57], v[174:177], v[182:185], v[54:57]
	v_mfma_f32_16x16x32_bf16 v[42:45], v[166:169], v[190:193], v[42:45]
	v_mfma_f32_16x16x32_bf16 v[38:41], v[174:177], v[190:193], v[38:41]
	v_mfma_f32_16x16x32_bf16 v[26:29], v[166:169], v[206:209], v[26:29]
	v_mfma_f32_16x16x32_bf16 v[22:25], v[174:177], v[206:209], v[22:25]
	v_mfma_f32_16x16x32_bf16 v[8:11], v[166:169], v[228:231], v[10:13]
	v_mfma_f32_16x16x32_bf16 v[4:7], v[174:177], v[228:231], v[4:7]
	v_mfma_f32_16x16x32_bf16 v[58:61], v[170:173], v[186:189], v[58:61]
	v_mfma_f32_16x16x32_bf16 v[54:57], v[178:181], v[186:189], v[54:57]
	v_mfma_f32_16x16x32_bf16 v[42:45], v[170:173], v[194:197], v[42:45]
	v_mfma_f32_16x16x32_bf16 v[38:41], v[178:181], v[194:197], v[38:41]
	v_mfma_f32_16x16x32_bf16 v[26:29], v[170:173], v[224:227], v[26:29]
	v_mfma_f32_16x16x32_bf16 v[22:25], v[178:181], v[224:227], v[22:25]
	v_mfma_f32_16x16x32_bf16 v[10:13], v[170:173], v[232:235], v[8:11]
	v_mfma_f32_16x16x32_bf16 v[6:9], v[178:181], v[232:235], v[4:7]
	s_setprio 0
	s_barrier
	s_add_u32 s44, s44, 0x100
	s_addc_u32 s45, s45, 0
	s_add_u32 s65, s65, 0x100
	s_addc_u32 s66, s66, 0
	s_cmp_ge_i32 s67, s56
	s_mov_b32 s46, s67
	s_cbranch_scc0 .LBB0_1402
	s_add_i32 s48, s51, 0x1c000
	s_mov_b32 s68, 0x18000
	s_mov_b32 s69, 0x1c000
	s_add_i32 s70, s51, 0x14000

; #define PG8_STAGE(bufoff, gbase, voff) do { _Pragma("unroll") for (int _i = 0; _i < 2; ++_i) \
;         __builtin_amdgcn_global_load_lds((const unsigned*)((const char*)(gbase) + (voff)[_i]), (LAS unsigned*)(lds + (bufoff) + ldsw + _i * 8192), 16, 0, 0); } while (0)
; #define PG8_LDA(dst, b, h) do { _Pragma("unroll") for (int m = 0; m < 4; ++m) _Pragma("unroll") for (int k = 0; k < 2; ++k) dst[m][k] = *(const LAS bf16x8*)(lds + PG8_SA(b, h) + aoff + m * 2048 + k * 1024); } while (0)
; #define PG8_LDB(dst, b, h) do { _Pragma("unroll") for (int n = 0; n < 2; ++n) _Pragma("unroll") for (int k = 0; k < 2; ++k) dst[n][k] = *(const LAS bf16x8*)(lds + PG8_SB(b, h) + boff + n * 2048 + k * 1024); } while (0)
; #define PG8_MMA(ai, bj, At, Bt) do { __builtin_amdgcn_s_setprio(1); _Pragma("unroll") for (int m = 0; m < 4; ++m) _Pragma("unroll") for (int n = 0; n < 2; ++n) _Pragma("unroll") for (int k = 0; k < 2; ++k) \
;         acc[ai][bj][m][n] = __builtin_amdgcn_mfma_f32_16x16x32_bf16(Bt[n][k], At[m][k], acc[ai][bj][m][n], 0, 0, 0); __builtin_amdgcn_s_setprio(0); } while (0)
; #define PG8_WAIT_V(n) asm volatile("s_waitcnt vmcnt(" #n ")" ::: "memory")
; #define PG8_WAIT_L(n) asm volatile("s_waitcnt lgkmcnt(" #n ")" ::: "memory")
; #define PG8_BAR __builtin_amdgcn_s_barrier()
; template <class Epi, bool ALIGN_EPI = true>
; __device__ __forceinline__ void gemm_phase(LAS unsigned char* lds, const Gemm g, const Sched& S, const Epi& E) {
;     ...
;         for (int t = t_lo; t < t_hi; t += 2) {
;             const bool last = (t == nt - 2);
;             const char* a1 = cA + (size_t)(t + 1) * kstep;
;             const char* a2 = last ? nA : cA + (size_t)(t + 2) * kstep; const char* b2 = last ? nB : cB + (size_t)(t + 2) * kstep;
;             const char* a3 = a2 + kstep; const char* b3 = b2 + kstep;
;             const int rflag = __builtin_amdgcn_readfirstlane(t | (int)(ui == 0));
;             PG8_LDB(B0, 0, 0); PG8_LDB(B1, 0, 1); PG8_SCHED; PG8_LDA(At, 0, 0); PG8_STAGE(PG8_SA(1, 1), a1 + hstepA, voffA);
;             if constexpr (Epi::NSTORES > 0) PG8_WAIT_RELAX(rflag, 8 + Epi::NSTORES); else PG8_WAIT_V(8);
;             PG8_WAIT_L(0); PG8_BAR; PG8_MMA(0, 0, At, B0); PG8_MMA(0, 1, At, B1); PG8_BAR; PG8_SCHED;
;             PG8_LDA(At, 0, 1); PG8_STAGE(PG8_SB(0, 0), b2, voffB); PG8_STAGE(PG8_SB(0, 1), b2 + hstepB, voffB); PG8_STAGE(PG8_SA(0, 0), a2, voffA);
.LBB0_1927:
	s_add_u32 s26, s33, s24
	s_addc_u32 s27, s34, s25
	s_add_u32 s42, s35, s40
	s_addc_u32 s43, s36, s41
	s_andn2_b64 vcc, exec, s[18:19]
	s_cbranch_vccnz .LBB0_1930
	s_and_b64 s[46:47], s[44:45], exec
	s_cselect_b32 s21, s27, s17
	s_cselect_b32 s23, s26, s16
	s_cselect_b32 s63, s43, s15
	s_cselect_b32 s64, s42, s14
	s_add_u32 s46, s16, 0x40080
	s_addc_u32 s47, s17, 0
	s_add_u32 s65, s14, 0x100
	s_addc_u32 s66, s15, 0
	s_mov_b32 s48, 0
	v_add_u32_e32 v236, 0x40000, v140
	v_add_u32_e32 v237, 0x40000, v136
	v_add_u32_e32 v238, 0x40000, v138
	v_add_u32_e32 v239, 0x40000, v134
.LBB0_1929:
	s_add_i32 s67, s48, 2
	s_add_u32 s49, s46, 0xfffc0080
	s_addc_u32 s50, s47, -1
	s_cmp_eq_u32 s59, s48
	s_cselect_b32 s51, s21, s50
	s_cselect_b32 s50, s23, s49
	s_cselect_b32 s49, s63, s66
	s_cselect_b32 s48, s64, s65
	s_add_u32 s100, s46, 0xfffc0000
	s_addc_u32 s101, s47, -1
	ds_read_b128 v[150:153], v147
	ds_read_b128 v[154:157], v147 offset:1024
	ds_read_b128 v[158:161], v147 offset:2048
	ds_read_b128 v[162:165], v147 offset:3072
	ds_read_b128 v[166:169], v147 offset:16384
	ds_read_b128 v[170:173], v147 offset:17408
	ds_read_b128 v[174:177], v147 offset:18432
	ds_read_b128 v[178:181], v147 offset:19456
	ds_read_b128 v[182:185], v148
	ds_read_b128 v[186:189], v148 offset:1024
	ds_read_b128 v[190:193], v148 offset:2048
	ds_read_b128 v[194:197], v148 offset:3072
	s_mov_b32 m0, s57
	ds_read_b128 v[206:209], v148 offset:4096
	global_load_lds_dwordx4 v142, s[100:101]
	s_mov_b32 m0, s58
	ds_read_b128 v[224:227], v148 offset:5120
	global_load_lds_dwordx4 v144, s[100:101]
	s_add_i32 m0, s52, 0xc000
	ds_read_b128 v[228:231], v148 offset:6144
	global_load_lds_dwordx4 v142, s[46:47]
	s_add_i32 m0, s52, 0xe000
	ds_read_b128 v[232:235], v148 offset:7168
	global_load_lds_dwordx4 v144, s[46:47]
	s_waitcnt vmcnt(8) lgkmcnt(0)
	s_barrier
	s_setprio 1
	v_mfma_f32_16x16x32_bf16 v[130:133], v[150:153], v[182:185], v[130:133]
	v_mfma_f32_16x16x32_bf16 v[126:129], v[158:161], v[182:185], v[126:129]
	v_mfma_f32_16x16x32_bf16 v[114:117], v[150:153], v[190:193], v[114:117]
	v_mfma_f32_16x16x32_bf16 v[110:113], v[158:161], v[190:193], v[110:113]
	v_mfma_f32_16x16x32_bf16 v[98:101], v[150:153], v[206:209], v[98:101]
	v_mfma_f32_16x16x32_bf16 v[94:97], v[158:161], v[206:209], v[94:97]
	v_mfma_f32_16x16x32_bf16 v[82:85], v[150:153], v[228:231], v[82:85]
	v_mfma_f32_16x16x32_bf16 v[78:81], v[158:161], v[228:231], v[78:81]
	v_mfma_f32_16x16x32_bf16 v[130:133], v[154:157], v[186:189], v[130:133]
	v_mfma_f32_16x16x32_bf16 v[126:129], v[162:165], v[186:189], v[126:129]
	v_mfma_f32_16x16x32_bf16 v[114:117], v[154:157], v[194:197], v[114:117]
	v_mfma_f32_16x16x32_bf16 v[110:113], v[162:165], v[194:197], v[110:113]
	v_mfma_f32_16x16x32_bf16 v[98:101], v[154:157], v[224:227], v[98:101]
	v_mfma_f32_16x16x32_bf16 v[94:97], v[162:165], v[224:227], v[94:97]
	v_mfma_f32_16x16x32_bf16 v[82:85], v[154:157], v[232:235], v[82:85]
	v_mfma_f32_16x16x32_bf16 v[78:81], v[162:165], v[232:235], v[78:81]
	s_setprio 0
	s_setprio 1
	v_mfma_f32_16x16x32_bf16 v[122:125], v[166:169], v[182:185], v[122:125]
	v_mfma_f32_16x16x32_bf16 v[118:121], v[174:177], v[182:185], v[118:121]
	v_mfma_f32_16x16x32_bf16 v[106:109], v[166:169], v[190:193], v[106:109]
	v_mfma_f32_16x16x32_bf16 v[102:105], v[174:177], v[190:193], v[102:105]
	v_mfma_f32_16x16x32_bf16 v[90:93], v[166:169], v[206:209], v[90:93]
	v_mfma_f32_16x16x32_bf16 v[86:89], v[174:177], v[206:209], v[86:89]
	v_mfma_f32_16x16x32_bf16 v[74:77], v[166:169], v[228:231], v[74:77]
	v_mfma_f32_16x16x32_bf16 v[70:73], v[174:177], v[228:231], v[70:73]
	v_mfma_f32_16x16x32_bf16 v[122:125], v[170:173], v[186:189], v[122:125]
	v_mfma_f32_16x16x32_bf16 v[118:121], v[178:181], v[186:189], v[118:121]
	v_mfma_f32_16x16x32_bf16 v[106:109], v[170:173], v[194:197], v[106:109]
	v_mfma_f32_16x16x32_bf16 v[102:105], v[178:181], v[194:197], v[102:105]
	v_mfma_f32_16x16x32_bf16 v[90:93], v[170:173], v[224:227], v[90:93]
	v_mfma_f32_16x16x32_bf16 v[86:89], v[178:181], v[224:227], v[86:89]
	v_mfma_f32_16x16x32_bf16 v[74:77], v[170:173], v[232:235], v[74:77]
	v_mfma_f32_16x16x32_bf16 v[70:73], v[178:181], v[232:235], v[70:73]
	s_setprio 0
	s_barrier
	ds_read_b128 v[182:185], v148 offset:16384
	ds_read_b128 v[186:189], v148 offset:17408
	ds_read_b128 v[190:193], v148 offset:18432
	ds_read_b128 v[194:197], v148 offset:19456
	s_add_i32 m0, s37, 0x10000
	ds_read_b128 v[206:209], v148 offset:20480
	global_load_lds_dwordx4 v138, s[48:49]
	s_add_i32 m0, s37, 0x12000
	ds_read_b128 v[224:227], v148 offset:21504
	global_load_lds_dwordx4 v134, s[48:49]
	s_add_i32 m0, s37, 0x14000
	ds_read_b128 v[228:231], v148 offset:22528
	global_load_lds_dwordx4 v238, s[48:49]
	s_add_i32 m0, s37, 0x16000
	ds_read_b128 v[232:235], v148 offset:23552
	global_load_lds_dwordx4 v239, s[48:49]
	s_waitcnt vmcnt(6) lgkmcnt(0)
	s_barrier
; #define PG8_STAGE(bufoff, gbase, voff) do { _Pragma("unroll") for (int _i = 0; _i < 2; ++_i) \
;         __builtin_amdgcn_global_load_lds((const unsigned*)((const char*)(gbase) + (voff)[_i]), (LAS unsigned*)(lds + (bufoff) + ldsw + _i * 8192), 16, 0, 0); } while (0)
; #define PG8_LDA(dst, b, h) do { _Pragma("unroll") for (int m = 0; m < 4; ++m) _Pragma("unroll") for (int k = 0; k < 2; ++k) dst[m][k] = *(const LAS bf16x8*)(lds + PG8_SA(b, h) + aoff + m * 2048 + k * 1024); } while (0)
; #define PG8_LDB(dst, b, h) do { _Pragma("unroll") for (int n = 0; n < 2; ++n) _Pragma("unroll") for (int k = 0; k < 2; ++k) dst[n][k] = *(const LAS bf16x8*)(lds + PG8_SB(b, h) + boff + n * 2048 + k * 1024); } while (0)
; #define PG8_MMA(ai, bj, At, Bt) do { __builtin_amdgcn_s_setprio(1); _Pragma("unroll") for (int m = 0; m < 4; ++m) _Pragma("unroll") for (int n = 0; n < 2; ++n) _Pragma("unroll") for (int k = 0; k < 2; ++k) \
;         acc[ai][bj][m][n] = __builtin_amdgcn_mfma_f32_16x16x32_bf16(Bt[n][k], At[m][k], acc[ai][bj][m][n], 0, 0, 0); __builtin_amdgcn_s_setprio(0); } while (0)
; #define PG8_WAIT_V(n) asm volatile("s_waitcnt vmcnt(" #n ")" ::: "memory")
; #define PG8_WAIT_L(n) asm volatile("s_waitcnt lgkmcnt(" #n ")" ::: "memory")
; #define PG8_BAR __builtin_amdgcn_s_barrier()
; #define PG8_WAIT_RELAX(flag, n) asm volatile("s_cmp_eq_u32 %0, 0\n\ts_cbranch_scc1 .Lrw%=\n\ts_waitcnt vmcnt(8)\n.Lrw%=:\n\ts_waitcnt vmcnt(%1)" :: "s"(flag), "n"(n) : "scc", "memory")
; #define PG8_SCHED __builtin_amdgcn_sched_barrier(0)
; template <class Epi, bool ALIGN_EPI = true>
; __device__ __forceinline__ void gemm_phase(LAS unsigned char* lds, const Gemm g, const Sched& S, const Epi& E) {
;     ...
;             if constexpr (Epi::NSTORES > 0) PG8_WAIT_RELAX(rflag, 8 + Epi::NSTORES); else PG8_WAIT_V(8);
;             PG8_WAIT_L(0); PG8_BAR; PG8_MMA(1, 0, At, B0); PG8_MMA(1, 1, At, B1); PG8_BAR; PG8_SCHED;
;             PG8_LDB(B0, 1, 0); PG8_LDB(B1, 1, 1); PG8_SCHED; PG8_LDA(At, 1, 0); PG8_STAGE(PG8_SA(0, 1), a2 + hstepA, voffA);
;             PG8_WAIT_V(8); PG8_WAIT_L(0); PG8_BAR; PG8_MMA(0, 0, At, B0); PG8_MMA(0, 1, At, B1); PG8_BAR; PG8_SCHED;
	s_setprio 1
	v_mfma_f32_16x16x32_bf16 v[66:69], v[150:153], v[182:185], v[66:69]
	v_mfma_f32_16x16x32_bf16 v[62:65], v[158:161], v[182:185], v[62:65]
	v_mfma_f32_16x16x32_bf16 v[50:53], v[150:153], v[190:193], v[50:53]
	v_mfma_f32_16x16x32_bf16 v[46:49], v[158:161], v[190:193], v[46:49]
	v_mfma_f32_16x16x32_bf16 v[34:37], v[150:153], v[206:209], v[34:37]
	v_mfma_f32_16x16x32_bf16 v[30:33], v[158:161], v[206:209], v[30:33]
	v_mfma_f32_16x16x32_bf16 v[18:21], v[150:153], v[228:231], v[18:21]
	v_mfma_f32_16x16x32_bf16 v[14:17], v[158:161], v[228:231], v[14:17]
	v_mfma_f32_16x16x32_bf16 v[66:69], v[154:157], v[186:189], v[66:69]
	v_mfma_f32_16x16x32_bf16 v[62:65], v[162:165], v[186:189], v[62:65]
	v_mfma_f32_16x16x32_bf16 v[50:53], v[154:157], v[194:197], v[50:53]
	v_mfma_f32_16x16x32_bf16 v[46:49], v[162:165], v[194:197], v[46:49]
	v_mfma_f32_16x16x32_bf16 v[34:37], v[154:157], v[224:227], v[34:37]
	v_mfma_f32_16x16x32_bf16 v[30:33], v[162:165], v[224:227], v[30:33]
	v_mfma_f32_16x16x32_bf16 v[18:21], v[154:157], v[232:235], v[18:21]
	v_mfma_f32_16x16x32_bf16 v[14:17], v[162:165], v[232:235], v[14:17]
	s_setprio 0
	s_setprio 1
	v_mfma_f32_16x16x32_bf16 v[58:61], v[166:169], v[182:185], v[58:61]
	v_mfma_f32_16x16x32_bf16 v[54:57], v[174:177], v[182:185], v[54:57]
	v_mfma_f32_16x16x32_bf16 v[42:45], v[166:169], v[190:193], v[42:45]
	v_mfma_f32_16x16x32_bf16 v[38:41], v[174:177], v[190:193], v[38:41]
	v_mfma_f32_16x16x32_bf16 v[26:29], v[166:169], v[206:209], v[26:29]
	v_mfma_f32_16x16x32_bf16 v[22:25], v[174:177], v[206:209], v[22:25]
	v_mfma_f32_16x16x32_bf16 v[10:13], v[166:169], v[228:231], v[10:13]
	v_mfma_f32_16x16x32_bf16 v[4:7], v[174:177], v[228:231], v[6:9]
	v_mfma_f32_16x16x32_bf16 v[58:61], v[170:173], v[186:189], v[58:61]
	v_mfma_f32_16x16x32_bf16 v[54:57], v[178:181], v[186:189], v[54:57]
	v_mfma_f32_16x16x32_bf16 v[42:45], v[170:173], v[194:197], v[42:45]
	v_mfma_f32_16x16x32_bf16 v[38:41], v[178:181], v[194:197], v[38:41]
	v_mfma_f32_16x16x32_bf16 v[26:29], v[170:173], v[224:227], v[26:29]
	v_mfma_f32_16x16x32_bf16 v[22:25], v[178:181], v[224:227], v[22:25]
	v_mfma_f32_16x16x32_bf16 v[10:13], v[170:173], v[232:235], v[10:13]
	v_mfma_f32_16x16x32_bf16 v[4:7], v[178:181], v[232:235], v[4:7]
	s_setprio 0
	s_barrier
	ds_read_b128 v[150:153], v147 offset:32768
	ds_read_b128 v[154:157], v147 offset:33792
	ds_read_b128 v[158:161], v147 offset:34816
	ds_read_b128 v[162:165], v147 offset:35840
	ds_read_b128 v[166:169], v147 offset:49152
	ds_read_b128 v[170:173], v147 offset:50176
	ds_read_b128 v[174:177], v147 offset:51200
	ds_read_b128 v[178:181], v147 offset:52224
	ds_read_b128 v[182:185], v148 offset:32768
	ds_read_b128 v[186:189], v148 offset:33792
	ds_read_b128 v[190:193], v148 offset:34816
	ds_read_b128 v[194:197], v148 offset:35840
	s_mov_b32 m0, s52
	ds_read_b128 v[206:209], v148 offset:36864
	global_load_lds_dwordx4 v140, s[50:51]
	s_mov_b32 m0, s53
	ds_read_b128 v[224:227], v148 offset:37888
	global_load_lds_dwordx4 v136, s[50:51]
	s_mov_b32 m0, s54
	ds_read_b128 v[228:231], v148 offset:38912
	global_load_lds_dwordx4 v236, s[50:51]
	s_mov_b32 m0, s55
	ds_read_b128 v[232:235], v148 offset:39936
	global_load_lds_dwordx4 v237, s[50:51]
	s_waitcnt vmcnt(8) lgkmcnt(0)
	s_barrier
	s_setprio 1
	v_mfma_f32_16x16x32_bf16 v[130:133], v[150:153], v[182:185], v[130:133]
	v_mfma_f32_16x16x32_bf16 v[126:129], v[158:161], v[182:185], v[126:129]
	v_mfma_f32_16x16x32_bf16 v[114:117], v[150:153], v[190:193], v[114:117]
	v_mfma_f32_16x16x32_bf16 v[110:113], v[158:161], v[190:193], v[110:113]
	v_mfma_f32_16x16x32_bf16 v[98:101], v[150:153], v[206:209], v[98:101]
	v_mfma_f32_16x16x32_bf16 v[94:97], v[158:161], v[206:209], v[94:97]
	v_mfma_f32_16x16x32_bf16 v[82:85], v[150:153], v[228:231], v[82:85]
	v_mfma_f32_16x16x32_bf16 v[78:81], v[158:161], v[228:231], v[78:81]
	v_mfma_f32_16x16x32_bf16 v[130:133], v[154:157], v[186:189], v[130:133]
	v_mfma_f32_16x16x32_bf16 v[126:129], v[162:165], v[186:189], v[126:129]
	v_mfma_f32_16x16x32_bf16 v[114:117], v[154:157], v[194:197], v[114:117]
	v_mfma_f32_16x16x32_bf16 v[110:113], v[162:165], v[194:197], v[110:113]
	v_mfma_f32_16x16x32_bf16 v[98:101], v[154:157], v[224:227], v[98:101]
	v_mfma_f32_16x16x32_bf16 v[94:97], v[162:165], v[224:227], v[94:97]
	v_mfma_f32_16x16x32_bf16 v[82:85], v[154:157], v[232:235], v[82:85]
	v_mfma_f32_16x16x32_bf16 v[78:81], v[162:165], v[232:235], v[78:81]
	s_setprio 0
	s_setprio 1
	v_mfma_f32_16x16x32_bf16 v[122:125], v[166:169], v[182:185], v[122:125]
	v_mfma_f32_16x16x32_bf16 v[118:121], v[174:177], v[182:185], v[118:121]
	v_mfma_f32_16x16x32_bf16 v[106:109], v[166:169], v[190:193], v[106:109]
	v_mfma_f32_16x16x32_bf16 v[102:105], v[174:177], v[190:193], v[102:105]
	v_mfma_f32_16x16x32_bf16 v[90:93], v[166:169], v[206:209], v[90:93]
	v_mfma_f32_16x16x32_bf16 v[86:89], v[174:177], v[206:209], v[86:89]
	v_mfma_f32_16x16x32_bf16 v[74:77], v[166:169], v[228:231], v[74:77]
	v_mfma_f32_16x16x32_bf16 v[70:73], v[174:177], v[228:231], v[70:73]
	v_mfma_f32_16x16x32_bf16 v[122:125], v[170:173], v[186:189], v[122:125]
	v_mfma_f32_16x16x32_bf16 v[118:121], v[178:181], v[186:189], v[118:121]
	v_mfma_f32_16x16x32_bf16 v[106:109], v[170:173], v[194:197], v[106:109]
	v_mfma_f32_16x16x32_bf16 v[102:105], v[178:181], v[194:197], v[102:105]
	v_mfma_f32_16x16x32_bf16 v[90:93], v[170:173], v[224:227], v[90:93]
	v_mfma_f32_16x16x32_bf16 v[86:89], v[178:181], v[224:227], v[86:89]
	v_mfma_f32_16x16x32_bf16 v[74:77], v[170:173], v[232:235], v[74:77]
	v_mfma_f32_16x16x32_bf16 v[70:73], v[178:181], v[232:235], v[70:73]
	s_setprio 0
	s_barrier
; #define PG8_STAGE(bufoff, gbase, voff) do { _Pragma("unroll") for (int _i = 0; _i < 2; ++_i) \
;         __builtin_amdgcn_global_load_lds((const unsigned*)((const char*)(gbase) + (voff)[_i]), (LAS unsigned*)(lds + (bufoff) + ldsw + _i * 8192), 16, 0, 0); } while (0)
; #define PG8_LDA(dst, b, h) do { _Pragma("unroll") for (int m = 0; m < 4; ++m) _Pragma("unroll") for (int k = 0; k < 2; ++k) dst[m][k] = *(const LAS bf16x8*)(lds + PG8_SA(b, h) + aoff + m * 2048 + k * 1024); } while (0)
; #define PG8_MMA(ai, bj, At, Bt) do { __builtin_amdgcn_s_setprio(1); _Pragma("unroll") for (int m = 0; m < 4; ++m) _Pragma("unroll") for (int n = 0; n < 2; ++n) _Pragma("unroll") for (int k = 0; k < 2; ++k) \
;         acc[ai][bj][m][n] = __builtin_amdgcn_mfma_f32_16x16x32_bf16(Bt[n][k], At[m][k], acc[ai][bj][m][n], 0, 0, 0); __builtin_amdgcn_s_setprio(0); } while (0)
; #define PG8_WAIT_V(n) asm volatile("s_waitcnt vmcnt(" #n ")" ::: "memory")
; #define PG8_WAIT_L(n) asm volatile("s_waitcnt lgkmcnt(" #n ")" ::: "memory")
; #define PG8_BAR __builtin_amdgcn_s_barrier()
; #define PG8_SCHED __builtin_amdgcn_sched_barrier(0)
; template <class Epi, bool ALIGN_EPI = true>
; __device__ __forceinline__ void gemm_phase(LAS unsigned char* lds, const Gemm g, const Sched& S, const Epi& E) {
;     ...
;             PG8_LDA(At, 1, 1); PG8_STAGE(PG8_SB(1, 0), b3, voffB); PG8_STAGE(PG8_SB(1, 1), b3 + hstepB, voffB); PG8_STAGE(PG8_SA(1, 0), a3, voffA);
;             PG8_WAIT_V(8); PG8_WAIT_L(0); PG8_BAR; PG8_MMA(1, 0, At, B0); PG8_MMA(1, 1, At, B1); PG8_BAR; PG8_SCHED;
;         }
	ds_read_b128 v[182:185], v148 offset:49152
	ds_read_b128 v[186:189], v148 offset:50176
	ds_read_b128 v[190:193], v148 offset:51200
	ds_read_b128 v[194:197], v148 offset:52224
	s_add_i32 m0, s37, 0x17f80
	ds_read_b128 v[206:209], v148 offset:53248
	global_load_lds_dwordx4 v138, s[48:49] offset:128
	s_add_i32 m0, s37, 0x19f80
	ds_read_b128 v[224:227], v148 offset:54272
	global_load_lds_dwordx4 v134, s[48:49] offset:128
	s_add_i32 m0, s37, 0x1bf80
	ds_read_b128 v[228:231], v148 offset:55296
	global_load_lds_dwordx4 v238, s[48:49] offset:128
	s_add_i32 m0, s37, 0x1df80
	ds_read_b128 v[232:235], v148 offset:56320
	global_load_lds_dwordx4 v239, s[48:49] offset:128
	s_waitcnt vmcnt(6) lgkmcnt(0)
	s_barrier
	s_setprio 1
	v_mfma_f32_16x16x32_bf16 v[66:69], v[150:153], v[182:185], v[66:69]
	v_mfma_f32_16x16x32_bf16 v[62:65], v[158:161], v[182:185], v[62:65]
	v_mfma_f32_16x16x32_bf16 v[50:53], v[150:153], v[190:193], v[50:53]
	v_mfma_f32_16x16x32_bf16 v[46:49], v[158:161], v[190:193], v[46:49]
	v_mfma_f32_16x16x32_bf16 v[34:37], v[150:153], v[206:209], v[34:37]
	v_mfma_f32_16x16x32_bf16 v[30:33], v[158:161], v[206:209], v[30:33]
	v_mfma_f32_16x16x32_bf16 v[18:21], v[150:153], v[228:231], v[18:21]
	v_mfma_f32_16x16x32_bf16 v[14:17], v[158:161], v[228:231], v[14:17]
	v_mfma_f32_16x16x32_bf16 v[66:69], v[154:157], v[186:189], v[66:69]
	v_mfma_f32_16x16x32_bf16 v[62:65], v[162:165], v[186:189], v[62:65]
	v_mfma_f32_16x16x32_bf16 v[50:53], v[154:157], v[194:197], v[50:53]
	v_mfma_f32_16x16x32_bf16 v[46:49], v[162:165], v[194:197], v[46:49]
	v_mfma_f32_16x16x32_bf16 v[34:37], v[154:157], v[224:227], v[34:37]
	v_mfma_f32_16x16x32_bf16 v[30:33], v[162:165], v[224:227], v[30:33]
	v_mfma_f32_16x16x32_bf16 v[18:21], v[154:157], v[232:235], v[18:21]
	v_mfma_f32_16x16x32_bf16 v[14:17], v[162:165], v[232:235], v[14:17]
	s_setprio 0
	s_setprio 1
	v_mfma_f32_16x16x32_bf16 v[58:61], v[166:169], v[182:185], v[58:61]
	v_mfma_f32_16x16x32_bf16 v[54:57], v[174:177], v[182:185], v[54:57]
	v_mfma_f32_16x16x32_bf16 v[42:45], v[166:169], v[190:193], v[42:45]
	v_mfma_f32_16x16x32_bf16 v[38:41], v[174:177], v[190:193], v[38:41]
	v_mfma_f32_16x16x32_bf16 v[26:29], v[166:169], v[206:209], v[26:29]
	v_mfma_f32_16x16x32_bf16 v[22:25], v[174:177], v[206:209], v[22:25]
	v_mfma_f32_16x16x32_bf16 v[8:11], v[166:169], v[228:231], v[10:13]
	v_mfma_f32_16x16x32_bf16 v[4:7], v[174:177], v[228:231], v[4:7]
	v_mfma_f32_16x16x32_bf16 v[58:61], v[170:173], v[186:189], v[58:61]
	v_mfma_f32_16x16x32_bf16 v[54:57], v[178:181], v[186:189], v[54:57]
	v_mfma_f32_16x16x32_bf16 v[42:45], v[170:173], v[194:197], v[42:45]
	v_mfma_f32_16x16x32_bf16 v[38:41], v[178:181], v[194:197], v[38:41]
	v_mfma_f32_16x16x32_bf16 v[26:29], v[170:173], v[224:227], v[26:29]
	v_mfma_f32_16x16x32_bf16 v[22:25], v[178:181], v[224:227], v[22:25]
	v_mfma_f32_16x16x32_bf16 v[10:13], v[170:173], v[232:235], v[8:11]
	v_mfma_f32_16x16x32_bf16 v[6:9], v[178:181], v[232:235], v[4:7]
	s_setprio 0
	s_barrier
	s_add_u32 s46, s46, 0x100
	s_addc_u32 s47, s47, 0
	s_add_u32 s65, s65, 0x100
	s_addc_u32 s66, s66, 0
	s_cmp_ge_i32 s67, s56
	s_mov_b32 s48, s67
	s_cbranch_scc0 .LBB0_1929
	s_add_i32 s50, s37, 0x1c000
	s_mov_b32 s68, 0x18000
	s_mov_b32 s69, 0x1c000
	s_add_i32 s70, s37, 0x14000

; template <class Epi, bool ALIGN_EPI = true>
; __device__ __forceinline__ void gemm_phase(LAS unsigned char* lds, const Gemm g, const Sched& S, const Epi& E) {
;     ...
;     for (int i = 0; i < 2; ++i) { int R, C; stage_rc(tid * 16 + i * 8192, R, C); const int Rb = (R & ~31) + perm32(R & 31);
;         voffA[i] = (unsigned)(R * g.lda + C) * 2u; voffB[i] = (unsigned)(Rb * g.ldb + C) * 2u; }
;     const size_t kstep = (size_t)(BK * 2);
;     const size_t hstepA = (size_t)HALF * g.lda * 2, hstepB = (size_t)HALF * g.ldb * 2;
;     ...
;         const bool has_next = S.next(ui + 1, nxt);
;         const char* nA = has_next ? (const char*)g.A + nxt.aoff : cA; const char* nB = has_next ? (const char*)g.Bt + nxt.boff : cB;
.LBB0_2021:
	s_add_u32 s40, s30, s22
	s_addc_u32 s41, s31, s23
	s_add_u32 s42, s33, s24
	s_addc_u32 s43, s34, s25
	s_andn2_b64 vcc, exec, s[14:15]
	s_cbranch_vccnz .LBB0_2025
	s_and_b64 s[26:27], s[44:45], exec
	s_cselect_b32 s19, s41, s7
	s_cselect_b32 s21, s40, s6
	s_cselect_b32 s65, s43, s1
	s_cselect_b32 s66, s42, s0
	s_cmp_eq_u32 s61, 0
	s_cselect_b64 s[26:27], -1, 0
	v_cndmask_b32_e64 v2, 0, 1, s[26:27]
	s_add_u32 s26, s6, 0x80080
	s_addc_u32 s27, s7, 0
	s_add_u32 s67, s0, 0x100
	s_mov_b32 s46, 0
	s_addc_u32 s68, s1, 0
	v_add_u32_e32 v236, 0x80000, v134
	v_add_u32_e32 v237, 0x80000, v138
	v_add_u32_e32 v238, 0x80000, v136
	v_add_u32_e32 v239, 0x80000, v140

; #define PG8_STAGE(bufoff, gbase, voff) do { _Pragma("unroll") for (int _i = 0; _i < 2; ++_i) \
;         __builtin_amdgcn_global_load_lds((const unsigned*)((const char*)(gbase) + (voff)[_i]), (LAS unsigned*)(lds + (bufoff) + ldsw + _i * 8192), 16, 0, 0); } while (0)
; #define PG8_LDA(dst, b, h) do { _Pragma("unroll") for (int m = 0; m < 4; ++m) _Pragma("unroll") for (int k = 0; k < 2; ++k) dst[m][k] = *(const LAS bf16x8*)(lds + PG8_SA(b, h) + aoff + m * 2048 + k * 1024); } while (0)
; #define PG8_LDB(dst, b, h) do { _Pragma("unroll") for (int n = 0; n < 2; ++n) _Pragma("unroll") for (int k = 0; k < 2; ++k) dst[n][k] = *(const LAS bf16x8*)(lds + PG8_SB(b, h) + boff + n * 2048 + k * 1024); } while (0)
; #define PG8_MMA(ai, bj, At, Bt) do { __builtin_amdgcn_s_setprio(1); _Pragma("unroll") for (int m = 0; m < 4; ++m) _Pragma("unroll") for (int n = 0; n < 2; ++n) _Pragma("unroll") for (int k = 0; k < 2; ++k) \
;         acc[ai][bj][m][n] = __builtin_amdgcn_mfma_f32_16x16x32_bf16(Bt[n][k], At[m][k], acc[ai][bj][m][n], 0, 0, 0); __builtin_amdgcn_s_setprio(0); } while (0)
; #define PG8_WAIT_V(n) asm volatile("s_waitcnt vmcnt(" #n ")" ::: "memory")
; #define PG8_WAIT_L(n) asm volatile("s_waitcnt lgkmcnt(" #n ")" ::: "memory")
; #define PG8_BAR __builtin_amdgcn_s_barrier()
; #define PG8_WAIT_RELAX(flag, n) asm volatile("s_cmp_eq_u32 %0, 0\n\ts_cbranch_scc1 .Lrw%=\n\ts_waitcnt vmcnt(8)\n.Lrw%=:\n\ts_waitcnt vmcnt(%1)" :: "s"(flag), "n"(n) : "scc", "memory")
; #define PG8_SCHED __builtin_amdgcn_sched_barrier(0)
; template <class Epi, bool ALIGN_EPI = true>
; __device__ __forceinline__ void gemm_phase(LAS unsigned char* lds, const Gemm g, const Sched& S, const Epi& E) {
;     ...
;             PG8_LDB(B0, 0, 0); PG8_LDB(B1, 0, 1); PG8_SCHED; PG8_LDA(At, 0, 0); PG8_STAGE(PG8_SA(1, 1), a1 + hstepA, voffA);
;             if constexpr (Epi::NSTORES > 0) PG8_WAIT_RELAX(rflag, 8 + Epi::NSTORES); else PG8_WAIT_V(8);
;             PG8_WAIT_L(0); PG8_BAR; PG8_MMA(0, 0, At, B0); PG8_MMA(0, 1, At, B1); PG8_BAR; PG8_SCHED;
;             PG8_LDA(At, 0, 1); PG8_STAGE(PG8_SB(0, 0), b2, voffB); PG8_STAGE(PG8_SB(0, 1), b2 + hstepB, voffB); PG8_STAGE(PG8_SA(0, 0), a2, voffA);
.Lrw18:
	s_waitcnt vmcnt(16) lgkmcnt(0)
	s_barrier
	s_setprio 1
	v_mfma_f32_16x16x32_bf16 v[130:133], v[146:149], v[182:185], v[130:133]
	v_mfma_f32_16x16x32_bf16 v[126:129], v[158:161], v[182:185], v[126:129]
	v_mfma_f32_16x16x32_bf16 v[122:125], v[146:149], v[190:193], v[122:125]
	v_mfma_f32_16x16x32_bf16 v[118:121], v[158:161], v[190:193], v[118:121]
	v_mfma_f32_16x16x32_bf16 v[114:117], v[146:149], v[206:209], v[114:117]
	v_mfma_f32_16x16x32_bf16 v[110:113], v[158:161], v[206:209], v[110:113]
	v_mfma_f32_16x16x32_bf16 v[106:109], v[146:149], v[228:231], v[106:109]
	v_mfma_f32_16x16x32_bf16 v[102:105], v[158:161], v[228:231], v[102:105]
	v_mfma_f32_16x16x32_bf16 v[130:133], v[154:157], v[186:189], v[130:133]
	v_mfma_f32_16x16x32_bf16 v[126:129], v[162:165], v[186:189], v[126:129]
	v_mfma_f32_16x16x32_bf16 v[122:125], v[154:157], v[194:197], v[122:125]
	v_mfma_f32_16x16x32_bf16 v[118:121], v[162:165], v[194:197], v[118:121]
	v_mfma_f32_16x16x32_bf16 v[114:117], v[154:157], v[224:227], v[114:117]
	v_mfma_f32_16x16x32_bf16 v[110:113], v[162:165], v[224:227], v[110:113]
	v_mfma_f32_16x16x32_bf16 v[106:109], v[154:157], v[232:235], v[106:109]
	v_mfma_f32_16x16x32_bf16 v[102:105], v[162:165], v[232:235], v[102:105]
	s_setprio 0
	s_setprio 1
	v_mfma_f32_16x16x32_bf16 v[98:101], v[166:169], v[182:185], v[98:101]
	v_mfma_f32_16x16x32_bf16 v[94:97], v[174:177], v[182:185], v[94:97]
	v_mfma_f32_16x16x32_bf16 v[90:93], v[166:169], v[190:193], v[90:93]
	v_mfma_f32_16x16x32_bf16 v[86:89], v[174:177], v[190:193], v[86:89]
	v_mfma_f32_16x16x32_bf16 v[82:85], v[166:169], v[206:209], v[82:85]
	v_mfma_f32_16x16x32_bf16 v[78:81], v[174:177], v[206:209], v[78:81]
	v_mfma_f32_16x16x32_bf16 v[74:77], v[166:169], v[228:231], v[74:77]
	v_mfma_f32_16x16x32_bf16 v[70:73], v[174:177], v[228:231], v[70:73]
	v_mfma_f32_16x16x32_bf16 v[98:101], v[170:173], v[186:189], v[98:101]
	v_mfma_f32_16x16x32_bf16 v[94:97], v[178:181], v[186:189], v[94:97]
	v_mfma_f32_16x16x32_bf16 v[90:93], v[170:173], v[194:197], v[90:93]
	v_mfma_f32_16x16x32_bf16 v[86:89], v[178:181], v[194:197], v[86:89]
	v_mfma_f32_16x16x32_bf16 v[82:85], v[170:173], v[224:227], v[82:85]
	v_mfma_f32_16x16x32_bf16 v[78:81], v[178:181], v[224:227], v[78:81]
	v_mfma_f32_16x16x32_bf16 v[74:77], v[170:173], v[232:235], v[74:77]
	v_mfma_f32_16x16x32_bf16 v[70:73], v[178:181], v[232:235], v[70:73]
	s_setprio 0
	s_barrier
	ds_read_b128 v[182:185], v152 offset:16384
	ds_read_b128 v[186:189], v152 offset:17408
	ds_read_b128 v[190:193], v152 offset:18432
	ds_read_b128 v[194:197], v152 offset:19456
	s_add_i32 m0, s35, 0x10000
	ds_read_b128 v[206:209], v152 offset:20480
	global_load_lds_dwordx4 v136, s[46:47]
	s_add_i32 m0, s35, 0x12000
	ds_read_b128 v[224:227], v152 offset:21504
	global_load_lds_dwordx4 v140, s[46:47]
	s_add_i32 m0, s35, 0x14000
	ds_read_b128 v[228:231], v152 offset:22528
	global_load_lds_dwordx4 v238, s[46:47]
	s_add_i32 m0, s35, 0x16000
	ds_read_b128 v[232:235], v152 offset:23552
	global_load_lds_dwordx4 v239, s[46:47]
	s_cmp_eq_u32 s73, 0
	s_cbranch_scc1 .Lrw19
	s_waitcnt vmcnt(6)
; #define PG8_STAGE(bufoff, gbase, voff) do { _Pragma("unroll") for (int _i = 0; _i < 2; ++_i) \
;         __builtin_amdgcn_global_load_lds((const unsigned*)((const char*)(gbase) + (voff)[_i]), (LAS unsigned*)(lds + (bufoff) + ldsw + _i * 8192), 16, 0, 0); } while (0)
; #define PG8_LDA(dst, b, h) do { _Pragma("unroll") for (int m = 0; m < 4; ++m) _Pragma("unroll") for (int k = 0; k < 2; ++k) dst[m][k] = *(const LAS bf16x8*)(lds + PG8_SA(b, h) + aoff + m * 2048 + k * 1024); } while (0)
; #define PG8_LDB(dst, b, h) do { _Pragma("unroll") for (int n = 0; n < 2; ++n) _Pragma("unroll") for (int k = 0; k < 2; ++k) dst[n][k] = *(const LAS bf16x8*)(lds + PG8_SB(b, h) + boff + n * 2048 + k * 1024); } while (0)
; #define PG8_MMA(ai, bj, At, Bt) do { __builtin_amdgcn_s_setprio(1); _Pragma("unroll") for (int m = 0; m < 4; ++m) _Pragma("unroll") for (int n = 0; n < 2; ++n) _Pragma("unroll") for (int k = 0; k < 2; ++k) \
;         acc[ai][bj][m][n] = __builtin_amdgcn_mfma_f32_16x16x32_bf16(Bt[n][k], At[m][k], acc[ai][bj][m][n], 0, 0, 0); __builtin_amdgcn_s_setprio(0); } while (0)
; #define PG8_WAIT_V(n) asm volatile("s_waitcnt vmcnt(" #n ")" ::: "memory")
; #define PG8_WAIT_L(n) asm volatile("s_waitcnt lgkmcnt(" #n ")" ::: "memory")
; #define PG8_BAR __builtin_amdgcn_s_barrier()
; #define PG8_WAIT_RELAX(flag, n) asm volatile("s_cmp_eq_u32 %0, 0\n\ts_cbranch_scc1 .Lrw%=\n\ts_waitcnt vmcnt(8)\n.Lrw%=:\n\ts_waitcnt vmcnt(%1)" :: "s"(flag), "n"(n) : "scc", "memory")
; template <class Epi, bool ALIGN_EPI = true>
; __device__ __forceinline__ void gemm_phase(LAS unsigned char* lds, const Gemm g, const Sched& S, const Epi& E) {
;     ...
;             if constexpr (Epi::NSTORES > 0) PG8_WAIT_RELAX(rflag, 8 + Epi::NSTORES); else PG8_WAIT_V(8);
;             PG8_WAIT_L(0); PG8_BAR; PG8_MMA(1, 0, At, B0); PG8_MMA(1, 1, At, B1); PG8_BAR; PG8_SCHED;
;             PG8_LDB(B0, 1, 0); PG8_LDB(B1, 1, 1); PG8_SCHED; PG8_LDA(At, 1, 0); PG8_STAGE(PG8_SA(0, 1), a2 + hstepA, voffA);
;             PG8_WAIT_V(8); PG8_WAIT_L(0); PG8_BAR; PG8_MMA(0, 0, At, B0); PG8_MMA(0, 1, At, B1); PG8_BAR; PG8_SCHED;
;             PG8_LDA(At, 1, 1); PG8_STAGE(PG8_SB(1, 0), b3, voffB); PG8_STAGE(PG8_SB(1, 1), b3 + hstepB, voffB); PG8_STAGE(PG8_SA(1, 0), a3, voffA);
;             PG8_WAIT_V(8); PG8_WAIT_L(0); PG8_BAR; PG8_MMA(1, 0, At, B0); PG8_MMA(1, 1, At, B1); PG8_BAR; PG8_SCHED;
;         }
.Lrw19:
	s_waitcnt vmcnt(16) lgkmcnt(0)
	s_barrier
	s_setprio 1
	v_mfma_f32_16x16x32_bf16 v[66:69], v[146:149], v[182:185], v[66:69]
	v_mfma_f32_16x16x32_bf16 v[62:65], v[158:161], v[182:185], v[62:65]
	v_mfma_f32_16x16x32_bf16 v[58:61], v[146:149], v[190:193], v[58:61]
	v_mfma_f32_16x16x32_bf16 v[54:57], v[158:161], v[190:193], v[54:57]
	v_mfma_f32_16x16x32_bf16 v[50:53], v[146:149], v[206:209], v[50:53]
	v_mfma_f32_16x16x32_bf16 v[46:49], v[158:161], v[206:209], v[46:49]
	v_mfma_f32_16x16x32_bf16 v[42:45], v[146:149], v[228:231], v[42:45]
	v_mfma_f32_16x16x32_bf16 v[38:41], v[158:161], v[228:231], v[38:41]
	v_mfma_f32_16x16x32_bf16 v[66:69], v[154:157], v[186:189], v[66:69]
	v_mfma_f32_16x16x32_bf16 v[62:65], v[162:165], v[186:189], v[62:65]
	v_mfma_f32_16x16x32_bf16 v[58:61], v[154:157], v[194:197], v[58:61]
	v_mfma_f32_16x16x32_bf16 v[54:57], v[162:165], v[194:197], v[54:57]
	v_mfma_f32_16x16x32_bf16 v[50:53], v[154:157], v[224:227], v[50:53]
	v_mfma_f32_16x16x32_bf16 v[46:49], v[162:165], v[224:227], v[46:49]
	v_mfma_f32_16x16x32_bf16 v[42:45], v[154:157], v[232:235], v[42:45]
	v_mfma_f32_16x16x32_bf16 v[38:41], v[162:165], v[232:235], v[38:41]
	s_setprio 0
	s_setprio 1
	v_mfma_f32_16x16x32_bf16 v[34:37], v[166:169], v[182:185], v[34:37]
	v_mfma_f32_16x16x32_bf16 v[30:33], v[174:177], v[182:185], v[30:33]
	v_mfma_f32_16x16x32_bf16 v[26:29], v[166:169], v[190:193], v[26:29]
	v_mfma_f32_16x16x32_bf16 v[22:25], v[174:177], v[190:193], v[22:25]
	v_mfma_f32_16x16x32_bf16 v[18:21], v[166:169], v[206:209], v[18:21]
	v_mfma_f32_16x16x32_bf16 v[14:17], v[174:177], v[206:209], v[14:17]
	v_mfma_f32_16x16x32_bf16 v[10:13], v[166:169], v[228:231], v[10:13]
	v_mfma_f32_16x16x32_bf16 v[4:7], v[174:177], v[228:231], v[6:9]
	v_mfma_f32_16x16x32_bf16 v[34:37], v[170:173], v[186:189], v[34:37]
	v_mfma_f32_16x16x32_bf16 v[30:33], v[178:181], v[186:189], v[30:33]
	v_mfma_f32_16x16x32_bf16 v[26:29], v[170:173], v[194:197], v[26:29]
	v_mfma_f32_16x16x32_bf16 v[22:25], v[178:181], v[194:197], v[22:25]
	v_mfma_f32_16x16x32_bf16 v[18:21], v[170:173], v[224:227], v[18:21]
	v_mfma_f32_16x16x32_bf16 v[14:17], v[178:181], v[224:227], v[14:17]
	v_mfma_f32_16x16x32_bf16 v[10:13], v[170:173], v[232:235], v[10:13]
	v_mfma_f32_16x16x32_bf16 v[4:7], v[178:181], v[232:235], v[4:7]
	s_setprio 0
	s_barrier
	ds_read_b128 v[146:149], v151 offset:32768
	ds_read_b128 v[154:157], v151 offset:33792
	ds_read_b128 v[158:161], v151 offset:34816
	ds_read_b128 v[162:165], v151 offset:35840
	ds_read_b128 v[166:169], v151 offset:49152
	ds_read_b128 v[170:173], v151 offset:50176
	ds_read_b128 v[174:177], v151 offset:51200
	ds_read_b128 v[178:181], v151 offset:52224
	ds_read_b128 v[182:185], v152 offset:32768
	ds_read_b128 v[186:189], v152 offset:33792
	ds_read_b128 v[190:193], v152 offset:34816
	ds_read_b128 v[194:197], v152 offset:35840
	s_mov_b32 m0, s36
	ds_read_b128 v[206:209], v152 offset:36864
	global_load_lds_dwordx4 v134, s[48:49]
	s_mov_b32 m0, s37
	ds_read_b128 v[224:227], v152 offset:37888
	global_load_lds_dwordx4 v138, s[48:49]
	s_mov_b32 m0, s50
	ds_read_b128 v[228:231], v152 offset:38912
	global_load_lds_dwordx4 v236, s[48:49]
	s_mov_b32 m0, s51
	ds_read_b128 v[232:235], v152 offset:39936
	global_load_lds_dwordx4 v237, s[48:49]
	s_waitcnt vmcnt(8) lgkmcnt(0)
	s_barrier
	s_setprio 1
	v_mfma_f32_16x16x32_bf16 v[130:133], v[146:149], v[182:185], v[130:133]
	v_mfma_f32_16x16x32_bf16 v[126:129], v[158:161], v[182:185], v[126:129]
	v_mfma_f32_16x16x32_bf16 v[122:125], v[146:149], v[190:193], v[122:125]
	v_mfma_f32_16x16x32_bf16 v[118:121], v[158:161], v[190:193], v[118:121]
	v_mfma_f32_16x16x32_bf16 v[114:117], v[146:149], v[206:209], v[114:117]
	v_mfma_f32_16x16x32_bf16 v[110:113], v[158:161], v[206:209], v[110:113]
	v_mfma_f32_16x16x32_bf16 v[106:109], v[146:149], v[228:231], v[106:109]
	v_mfma_f32_16x16x32_bf16 v[102:105], v[158:161], v[228:231], v[102:105]
	v_mfma_f32_16x16x32_bf16 v[130:133], v[154:157], v[186:189], v[130:133]
	v_mfma_f32_16x16x32_bf16 v[126:129], v[162:165], v[186:189], v[126:129]
	v_mfma_f32_16x16x32_bf16 v[122:125], v[154:157], v[194:197], v[122:125]
	v_mfma_f32_16x16x32_bf16 v[118:121], v[162:165], v[194:197], v[118:121]
	v_mfma_f32_16x16x32_bf16 v[114:117], v[154:157], v[224:227], v[114:117]
	v_mfma_f32_16x16x32_bf16 v[110:113], v[162:165], v[224:227], v[110:113]
	v_mfma_f32_16x16x32_bf16 v[106:109], v[154:157], v[232:235], v[106:109]
	v_mfma_f32_16x16x32_bf16 v[102:105], v[162:165], v[232:235], v[102:105]
	s_setprio 0
	s_setprio 1
	v_mfma_f32_16x16x32_bf16 v[98:101], v[166:169], v[182:185], v[98:101]
	v_mfma_f32_16x16x32_bf16 v[94:97], v[174:177], v[182:185], v[94:97]
	v_mfma_f32_16x16x32_bf16 v[90:93], v[166:169], v[190:193], v[90:93]
	v_mfma_f32_16x16x32_bf16 v[86:89], v[174:177], v[190:193], v[86:89]
	v_mfma_f32_16x16x32_bf16 v[82:85], v[166:169], v[206:209], v[82:85]
	v_mfma_f32_16x16x32_bf16 v[78:81], v[174:177], v[206:209], v[78:81]
	v_mfma_f32_16x16x32_bf16 v[74:77], v[166:169], v[228:231], v[74:77]
	v_mfma_f32_16x16x32_bf16 v[70:73], v[174:177], v[228:231], v[70:73]
	v_mfma_f32_16x16x32_bf16 v[98:101], v[170:173], v[186:189], v[98:101]
	v_mfma_f32_16x16x32_bf16 v[94:97], v[178:181], v[186:189], v[94:97]
	v_mfma_f32_16x16x32_bf16 v[90:93], v[170:173], v[194:197], v[90:93]
	v_mfma_f32_16x16x32_bf16 v[86:89], v[178:181], v[194:197], v[86:89]
	v_mfma_f32_16x16x32_bf16 v[82:85], v[170:173], v[224:227], v[82:85]
	v_mfma_f32_16x16x32_bf16 v[78:81], v[178:181], v[224:227], v[78:81]
	v_mfma_f32_16x16x32_bf16 v[74:77], v[170:173], v[232:235], v[74:77]
	v_mfma_f32_16x16x32_bf16 v[70:73], v[178:181], v[232:235], v[70:73]
	s_setprio 0
	s_barrier
	ds_read_b128 v[182:185], v152 offset:49152
	ds_read_b128 v[186:189], v152 offset:50176
	ds_read_b128 v[190:193], v152 offset:51200
	ds_read_b128 v[194:197], v152 offset:52224
	s_add_i32 m0, s35, 0x17f80
	ds_read_b128 v[206:209], v152 offset:53248
	global_load_lds_dwordx4 v136, s[46:47] offset:128
	s_add_i32 m0, s35, 0x19f80
	ds_read_b128 v[224:227], v152 offset:54272
	global_load_lds_dwordx4 v140, s[46:47] offset:128
	s_add_i32 m0, s35, 0x1bf80
	ds_read_b128 v[228:231], v152 offset:55296
	global_load_lds_dwordx4 v238, s[46:47] offset:128
	s_add_i32 m0, s35, 0x1df80
	ds_read_b128 v[232:235], v152 offset:56320
	global_load_lds_dwordx4 v239, s[46:47] offset:128
	s_cmp_ge_i32 s69, s54
	s_cbranch_scc0 .Lx4last_13
	s_add_i32 m0, s56, 0xffffff80
	s_nop 0
	global_load_lds_dwordx4 v134, s[48:49] offset:128
	s_add_i32 m0, s57, 0xffffff80
	s_nop 0
	global_load_lds_dwordx4 v138, s[48:49] offset:128

; #define PG8_STAGE(bufoff, gbase, voff) do { _Pragma("unroll") for (int _i = 0; _i < 2; ++_i) \
;         __builtin_amdgcn_global_load_lds((const unsigned*)((const char*)(gbase) + (voff)[_i]), (LAS unsigned*)(lds + (bufoff) + ldsw + _i * 8192), 16, 0, 0); } while (0)
; #define PG8_LDA(dst, b, h) do { _Pragma("unroll") for (int m = 0; m < 4; ++m) _Pragma("unroll") for (int k = 0; k < 2; ++k) dst[m][k] = *(const LAS bf16x8*)(lds + PG8_SA(b, h) + aoff + m * 2048 + k * 1024); } while (0)
; #define PG8_WAIT_V(n) asm volatile("s_waitcnt vmcnt(" #n ")" ::: "memory")
; template <class Epi, bool ALIGN_EPI = true>
; __device__ __forceinline__ void gemm_phase(LAS unsigned char* lds, const Gemm g, const Sched& S, const Epi& E) {
;     ...
;         const bool has_next = S.next(ui + 1, nxt);
;         const char* nA = has_next ? (const char*)g.A + nxt.aoff : cA; const char* nB = has_next ? (const char*)g.Bt + nxt.boff : cB;
;         for (int hh = 0; hh < (Epi::HAS_MID ? 2 : 1); ++hh) {
;         if constexpr (Epi::HAS_MID) { if (hh == 1) { int le = lane; asm volatile("" : "+v"(le)); E.mid(acc, cur, wr, wc, le & 15, le >> 4); } }
;         const int t_lo = Epi::HAS_MID ? hh * (nt >> 1) : 0, t_hi = Epi::HAS_MID ? (hh + 1) * (nt >> 1) : nt;
;         for (int t = t_lo; t < t_hi; t += 2) {
;             const bool last = (t == nt - 2);
;             const char* a1 = cA + (size_t)(t + 1) * kstep;
;             const char* a2 = last ? nA : cA + (size_t)(t + 2) * kstep; const char* b2 = last ? nB : cB + (size_t)(t + 2) * kstep;
;             const char* a3 = a2 + kstep; const char* b3 = b2 + kstep;
;             const int rflag = __builtin_amdgcn_readfirstlane(t | (int)(ui == 0));
;             PG8_LDB(B0, 0, 0); PG8_LDB(B1, 0, 1); PG8_SCHED; PG8_LDA(At, 0, 0); PG8_STAGE(PG8_SA(1, 1), a1 + hstepA, voffA);
;             if constexpr (Epi::NSTORES > 0) PG8_WAIT_RELAX(rflag, 8 + Epi::NSTORES); else PG8_WAIT_V(8);
;             PG8_WAIT_L(0); PG8_BAR; PG8_MMA(0, 0, At, B0); PG8_MMA(0, 1, At, B1); PG8_BAR; PG8_SCHED;
;             PG8_LDA(At, 0, 1); PG8_STAGE(PG8_SB(0, 0), b2, voffB); PG8_STAGE(PG8_SB(0, 1), b2 + hstepB, voffB); PG8_STAGE(PG8_SA(0, 0), a2, voffA);
;             if constexpr (Epi::NSTORES > 0) PG8_WAIT_RELAX(rflag, 8 + Epi::NSTORES); else PG8_WAIT_V(8);
;             PG8_WAIT_L(0); PG8_BAR; PG8_MMA(1, 0, At, B0); PG8_MMA(1, 1, At, B1); PG8_BAR; PG8_SCHED;
.LBB0_2285:
	s_add_u32 s24, s33, s20
	s_addc_u32 s25, s34, s21
	s_add_u32 s26, s35, s22
	s_addc_u32 s27, s36, s23
	s_andn2_b64 vcc, exec, s[18:19]
	s_cbranch_vccnz .LBB0_2288
	s_and_b64 s[42:43], s[40:41], exec
	s_cselect_b32 s63, s25, s17
	s_cselect_b32 s64, s24, s16
	s_cselect_b32 s65, s27, s15
	s_cselect_b32 s66, s26, s14
	s_add_u32 s67, s14, 0x100
	s_addc_u32 s68, s15, 0
	s_mov_b32 s44, 0
	s_mov_b64 s[48:49], s[16:17]
	v_add_u32_e32 v236, 0x160000, v140
	v_add_u32_e32 v237, 0x160000, v136
	v_add_u32_e32 v238, 0x160000, v138
	v_add_u32_e32 v239, 0x160000, v134
.LBB0_2287:
	s_add_i32 s69, s44, 2
	s_add_u32 s42, s48, 0x100
	s_addc_u32 s43, s49, 0
	s_cmp_eq_u32 s57, s44
	s_cselect_b32 s47, s63, s43
	s_cselect_b32 s46, s64, s42
	s_cselect_b32 s45, s65, s68
	s_cselect_b32 s44, s66, s67
	s_add_u32 s100, s48, 0xffea0000
	s_addc_u32 s101, s49, -1
	ds_read_b128 v[150:153], v147
	ds_read_b128 v[154:157], v147 offset:1024
	ds_read_b128 v[158:161], v147 offset:2048
	ds_read_b128 v[162:165], v147 offset:3072
	ds_read_b128 v[166:169], v147 offset:16384
	ds_read_b128 v[170:173], v147 offset:17408
	ds_read_b128 v[174:177], v147 offset:18432
	ds_read_b128 v[178:181], v147 offset:19456
	ds_read_b128 v[182:185], v148
	ds_read_b128 v[186:189], v148 offset:1024
	ds_read_b128 v[190:193], v148 offset:2048
	ds_read_b128 v[194:197], v148 offset:3072
	s_mov_b32 m0, s55
	ds_read_b128 v[206:209], v148 offset:4096
	global_load_lds_dwordx4 v142, s[100:101]
	s_mov_b32 m0, s56
	ds_read_b128 v[224:227], v148 offset:5120
	global_load_lds_dwordx4 v144, s[100:101]
	s_add_i32 m0, s50, 0xc000
	ds_read_b128 v[228:231], v148 offset:6144
	global_load_lds_dwordx4 v142, s[48:49]
	s_add_i32 m0, s50, 0xe000
	ds_read_b128 v[232:235], v148 offset:7168
	global_load_lds_dwordx4 v144, s[48:49]
	s_waitcnt vmcnt(8) lgkmcnt(0)
	s_barrier
	s_setprio 1
	v_mfma_f32_16x16x32_bf16 v[130:133], v[150:153], v[182:185], v[130:133]
	v_mfma_f32_16x16x32_bf16 v[126:129], v[158:161], v[182:185], v[126:129]
	v_mfma_f32_16x16x32_bf16 v[114:117], v[150:153], v[190:193], v[114:117]
	v_mfma_f32_16x16x32_bf16 v[110:113], v[158:161], v[190:193], v[110:113]
	v_mfma_f32_16x16x32_bf16 v[98:101], v[150:153], v[206:209], v[98:101]
	v_mfma_f32_16x16x32_bf16 v[94:97], v[158:161], v[206:209], v[94:97]
	v_mfma_f32_16x16x32_bf16 v[82:85], v[150:153], v[228:231], v[82:85]
	v_mfma_f32_16x16x32_bf16 v[78:81], v[158:161], v[228:231], v[78:81]
	v_mfma_f32_16x16x32_bf16 v[130:133], v[154:157], v[186:189], v[130:133]
	v_mfma_f32_16x16x32_bf16 v[126:129], v[162:165], v[186:189], v[126:129]
	v_mfma_f32_16x16x32_bf16 v[114:117], v[154:157], v[194:197], v[114:117]
	v_mfma_f32_16x16x32_bf16 v[110:113], v[162:165], v[194:197], v[110:113]
	v_mfma_f32_16x16x32_bf16 v[98:101], v[154:157], v[224:227], v[98:101]
	v_mfma_f32_16x16x32_bf16 v[94:97], v[162:165], v[224:227], v[94:97]
	v_mfma_f32_16x16x32_bf16 v[82:85], v[154:157], v[232:235], v[82:85]
	v_mfma_f32_16x16x32_bf16 v[78:81], v[162:165], v[232:235], v[78:81]
	s_setprio 0
	s_setprio 1
	v_mfma_f32_16x16x32_bf16 v[122:125], v[166:169], v[182:185], v[122:125]
	v_mfma_f32_16x16x32_bf16 v[118:121], v[174:177], v[182:185], v[118:121]
	v_mfma_f32_16x16x32_bf16 v[106:109], v[166:169], v[190:193], v[106:109]
	v_mfma_f32_16x16x32_bf16 v[102:105], v[174:177], v[190:193], v[102:105]
	v_mfma_f32_16x16x32_bf16 v[90:93], v[166:169], v[206:209], v[90:93]
	v_mfma_f32_16x16x32_bf16 v[86:89], v[174:177], v[206:209], v[86:89]
	v_mfma_f32_16x16x32_bf16 v[74:77], v[166:169], v[228:231], v[74:77]
	v_mfma_f32_16x16x32_bf16 v[70:73], v[174:177], v[228:231], v[70:73]
	v_mfma_f32_16x16x32_bf16 v[122:125], v[170:173], v[186:189], v[122:125]
	v_mfma_f32_16x16x32_bf16 v[118:121], v[178:181], v[186:189], v[118:121]
	v_mfma_f32_16x16x32_bf16 v[106:109], v[170:173], v[194:197], v[106:109]
	v_mfma_f32_16x16x32_bf16 v[102:105], v[178:181], v[194:197], v[102:105]
	v_mfma_f32_16x16x32_bf16 v[90:93], v[170:173], v[224:227], v[90:93]
	v_mfma_f32_16x16x32_bf16 v[86:89], v[178:181], v[224:227], v[86:89]
	v_mfma_f32_16x16x32_bf16 v[74:77], v[170:173], v[232:235], v[74:77]
	v_mfma_f32_16x16x32_bf16 v[70:73], v[178:181], v[232:235], v[70:73]
	s_setprio 0
	s_barrier
	ds_read_b128 v[182:185], v148 offset:16384
	ds_read_b128 v[186:189], v148 offset:17408
	ds_read_b128 v[190:193], v148 offset:18432
	ds_read_b128 v[194:197], v148 offset:19456
	s_add_i32 m0, s37, 0x10000
	ds_read_b128 v[206:209], v148 offset:20480
	global_load_lds_dwordx4 v138, s[44:45]
	s_add_i32 m0, s37, 0x12000
	ds_read_b128 v[224:227], v148 offset:21504
	global_load_lds_dwordx4 v134, s[44:45]
	s_add_i32 m0, s37, 0x14000
	ds_read_b128 v[228:231], v148 offset:22528
	global_load_lds_dwordx4 v238, s[44:45]
	s_add_i32 m0, s37, 0x16000
	ds_read_b128 v[232:235], v148 offset:23552
	global_load_lds_dwordx4 v239, s[44:45]
	s_waitcnt vmcnt(6) lgkmcnt(0)
	s_barrier
; #define PG8_STAGE(bufoff, gbase, voff) do { _Pragma("unroll") for (int _i = 0; _i < 2; ++_i) \
;         __builtin_amdgcn_global_load_lds((const unsigned*)((const char*)(gbase) + (voff)[_i]), (LAS unsigned*)(lds + (bufoff) + ldsw + _i * 8192), 16, 0, 0); } while (0)
; #define PG8_LDA(dst, b, h) do { _Pragma("unroll") for (int m = 0; m < 4; ++m) _Pragma("unroll") for (int k = 0; k < 2; ++k) dst[m][k] = *(const LAS bf16x8*)(lds + PG8_SA(b, h) + aoff + m * 2048 + k * 1024); } while (0)
; #define PG8_LDB(dst, b, h) do { _Pragma("unroll") for (int n = 0; n < 2; ++n) _Pragma("unroll") for (int k = 0; k < 2; ++k) dst[n][k] = *(const LAS bf16x8*)(lds + PG8_SB(b, h) + boff + n * 2048 + k * 1024); } while (0)
; #define PG8_MMA(ai, bj, At, Bt) do { __builtin_amdgcn_s_setprio(1); _Pragma("unroll") for (int m = 0; m < 4; ++m) _Pragma("unroll") for (int n = 0; n < 2; ++n) _Pragma("unroll") for (int k = 0; k < 2; ++k) \
;         acc[ai][bj][m][n] = __builtin_amdgcn_mfma_f32_16x16x32_bf16(Bt[n][k], At[m][k], acc[ai][bj][m][n], 0, 0, 0); __builtin_amdgcn_s_setprio(0); } while (0)
; #define PG8_WAIT_V(n) asm volatile("s_waitcnt vmcnt(" #n ")" ::: "memory")
; #define PG8_WAIT_L(n) asm volatile("s_waitcnt lgkmcnt(" #n ")" ::: "memory")
; #define PG8_BAR __builtin_amdgcn_s_barrier()
; #define PG8_SCHED __builtin_amdgcn_sched_barrier(0)
; template <class Epi, bool ALIGN_EPI = true>
; __device__ __forceinline__ void gemm_phase(LAS unsigned char* lds, const Gemm g, const Sched& S, const Epi& E) {
;     ...
;             PG8_WAIT_L(0); PG8_BAR; PG8_MMA(1, 0, At, B0); PG8_MMA(1, 1, At, B1); PG8_BAR; PG8_SCHED;
;             PG8_LDB(B0, 1, 0); PG8_LDB(B1, 1, 1); PG8_SCHED; PG8_LDA(At, 1, 0); PG8_STAGE(PG8_SA(0, 1), a2 + hstepA, voffA);
;             PG8_WAIT_V(8); PG8_WAIT_L(0); PG8_BAR; PG8_MMA(0, 0, At, B0); PG8_MMA(0, 1, At, B1); PG8_BAR; PG8_SCHED;
;             PG8_LDA(At, 1, 1); PG8_STAGE(PG8_SB(1, 0), b3, voffB); PG8_STAGE(PG8_SB(1, 1), b3 + hstepB, voffB); PG8_STAGE(PG8_SA(1, 0), a3, voffA);
	s_setprio 1
	v_mfma_f32_16x16x32_bf16 v[66:69], v[150:153], v[182:185], v[66:69]
	v_mfma_f32_16x16x32_bf16 v[62:65], v[158:161], v[182:185], v[62:65]
	v_mfma_f32_16x16x32_bf16 v[50:53], v[150:153], v[190:193], v[50:53]
	v_mfma_f32_16x16x32_bf16 v[46:49], v[158:161], v[190:193], v[46:49]
	v_mfma_f32_16x16x32_bf16 v[34:37], v[150:153], v[206:209], v[34:37]
	v_mfma_f32_16x16x32_bf16 v[30:33], v[158:161], v[206:209], v[30:33]
	v_mfma_f32_16x16x32_bf16 v[18:21], v[150:153], v[228:231], v[18:21]
	v_mfma_f32_16x16x32_bf16 v[14:17], v[158:161], v[228:231], v[14:17]
	v_mfma_f32_16x16x32_bf16 v[66:69], v[154:157], v[186:189], v[66:69]
	v_mfma_f32_16x16x32_bf16 v[62:65], v[162:165], v[186:189], v[62:65]
	v_mfma_f32_16x16x32_bf16 v[50:53], v[154:157], v[194:197], v[50:53]
	v_mfma_f32_16x16x32_bf16 v[46:49], v[162:165], v[194:197], v[46:49]
	v_mfma_f32_16x16x32_bf16 v[34:37], v[154:157], v[224:227], v[34:37]
	v_mfma_f32_16x16x32_bf16 v[30:33], v[162:165], v[224:227], v[30:33]
	v_mfma_f32_16x16x32_bf16 v[18:21], v[154:157], v[232:235], v[18:21]
	v_mfma_f32_16x16x32_bf16 v[14:17], v[162:165], v[232:235], v[14:17]
	s_setprio 0
	s_setprio 1
	v_mfma_f32_16x16x32_bf16 v[58:61], v[166:169], v[182:185], v[58:61]
	v_mfma_f32_16x16x32_bf16 v[54:57], v[174:177], v[182:185], v[54:57]
	v_mfma_f32_16x16x32_bf16 v[42:45], v[166:169], v[190:193], v[42:45]
	v_mfma_f32_16x16x32_bf16 v[38:41], v[174:177], v[190:193], v[38:41]
	v_mfma_f32_16x16x32_bf16 v[26:29], v[166:169], v[206:209], v[26:29]
	v_mfma_f32_16x16x32_bf16 v[22:25], v[174:177], v[206:209], v[22:25]
	v_mfma_f32_16x16x32_bf16 v[10:13], v[166:169], v[228:231], v[10:13]
	v_mfma_f32_16x16x32_bf16 v[4:7], v[174:177], v[228:231], v[6:9]
	v_mfma_f32_16x16x32_bf16 v[58:61], v[170:173], v[186:189], v[58:61]
	v_mfma_f32_16x16x32_bf16 v[54:57], v[178:181], v[186:189], v[54:57]
	v_mfma_f32_16x16x32_bf16 v[42:45], v[170:173], v[194:197], v[42:45]
	v_mfma_f32_16x16x32_bf16 v[38:41], v[178:181], v[194:197], v[38:41]
	v_mfma_f32_16x16x32_bf16 v[26:29], v[170:173], v[224:227], v[26:29]
	v_mfma_f32_16x16x32_bf16 v[22:25], v[178:181], v[224:227], v[22:25]
	v_mfma_f32_16x16x32_bf16 v[10:13], v[170:173], v[232:235], v[10:13]
	v_mfma_f32_16x16x32_bf16 v[4:7], v[178:181], v[232:235], v[4:7]
	s_setprio 0
	s_barrier
	ds_read_b128 v[150:153], v147 offset:32768
	ds_read_b128 v[154:157], v147 offset:33792
	ds_read_b128 v[158:161], v147 offset:34816
	ds_read_b128 v[162:165], v147 offset:35840
	ds_read_b128 v[166:169], v147 offset:49152
	ds_read_b128 v[170:173], v147 offset:50176
	ds_read_b128 v[174:177], v147 offset:51200
	ds_read_b128 v[178:181], v147 offset:52224
	ds_read_b128 v[182:185], v148 offset:32768
	ds_read_b128 v[186:189], v148 offset:33792
	ds_read_b128 v[190:193], v148 offset:34816
	ds_read_b128 v[194:197], v148 offset:35840
	s_mov_b32 m0, s50
	ds_read_b128 v[206:209], v148 offset:36864
	global_load_lds_dwordx4 v140, s[46:47]
	s_mov_b32 m0, s51
	ds_read_b128 v[224:227], v148 offset:37888
	global_load_lds_dwordx4 v136, s[46:47]
	s_mov_b32 m0, s52
	ds_read_b128 v[228:231], v148 offset:38912
	global_load_lds_dwordx4 v236, s[46:47]
	s_mov_b32 m0, s53
	ds_read_b128 v[232:235], v148 offset:39936
	global_load_lds_dwordx4 v237, s[46:47]
	s_waitcnt vmcnt(8) lgkmcnt(0)
	s_barrier
; #define PG8_STAGE(bufoff, gbase, voff) do { _Pragma("unroll") for (int _i = 0; _i < 2; ++_i) \
;         __builtin_amdgcn_global_load_lds((const unsigned*)((const char*)(gbase) + (voff)[_i]), (LAS unsigned*)(lds + (bufoff) + ldsw + _i * 8192), 16, 0, 0); } while (0)
; #define PG8_LDA(dst, b, h) do { _Pragma("unroll") for (int m = 0; m < 4; ++m) _Pragma("unroll") for (int k = 0; k < 2; ++k) dst[m][k] = *(const LAS bf16x8*)(lds + PG8_SA(b, h) + aoff + m * 2048 + k * 1024); } while (0)
; #define PG8_LDB(dst, b, h) do { _Pragma("unroll") for (int n = 0; n < 2; ++n) _Pragma("unroll") for (int k = 0; k < 2; ++k) dst[n][k] = *(const LAS bf16x8*)(lds + PG8_SB(b, h) + boff + n * 2048 + k * 1024); } while (0)
; #define PG8_MMA(ai, bj, At, Bt) do { __builtin_amdgcn_s_setprio(1); _Pragma("unroll") for (int m = 0; m < 4; ++m) _Pragma("unroll") for (int n = 0; n < 2; ++n) _Pragma("unroll") for (int k = 0; k < 2; ++k) \
;         acc[ai][bj][m][n] = __builtin_amdgcn_mfma_f32_16x16x32_bf16(Bt[n][k], At[m][k], acc[ai][bj][m][n], 0, 0, 0); __builtin_amdgcn_s_setprio(0); } while (0)
; #define PG8_WAIT_V(n) asm volatile("s_waitcnt vmcnt(" #n ")" ::: "memory")
; #define PG8_WAIT_L(n) asm volatile("s_waitcnt lgkmcnt(" #n ")" ::: "memory")
; #define PG8_BAR __builtin_amdgcn_s_barrier()
; #define PG8_SCHED __builtin_amdgcn_sched_barrier(0)
; template <class Epi, bool ALIGN_EPI = true>
; __device__ __forceinline__ void gemm_phase(LAS unsigned char* lds, const Gemm g, const Sched& S, const Epi& E) {
;     ...
;             PG8_LDB(B0, 1, 0); PG8_LDB(B1, 1, 1); PG8_SCHED; PG8_LDA(At, 1, 0); PG8_STAGE(PG8_SA(0, 1), a2 + hstepA, voffA);
;             PG8_WAIT_V(8); PG8_WAIT_L(0); PG8_BAR; PG8_MMA(0, 0, At, B0); PG8_MMA(0, 1, At, B1); PG8_BAR; PG8_SCHED;
;             PG8_LDA(At, 1, 1); PG8_STAGE(PG8_SB(1, 0), b3, voffB); PG8_STAGE(PG8_SB(1, 1), b3 + hstepB, voffB); PG8_STAGE(PG8_SA(1, 0), a3, voffA);
;             PG8_WAIT_V(8); PG8_WAIT_L(0); PG8_BAR; PG8_MMA(1, 0, At, B0); PG8_MMA(1, 1, At, B1); PG8_BAR; PG8_SCHED;
;         }
	s_setprio 1
	v_mfma_f32_16x16x32_bf16 v[130:133], v[150:153], v[182:185], v[130:133]
	v_mfma_f32_16x16x32_bf16 v[126:129], v[158:161], v[182:185], v[126:129]
	v_mfma_f32_16x16x32_bf16 v[114:117], v[150:153], v[190:193], v[114:117]
	v_mfma_f32_16x16x32_bf16 v[110:113], v[158:161], v[190:193], v[110:113]
	v_mfma_f32_16x16x32_bf16 v[98:101], v[150:153], v[206:209], v[98:101]
	v_mfma_f32_16x16x32_bf16 v[94:97], v[158:161], v[206:209], v[94:97]
	v_mfma_f32_16x16x32_bf16 v[82:85], v[150:153], v[228:231], v[82:85]
	v_mfma_f32_16x16x32_bf16 v[78:81], v[158:161], v[228:231], v[78:81]
	v_mfma_f32_16x16x32_bf16 v[130:133], v[154:157], v[186:189], v[130:133]
	v_mfma_f32_16x16x32_bf16 v[126:129], v[162:165], v[186:189], v[126:129]
	v_mfma_f32_16x16x32_bf16 v[114:117], v[154:157], v[194:197], v[114:117]
	v_mfma_f32_16x16x32_bf16 v[110:113], v[162:165], v[194:197], v[110:113]
	v_mfma_f32_16x16x32_bf16 v[98:101], v[154:157], v[224:227], v[98:101]
	v_mfma_f32_16x16x32_bf16 v[94:97], v[162:165], v[224:227], v[94:97]
	v_mfma_f32_16x16x32_bf16 v[82:85], v[154:157], v[232:235], v[82:85]
	v_mfma_f32_16x16x32_bf16 v[78:81], v[162:165], v[232:235], v[78:81]
	s_setprio 0
	s_setprio 1
	v_mfma_f32_16x16x32_bf16 v[122:125], v[166:169], v[182:185], v[122:125]
	v_mfma_f32_16x16x32_bf16 v[118:121], v[174:177], v[182:185], v[118:121]
	v_mfma_f32_16x16x32_bf16 v[106:109], v[166:169], v[190:193], v[106:109]
	v_mfma_f32_16x16x32_bf16 v[102:105], v[174:177], v[190:193], v[102:105]
	v_mfma_f32_16x16x32_bf16 v[90:93], v[166:169], v[206:209], v[90:93]
	v_mfma_f32_16x16x32_bf16 v[86:89], v[174:177], v[206:209], v[86:89]
	v_mfma_f32_16x16x32_bf16 v[74:77], v[166:169], v[228:231], v[74:77]
	v_mfma_f32_16x16x32_bf16 v[70:73], v[174:177], v[228:231], v[70:73]
	v_mfma_f32_16x16x32_bf16 v[122:125], v[170:173], v[186:189], v[122:125]
	v_mfma_f32_16x16x32_bf16 v[118:121], v[178:181], v[186:189], v[118:121]
	v_mfma_f32_16x16x32_bf16 v[106:109], v[170:173], v[194:197], v[106:109]
	v_mfma_f32_16x16x32_bf16 v[102:105], v[178:181], v[194:197], v[102:105]
	v_mfma_f32_16x16x32_bf16 v[90:93], v[170:173], v[224:227], v[90:93]
	v_mfma_f32_16x16x32_bf16 v[86:89], v[178:181], v[224:227], v[86:89]
	v_mfma_f32_16x16x32_bf16 v[74:77], v[170:173], v[232:235], v[74:77]
	v_mfma_f32_16x16x32_bf16 v[70:73], v[178:181], v[232:235], v[70:73]
	s_setprio 0
	s_barrier
	ds_read_b128 v[182:185], v148 offset:49152
	ds_read_b128 v[186:189], v148 offset:50176
	ds_read_b128 v[190:193], v148 offset:51200
	ds_read_b128 v[194:197], v148 offset:52224
	s_add_i32 m0, s37, 0x17f80
	ds_read_b128 v[206:209], v148 offset:53248
	global_load_lds_dwordx4 v138, s[44:45] offset:128
	s_add_i32 m0, s37, 0x19f80
	ds_read_b128 v[224:227], v148 offset:54272
	global_load_lds_dwordx4 v134, s[44:45] offset:128
	s_add_i32 m0, s37, 0x1bf80
	ds_read_b128 v[228:231], v148 offset:55296
	global_load_lds_dwordx4 v238, s[44:45] offset:128
	s_add_i32 m0, s37, 0x1df80
	ds_read_b128 v[232:235], v148 offset:56320
	global_load_lds_dwordx4 v239, s[44:45] offset:128
	s_waitcnt vmcnt(6) lgkmcnt(0)
	s_barrier
	s_setprio 1
	v_mfma_f32_16x16x32_bf16 v[66:69], v[150:153], v[182:185], v[66:69]
	v_mfma_f32_16x16x32_bf16 v[62:65], v[158:161], v[182:185], v[62:65]
	v_mfma_f32_16x16x32_bf16 v[50:53], v[150:153], v[190:193], v[50:53]
	v_mfma_f32_16x16x32_bf16 v[46:49], v[158:161], v[190:193], v[46:49]
	v_mfma_f32_16x16x32_bf16 v[34:37], v[150:153], v[206:209], v[34:37]
	v_mfma_f32_16x16x32_bf16 v[30:33], v[158:161], v[206:209], v[30:33]
	v_mfma_f32_16x16x32_bf16 v[18:21], v[150:153], v[228:231], v[18:21]
	v_mfma_f32_16x16x32_bf16 v[14:17], v[158:161], v[228:231], v[14:17]
	v_mfma_f32_16x16x32_bf16 v[66:69], v[154:157], v[186:189], v[66:69]
	v_mfma_f32_16x16x32_bf16 v[62:65], v[162:165], v[186:189], v[62:65]
	v_mfma_f32_16x16x32_bf16 v[50:53], v[154:157], v[194:197], v[50:53]
	v_mfma_f32_16x16x32_bf16 v[46:49], v[162:165], v[194:197], v[46:49]
	v_mfma_f32_16x16x32_bf16 v[34:37], v[154:157], v[224:227], v[34:37]
	v_mfma_f32_16x16x32_bf16 v[30:33], v[162:165], v[224:227], v[30:33]
	v_mfma_f32_16x16x32_bf16 v[18:21], v[154:157], v[232:235], v[18:21]
	v_mfma_f32_16x16x32_bf16 v[14:17], v[162:165], v[232:235], v[14:17]
	s_setprio 0
	s_setprio 1
	v_mfma_f32_16x16x32_bf16 v[58:61], v[166:169], v[182:185], v[58:61]
	v_mfma_f32_16x16x32_bf16 v[54:57], v[174:177], v[182:185], v[54:57]
	v_mfma_f32_16x16x32_bf16 v[42:45], v[166:169], v[190:193], v[42:45]
	v_mfma_f32_16x16x32_bf16 v[38:41], v[174:177], v[190:193], v[38:41]
	v_mfma_f32_16x16x32_bf16 v[26:29], v[166:169], v[206:209], v[26:29]
	v_mfma_f32_16x16x32_bf16 v[22:25], v[174:177], v[206:209], v[22:25]
	v_mfma_f32_16x16x32_bf16 v[8:11], v[166:169], v[228:231], v[10:13]
	v_mfma_f32_16x16x32_bf16 v[4:7], v[174:177], v[228:231], v[4:7]
	v_mfma_f32_16x16x32_bf16 v[58:61], v[170:173], v[186:189], v[58:61]
	v_mfma_f32_16x16x32_bf16 v[54:57], v[178:181], v[186:189], v[54:57]
	v_mfma_f32_16x16x32_bf16 v[42:45], v[170:173], v[194:197], v[42:45]
	v_mfma_f32_16x16x32_bf16 v[38:41], v[178:181], v[194:197], v[38:41]
	v_mfma_f32_16x16x32_bf16 v[26:29], v[170:173], v[224:227], v[26:29]
	v_mfma_f32_16x16x32_bf16 v[22:25], v[178:181], v[224:227], v[22:25]
	v_mfma_f32_16x16x32_bf16 v[10:13], v[170:173], v[232:235], v[8:11]
	v_mfma_f32_16x16x32_bf16 v[6:9], v[178:181], v[232:235], v[4:7]
	s_setprio 0
	s_barrier
	s_add_u32 s67, s67, 0x100
	s_addc_u32 s68, s68, 0
	s_cmp_ge_i32 s69, s54
	s_mov_b64 s[48:49], s[42:43]
	s_mov_b32 s44, s69
	s_cbranch_scc0 .LBB0_2287
	s_add_i32 s46, s37, 0x1c000
	s_add_i32 s70, s37, 0x14000
	s_mov_b32 s71, 0x14000
